# all 10 GEMM main loops: accumulator-chained MFMA pairs in boustrophedon order with alternating k order (every consecutive MFMA shares the accumulator or one input fragment)
# speedup vs baseline: 1.0161x; 1.0039x over previous
.LBB0_176:
	s_add_u32 s34, s26, 0xfff80080
	s_addc_u32 s35, s27, -1
	s_add_i32 s43, 0, 0x10000
	s_cmp_eq_u32 s33, 28
	s_cselect_b32 s37, s3, s35
	s_cselect_b32 s36, s10, s34
	s_cselect_b32 s35, s11, s29
	s_cselect_b32 s34, s21, s22
	s_add_i32 s66, 0, 0x14000
	v_add_u32_e32 v158, s43, v151
	v_add_u32_e32 v182, s66, v151
	ds_read_b128 v[142:145], v158
	ds_read_b128 v[146:149], v158 offset:1024
	ds_read_b128 v[154:157], v158 offset:2048
	ds_read_b128 v[158:161], v158 offset:3072
	ds_read_b128 v[162:165], v182
	ds_read_b128 v[166:169], v182 offset:1024
	ds_read_b128 v[178:181], v182 offset:2048
	ds_read_b128 v[182:185], v182 offset:3072
	v_lshl_add_u64 v[228:229], s[26:27], 0, v[138:139]
	s_add_i32 m0, s56, 0xc000
	ds_read_b128 v[186:189], v153
	ds_read_b128 v[190:193], v153 offset:1024
	ds_read_b128 v[194:197], v153 offset:2048
	ds_read_b128 v[208:211], v153 offset:3072
	ds_read_b128 v[212:215], v153 offset:4096
	ds_read_b128 v[216:219], v153 offset:5120
	ds_read_b128 v[220:223], v153 offset:6144
	ds_read_b128 v[224:227], v153 offset:7168
	global_load_lds_dwordx4 v[228:229], off
	v_lshl_add_u64 v[228:229], s[26:27], 0, v[140:141]
	s_add_i32 m0, s56, 0xe000
	s_nop 0
	global_load_lds_dwordx4 v[228:229], off
	s_waitcnt vmcnt(8)
	s_waitcnt lgkmcnt(0)
	s_barrier
	s_setprio 1
	s_waitcnt lgkmcnt(0)
	v_mfma_f32_16x16x32_bf16 v[128:131], v[142:145], v[186:189], v[128:131]
	v_mfma_f32_16x16x32_bf16 v[128:131], v[146:149], v[190:193], v[128:131]
	v_mfma_f32_16x16x32_bf16 v[124:127], v[158:161], v[190:193], v[124:127]
	v_mfma_f32_16x16x32_bf16 v[124:127], v[154:157], v[186:189], v[124:127]
	v_mfma_f32_16x16x32_bf16 v[108:111], v[154:157], v[194:197], v[108:111]
	v_mfma_f32_16x16x32_bf16 v[108:111], v[158:161], v[208:211], v[108:111]
	v_mfma_f32_16x16x32_bf16 v[112:115], v[146:149], v[208:211], v[112:115]
	v_mfma_f32_16x16x32_bf16 v[112:115], v[142:145], v[194:197], v[112:115]
	v_mfma_f32_16x16x32_bf16 v[96:99], v[142:145], v[212:215], v[96:99]
	v_mfma_f32_16x16x32_bf16 v[96:99], v[146:149], v[216:219], v[96:99]
	v_mfma_f32_16x16x32_bf16 v[92:95], v[158:161], v[216:219], v[92:95]
	v_mfma_f32_16x16x32_bf16 v[92:95], v[154:157], v[212:215], v[92:95]
	v_mfma_f32_16x16x32_bf16 v[76:79], v[154:157], v[220:223], v[76:79]
	v_mfma_f32_16x16x32_bf16 v[76:79], v[158:161], v[224:227], v[76:79]
	v_mfma_f32_16x16x32_bf16 v[80:83], v[146:149], v[224:227], v[80:83]
	v_mfma_f32_16x16x32_bf16 v[80:83], v[142:145], v[220:223], v[80:83]
	s_setprio 0
	s_setprio 1
	v_mfma_f32_16x16x32_bf16 v[120:123], v[162:165], v[186:189], v[120:123]
	v_mfma_f32_16x16x32_bf16 v[120:123], v[166:169], v[190:193], v[120:123]
	v_mfma_f32_16x16x32_bf16 v[116:119], v[182:185], v[190:193], v[116:119]
	v_mfma_f32_16x16x32_bf16 v[116:119], v[178:181], v[186:189], v[116:119]
	v_mfma_f32_16x16x32_bf16 v[100:103], v[178:181], v[194:197], v[100:103]
	v_mfma_f32_16x16x32_bf16 v[100:103], v[182:185], v[208:211], v[100:103]
	v_mfma_f32_16x16x32_bf16 v[104:107], v[166:169], v[208:211], v[104:107]
	v_mfma_f32_16x16x32_bf16 v[104:107], v[162:165], v[194:197], v[104:107]
	v_mfma_f32_16x16x32_bf16 v[88:91], v[162:165], v[212:215], v[88:91]
	v_mfma_f32_16x16x32_bf16 v[88:91], v[166:169], v[216:219], v[88:91]
	v_mfma_f32_16x16x32_bf16 v[84:87], v[182:185], v[216:219], v[84:87]
	v_mfma_f32_16x16x32_bf16 v[84:87], v[178:181], v[212:215], v[84:87]
	v_mfma_f32_16x16x32_bf16 v[68:71], v[178:181], v[220:223], v[68:71]
	v_mfma_f32_16x16x32_bf16 v[68:71], v[182:185], v[224:227], v[68:71]
	v_mfma_f32_16x16x32_bf16 v[72:75], v[166:169], v[224:227], v[72:75]
	v_mfma_f32_16x16x32_bf16 v[72:75], v[162:165], v[220:223], v[72:75]
	s_setprio 0
	s_barrier
	s_add_i32 s43, s43, s54
	v_lshl_add_u64 v[228:229], s[34:35], 0, v[2:3]
	s_mov_b32 m0, s43
	ds_read_b128 v[186:189], v153 offset:16384
	ds_read_b128 v[190:193], v153 offset:17408
	ds_read_b128 v[194:197], v153 offset:18432
	ds_read_b128 v[208:211], v153 offset:19456
	ds_read_b128 v[212:215], v153 offset:20480
	ds_read_b128 v[216:219], v153 offset:21504
	ds_read_b128 v[220:223], v153 offset:22528
	ds_read_b128 v[224:227], v153 offset:23552
	global_load_lds_dwordx4 v[228:229], off
	s_add_i32 m0, s43, 0x2000
	s_add_u32 s64, s34, 0x80000
	v_lshl_add_u64 v[230:231], s[34:35], 0, v[132:133]
	s_addc_u32 s65, s35, 0
	s_add_i32 s43, s66, s54
	global_load_lds_dwordx4 v[230:231], off
	v_lshl_add_u64 v[232:233], s[64:65], 0, v[2:3]
	s_mov_b32 m0, s43
	v_lshl_add_u64 v[234:235], s[36:37], 0, v[134:135]
	global_load_lds_dwordx4 v[232:233], off
	v_lshl_add_u64 v[232:233], s[64:65], 0, v[132:133]
	s_add_i32 m0, s43, 0x2000
	s_nop 0
	global_load_lds_dwordx4 v[232:233], off
	v_lshl_add_u64 v[232:233], s[36:37], 0, v[136:137]
	s_mov_b32 m0, s56
	s_nop 0
	global_load_lds_dwordx4 v[232:233], off
	s_mov_b32 m0, s57
	s_nop 0
	global_load_lds_dwordx4 v[234:235], off
	s_waitcnt vmcnt(8)
	s_waitcnt lgkmcnt(0)
	s_barrier
	s_setprio 1
	s_waitcnt lgkmcnt(0)
	v_mfma_f32_16x16x32_bf16 v[64:67], v[142:145], v[186:189], v[64:67]
	v_mfma_f32_16x16x32_bf16 v[64:67], v[146:149], v[190:193], v[64:67]
	v_mfma_f32_16x16x32_bf16 v[60:63], v[158:161], v[190:193], v[60:63]
	v_mfma_f32_16x16x32_bf16 v[60:63], v[154:157], v[186:189], v[60:63]
	v_mfma_f32_16x16x32_bf16 v[44:47], v[154:157], v[194:197], v[44:47]
	v_mfma_f32_16x16x32_bf16 v[44:47], v[158:161], v[208:211], v[44:47]
	v_mfma_f32_16x16x32_bf16 v[48:51], v[146:149], v[208:211], v[48:51]
	v_mfma_f32_16x16x32_bf16 v[48:51], v[142:145], v[194:197], v[48:51]
	v_mfma_f32_16x16x32_bf16 v[32:35], v[142:145], v[212:215], v[32:35]
	v_mfma_f32_16x16x32_bf16 v[32:35], v[146:149], v[216:219], v[32:35]
	v_mfma_f32_16x16x32_bf16 v[28:31], v[158:161], v[216:219], v[28:31]
	v_mfma_f32_16x16x32_bf16 v[28:31], v[154:157], v[212:215], v[28:31]
	v_mfma_f32_16x16x32_bf16 v[12:15], v[154:157], v[220:223], v[12:15]
	v_mfma_f32_16x16x32_bf16 v[12:15], v[158:161], v[224:227], v[12:15]
	v_mfma_f32_16x16x32_bf16 v[16:19], v[146:149], v[224:227], v[16:19]
	v_mfma_f32_16x16x32_bf16 v[16:19], v[142:145], v[220:223], v[16:19]
	s_setprio 0
	s_setprio 1
	v_mfma_f32_16x16x32_bf16 v[56:59], v[162:165], v[186:189], v[56:59]
	v_mfma_f32_16x16x32_bf16 v[56:59], v[166:169], v[190:193], v[56:59]
	v_mfma_f32_16x16x32_bf16 v[52:55], v[182:185], v[190:193], v[52:55]
	v_mfma_f32_16x16x32_bf16 v[52:55], v[178:181], v[186:189], v[52:55]
	v_mfma_f32_16x16x32_bf16 v[36:39], v[178:181], v[194:197], v[36:39]
	v_mfma_f32_16x16x32_bf16 v[36:39], v[182:185], v[208:211], v[36:39]
	v_mfma_f32_16x16x32_bf16 v[40:43], v[166:169], v[208:211], v[40:43]
	v_mfma_f32_16x16x32_bf16 v[40:43], v[162:165], v[194:197], v[40:43]
	v_mfma_f32_16x16x32_bf16 v[24:27], v[162:165], v[212:215], v[24:27]
	v_mfma_f32_16x16x32_bf16 v[24:27], v[166:169], v[216:219], v[24:27]
	v_mfma_f32_16x16x32_bf16 v[20:23], v[182:185], v[216:219], v[20:23]
	v_mfma_f32_16x16x32_bf16 v[20:23], v[178:181], v[212:215], v[20:23]
	v_mfma_f32_16x16x32_bf16 v[4:7], v[178:181], v[220:223], v[4:7]
	v_mfma_f32_16x16x32_bf16 v[4:7], v[182:185], v[224:227], v[4:7]
	v_mfma_f32_16x16x32_bf16 v[8:11], v[166:169], v[224:227], v[8:11]
	v_mfma_f32_16x16x32_bf16 v[8:11], v[162:165], v[220:223], v[8:11]
	s_setprio 0
	s_barrier
	s_add_i32 s43, 0, 0x18000
	s_add_i32 s64, 0, 0x1c000
	v_add_u32_e32 v158, s43, v151
	v_add_u32_e32 v182, s64, v151
	ds_read_b128 v[142:145], v158
	ds_read_b128 v[146:149], v158 offset:1024
	ds_read_b128 v[154:157], v158 offset:2048
	ds_read_b128 v[158:161], v158 offset:3072
	ds_read_b128 v[162:165], v182
	ds_read_b128 v[166:169], v182 offset:1024
	ds_read_b128 v[178:181], v182 offset:2048
	ds_read_b128 v[182:185], v182 offset:3072
	s_add_u32 s36, s36, 0x80000
	s_addc_u32 s37, s37, 0
	s_mov_b32 m0, s58
	v_lshl_add_u64 v[236:237], s[36:37], 0, v[136:137]
	ds_read_b128 v[186:189], v153 offset:32768
	ds_read_b128 v[190:193], v153 offset:33792
	ds_read_b128 v[194:197], v153 offset:34816
	ds_read_b128 v[208:211], v153 offset:35840
	ds_read_b128 v[212:215], v153 offset:36864
	ds_read_b128 v[216:219], v153 offset:37888
	ds_read_b128 v[220:223], v153 offset:38912
	ds_read_b128 v[224:227], v153 offset:39936
	global_load_lds_dwordx4 v[236:237], off
	v_lshl_add_u64 v[236:237], s[36:37], 0, v[134:135]
	s_mov_b32 m0, s59
	s_nop 0
	global_load_lds_dwordx4 v[236:237], off
	s_waitcnt vmcnt(8)
	s_waitcnt lgkmcnt(0)
	s_barrier
	s_setprio 1
	s_waitcnt lgkmcnt(0)
	v_mfma_f32_16x16x32_bf16 v[128:131], v[142:145], v[186:189], v[128:131]
	v_mfma_f32_16x16x32_bf16 v[128:131], v[146:149], v[190:193], v[128:131]
	v_mfma_f32_16x16x32_bf16 v[124:127], v[158:161], v[190:193], v[124:127]
	v_mfma_f32_16x16x32_bf16 v[124:127], v[154:157], v[186:189], v[124:127]
	v_mfma_f32_16x16x32_bf16 v[108:111], v[154:157], v[194:197], v[108:111]
	v_mfma_f32_16x16x32_bf16 v[108:111], v[158:161], v[208:211], v[108:111]
	v_mfma_f32_16x16x32_bf16 v[112:115], v[146:149], v[208:211], v[112:115]
	v_mfma_f32_16x16x32_bf16 v[112:115], v[142:145], v[194:197], v[112:115]
	v_mfma_f32_16x16x32_bf16 v[96:99], v[142:145], v[212:215], v[96:99]
	v_mfma_f32_16x16x32_bf16 v[96:99], v[146:149], v[216:219], v[96:99]
	v_mfma_f32_16x16x32_bf16 v[92:95], v[158:161], v[216:219], v[92:95]
	v_mfma_f32_16x16x32_bf16 v[92:95], v[154:157], v[212:215], v[92:95]
	v_mfma_f32_16x16x32_bf16 v[76:79], v[154:157], v[220:223], v[76:79]
	v_mfma_f32_16x16x32_bf16 v[76:79], v[158:161], v[224:227], v[76:79]
	v_mfma_f32_16x16x32_bf16 v[80:83], v[146:149], v[224:227], v[80:83]
	v_mfma_f32_16x16x32_bf16 v[80:83], v[142:145], v[220:223], v[80:83]
	s_setprio 0
	s_setprio 1
	v_mfma_f32_16x16x32_bf16 v[120:123], v[162:165], v[186:189], v[120:123]
	v_mfma_f32_16x16x32_bf16 v[120:123], v[166:169], v[190:193], v[120:123]
	v_mfma_f32_16x16x32_bf16 v[116:119], v[182:185], v[190:193], v[116:119]
	v_mfma_f32_16x16x32_bf16 v[116:119], v[178:181], v[186:189], v[116:119]
	v_mfma_f32_16x16x32_bf16 v[100:103], v[178:181], v[194:197], v[100:103]
	v_mfma_f32_16x16x32_bf16 v[100:103], v[182:185], v[208:211], v[100:103]
	v_mfma_f32_16x16x32_bf16 v[104:107], v[166:169], v[208:211], v[104:107]
	v_mfma_f32_16x16x32_bf16 v[104:107], v[162:165], v[194:197], v[104:107]
	v_mfma_f32_16x16x32_bf16 v[88:91], v[162:165], v[212:215], v[88:91]
	v_mfma_f32_16x16x32_bf16 v[88:91], v[166:169], v[216:219], v[88:91]
	v_mfma_f32_16x16x32_bf16 v[84:87], v[182:185], v[216:219], v[84:87]
	v_mfma_f32_16x16x32_bf16 v[84:87], v[178:181], v[212:215], v[84:87]
	v_mfma_f32_16x16x32_bf16 v[68:71], v[178:181], v[220:223], v[68:71]
	v_mfma_f32_16x16x32_bf16 v[68:71], v[182:185], v[224:227], v[68:71]
	v_mfma_f32_16x16x32_bf16 v[72:75], v[166:169], v[224:227], v[72:75]
	v_mfma_f32_16x16x32_bf16 v[72:75], v[162:165], v[220:223], v[72:75]
	s_setprio 0
	s_barrier
	s_add_i32 s36, s43, s54
	v_lshl_add_u64 v[228:229], v[228:229], 0, s[18:19]
	s_mov_b32 m0, s36
	ds_read_b128 v[186:189], v153 offset:49152
	ds_read_b128 v[190:193], v153 offset:50176
	ds_read_b128 v[194:197], v153 offset:51200
	ds_read_b128 v[208:211], v153 offset:52224
	ds_read_b128 v[212:215], v153 offset:53248
	ds_read_b128 v[216:219], v153 offset:54272
	ds_read_b128 v[220:223], v153 offset:55296
	ds_read_b128 v[224:227], v153 offset:56320
	global_load_lds_dwordx4 v[228:229], off
	s_add_i32 m0, s36, 0x2000
	s_add_u32 s34, s34, 0x80080
	v_lshl_add_u64 v[228:229], v[230:231], 0, s[18:19]
	s_addc_u32 s35, s35, 0
	s_add_i32 s36, s64, s54
	global_load_lds_dwordx4 v[228:229], off
	v_lshl_add_u64 v[228:229], s[34:35], 0, v[2:3]
	s_mov_b32 m0, s36
	s_nop 0
	global_load_lds_dwordx4 v[228:229], off
	v_lshl_add_u64 v[228:229], s[34:35], 0, v[132:133]
	s_add_i32 m0, s36, 0x2000
	s_nop 0
	global_load_lds_dwordx4 v[228:229], off
	v_lshl_add_u64 v[228:229], v[232:233], 0, s[18:19]
	s_mov_b32 m0, s60
	s_nop 0
	global_load_lds_dwordx4 v[228:229], off
	v_lshl_add_u64 v[228:229], v[234:235], 0, s[18:19]
	s_mov_b32 m0, s61
	s_nop 0
	global_load_lds_dwordx4 v[228:229], off
	s_waitcnt vmcnt(8)
	s_waitcnt lgkmcnt(0)
	s_barrier
	s_setprio 1
	s_waitcnt lgkmcnt(0)
	v_mfma_f32_16x16x32_bf16 v[64:67], v[142:145], v[186:189], v[64:67]
	v_mfma_f32_16x16x32_bf16 v[64:67], v[146:149], v[190:193], v[64:67]
	v_mfma_f32_16x16x32_bf16 v[60:63], v[158:161], v[190:193], v[60:63]
	v_mfma_f32_16x16x32_bf16 v[60:63], v[154:157], v[186:189], v[60:63]
	v_mfma_f32_16x16x32_bf16 v[44:47], v[154:157], v[194:197], v[44:47]
	v_mfma_f32_16x16x32_bf16 v[44:47], v[158:161], v[208:211], v[44:47]
	v_mfma_f32_16x16x32_bf16 v[48:51], v[146:149], v[208:211], v[48:51]
	v_mfma_f32_16x16x32_bf16 v[48:51], v[142:145], v[194:197], v[48:51]
	v_mfma_f32_16x16x32_bf16 v[32:35], v[142:145], v[212:215], v[32:35]
	v_mfma_f32_16x16x32_bf16 v[32:35], v[146:149], v[216:219], v[32:35]
	v_mfma_f32_16x16x32_bf16 v[28:31], v[158:161], v[216:219], v[28:31]
	v_mfma_f32_16x16x32_bf16 v[28:31], v[154:157], v[212:215], v[28:31]
	v_mfma_f32_16x16x32_bf16 v[12:15], v[154:157], v[220:223], v[12:15]
	v_mfma_f32_16x16x32_bf16 v[12:15], v[158:161], v[224:227], v[12:15]
	v_mfma_f32_16x16x32_bf16 v[16:19], v[146:149], v[224:227], v[16:19]
	v_mfma_f32_16x16x32_bf16 v[16:19], v[142:145], v[220:223], v[16:19]
	s_setprio 0
	s_setprio 1
	v_mfma_f32_16x16x32_bf16 v[56:59], v[162:165], v[186:189], v[56:59]
	v_mfma_f32_16x16x32_bf16 v[56:59], v[166:169], v[190:193], v[56:59]
	v_mfma_f32_16x16x32_bf16 v[52:55], v[182:185], v[190:193], v[52:55]
	v_mfma_f32_16x16x32_bf16 v[52:55], v[178:181], v[186:189], v[52:55]
	v_mfma_f32_16x16x32_bf16 v[36:39], v[178:181], v[194:197], v[36:39]
	v_mfma_f32_16x16x32_bf16 v[36:39], v[182:185], v[208:211], v[36:39]
	v_mfma_f32_16x16x32_bf16 v[40:43], v[166:169], v[208:211], v[40:43]
	v_mfma_f32_16x16x32_bf16 v[40:43], v[162:165], v[194:197], v[40:43]
	v_mfma_f32_16x16x32_bf16 v[24:27], v[162:165], v[212:215], v[24:27]
	v_mfma_f32_16x16x32_bf16 v[24:27], v[166:169], v[216:219], v[24:27]
	v_mfma_f32_16x16x32_bf16 v[20:23], v[182:185], v[216:219], v[20:23]
	v_mfma_f32_16x16x32_bf16 v[20:23], v[178:181], v[212:215], v[20:23]
	v_mfma_f32_16x16x32_bf16 v[4:7], v[178:181], v[220:223], v[4:7]
	v_mfma_f32_16x16x32_bf16 v[4:7], v[182:185], v[224:227], v[4:7]
	v_mfma_f32_16x16x32_bf16 v[8:11], v[166:169], v[224:227], v[8:11]
	v_mfma_f32_16x16x32_bf16 v[8:11], v[162:165], v[220:223], v[8:11]
	s_setprio 0
	s_barrier
	s_add_i32 s33, s33, 2
	s_add_u32 s26, s26, 0x100
	s_addc_u32 s27, s27, 0
	s_add_u32 s22, s22, 0x100
	s_addc_u32 s29, s29, 0
	s_cmp_gt_u32 s33, 29
	s_cbranch_scc0 .LBB0_176
	s_and_b64 vcc, exec, s[12:13]
	s_cbranch_vccz .LBB0_179
	s_barrier

.LBB0_198:
	s_add_u32 s34, s26, 0xfff80080
	s_addc_u32 s35, s27, -1
	s_add_i32 s43, 0, 0x10000
	s_cmp_eq_u32 s33, 28
	s_cselect_b32 s37, s3, s35
	s_cselect_b32 s36, s10, s34
	s_cselect_b32 s35, s11, s29
	s_cselect_b32 s34, s21, s22
	s_add_i32 s66, 0, 0x14000
	v_add_u32_e32 v164, s43, v152
	v_add_u32_e32 v168, s66, v152
	ds_read_b128 v[142:145], v164
	ds_read_b128 v[146:149], v164 offset:1024
	ds_read_b128 v[160:163], v164 offset:2048
	ds_read_b128 v[164:167], v164 offset:3072
	ds_read_b128 v[178:181], v168
	ds_read_b128 v[182:185], v168 offset:1024
	ds_read_b128 v[186:189], v168 offset:2048
	ds_read_b128 v[190:193], v168 offset:3072
	v_lshl_add_u64 v[168:169], s[26:27], 0, v[138:139]
	s_add_i32 m0, s56, 0xc000
	ds_read_b128 v[194:197], v159
	ds_read_b128 v[208:211], v159 offset:1024
	ds_read_b128 v[212:215], v159 offset:2048
	ds_read_b128 v[216:219], v159 offset:3072
	ds_read_b128 v[220:223], v159 offset:4096
	ds_read_b128 v[224:227], v159 offset:5120
	ds_read_b128 v[228:231], v159 offset:6144
	ds_read_b128 v[232:235], v159 offset:7168
	global_load_lds_dwordx4 v[168:169], off
	v_lshl_add_u64 v[168:169], s[26:27], 0, v[140:141]
	s_add_i32 m0, s56, 0xe000
	s_nop 0
	global_load_lds_dwordx4 v[168:169], off
	s_waitcnt vmcnt(8)
	s_waitcnt lgkmcnt(0)
	s_barrier
	s_setprio 1
	s_waitcnt lgkmcnt(0)
	v_mfma_f32_16x16x32_bf16 v[128:131], v[142:145], v[194:197], v[128:131]
	v_mfma_f32_16x16x32_bf16 v[128:131], v[146:149], v[208:211], v[128:131]
	v_mfma_f32_16x16x32_bf16 v[124:127], v[164:167], v[208:211], v[124:127]
	v_mfma_f32_16x16x32_bf16 v[124:127], v[160:163], v[194:197], v[124:127]
	v_mfma_f32_16x16x32_bf16 v[108:111], v[160:163], v[212:215], v[108:111]
	v_mfma_f32_16x16x32_bf16 v[108:111], v[164:167], v[216:219], v[108:111]
	v_mfma_f32_16x16x32_bf16 v[112:115], v[146:149], v[216:219], v[112:115]
	v_mfma_f32_16x16x32_bf16 v[112:115], v[142:145], v[212:215], v[112:115]
	v_mfma_f32_16x16x32_bf16 v[96:99], v[142:145], v[220:223], v[96:99]
	v_mfma_f32_16x16x32_bf16 v[96:99], v[146:149], v[224:227], v[96:99]
	v_mfma_f32_16x16x32_bf16 v[92:95], v[164:167], v[224:227], v[92:95]
	v_mfma_f32_16x16x32_bf16 v[92:95], v[160:163], v[220:223], v[92:95]
	v_mfma_f32_16x16x32_bf16 v[76:79], v[160:163], v[228:231], v[76:79]
	v_mfma_f32_16x16x32_bf16 v[76:79], v[164:167], v[232:235], v[76:79]
	v_mfma_f32_16x16x32_bf16 v[80:83], v[146:149], v[232:235], v[80:83]
	v_mfma_f32_16x16x32_bf16 v[80:83], v[142:145], v[228:231], v[80:83]
	s_setprio 0
	s_setprio 1
	v_mfma_f32_16x16x32_bf16 v[120:123], v[178:181], v[194:197], v[120:123]
	v_mfma_f32_16x16x32_bf16 v[120:123], v[182:185], v[208:211], v[120:123]
	v_mfma_f32_16x16x32_bf16 v[116:119], v[190:193], v[208:211], v[116:119]
	v_mfma_f32_16x16x32_bf16 v[116:119], v[186:189], v[194:197], v[116:119]
	v_mfma_f32_16x16x32_bf16 v[100:103], v[186:189], v[212:215], v[100:103]
	v_mfma_f32_16x16x32_bf16 v[100:103], v[190:193], v[216:219], v[100:103]
	v_mfma_f32_16x16x32_bf16 v[104:107], v[182:185], v[216:219], v[104:107]
	v_mfma_f32_16x16x32_bf16 v[104:107], v[178:181], v[212:215], v[104:107]
	v_mfma_f32_16x16x32_bf16 v[88:91], v[178:181], v[220:223], v[88:91]
	v_mfma_f32_16x16x32_bf16 v[88:91], v[182:185], v[224:227], v[88:91]
	v_mfma_f32_16x16x32_bf16 v[84:87], v[190:193], v[224:227], v[84:87]
	v_mfma_f32_16x16x32_bf16 v[84:87], v[186:189], v[220:223], v[84:87]
	v_mfma_f32_16x16x32_bf16 v[68:71], v[186:189], v[228:231], v[68:71]
	v_mfma_f32_16x16x32_bf16 v[68:71], v[190:193], v[232:235], v[68:71]
	v_mfma_f32_16x16x32_bf16 v[72:75], v[182:185], v[232:235], v[72:75]
	v_mfma_f32_16x16x32_bf16 v[72:75], v[178:181], v[228:231], v[72:75]
	s_setprio 0
	s_barrier
	s_add_i32 s43, s43, s54
	v_lshl_add_u64 v[168:169], s[34:35], 0, v[2:3]
	s_mov_b32 m0, s43
	ds_read_b128 v[194:197], v159 offset:16384
	ds_read_b128 v[208:211], v159 offset:17408
	ds_read_b128 v[212:215], v159 offset:18432
	ds_read_b128 v[216:219], v159 offset:19456
	ds_read_b128 v[220:223], v159 offset:20480
	ds_read_b128 v[224:227], v159 offset:21504
	ds_read_b128 v[228:231], v159 offset:22528
	ds_read_b128 v[232:235], v159 offset:23552
	global_load_lds_dwordx4 v[168:169], off
	s_add_i32 m0, s43, 0x2000
	s_add_u32 s64, s34, 0x80000
	v_lshl_add_u64 v[236:237], s[34:35], 0, v[132:133]
	s_addc_u32 s65, s35, 0
	s_add_i32 s43, s66, s54
	global_load_lds_dwordx4 v[236:237], off
	v_lshl_add_u64 v[238:239], s[64:65], 0, v[2:3]
	s_mov_b32 m0, s43
	v_lshl_add_u64 v[240:241], s[36:37], 0, v[134:135]
	global_load_lds_dwordx4 v[238:239], off
	v_lshl_add_u64 v[238:239], s[64:65], 0, v[132:133]
	s_add_i32 m0, s43, 0x2000
	s_nop 0
	global_load_lds_dwordx4 v[238:239], off
	v_lshl_add_u64 v[238:239], s[36:37], 0, v[136:137]
	s_mov_b32 m0, s56
	s_nop 0
	global_load_lds_dwordx4 v[238:239], off
	s_mov_b32 m0, s57
	s_nop 0
	global_load_lds_dwordx4 v[240:241], off
	s_waitcnt vmcnt(8)
	s_waitcnt lgkmcnt(0)
	s_barrier
	s_setprio 1
	s_waitcnt lgkmcnt(0)
	v_mfma_f32_16x16x32_bf16 v[64:67], v[142:145], v[194:197], v[64:67]
	v_mfma_f32_16x16x32_bf16 v[64:67], v[146:149], v[208:211], v[64:67]
	v_mfma_f32_16x16x32_bf16 v[60:63], v[164:167], v[208:211], v[60:63]
	v_mfma_f32_16x16x32_bf16 v[60:63], v[160:163], v[194:197], v[60:63]
	v_mfma_f32_16x16x32_bf16 v[44:47], v[160:163], v[212:215], v[44:47]
	v_mfma_f32_16x16x32_bf16 v[44:47], v[164:167], v[216:219], v[44:47]
	v_mfma_f32_16x16x32_bf16 v[48:51], v[146:149], v[216:219], v[48:51]
	v_mfma_f32_16x16x32_bf16 v[48:51], v[142:145], v[212:215], v[48:51]
	v_mfma_f32_16x16x32_bf16 v[32:35], v[142:145], v[220:223], v[32:35]
	v_mfma_f32_16x16x32_bf16 v[32:35], v[146:149], v[224:227], v[32:35]
	v_mfma_f32_16x16x32_bf16 v[28:31], v[164:167], v[224:227], v[28:31]
	v_mfma_f32_16x16x32_bf16 v[28:31], v[160:163], v[220:223], v[28:31]
	v_mfma_f32_16x16x32_bf16 v[12:15], v[160:163], v[228:231], v[12:15]
	v_mfma_f32_16x16x32_bf16 v[12:15], v[164:167], v[232:235], v[12:15]
	v_mfma_f32_16x16x32_bf16 v[16:19], v[146:149], v[232:235], v[16:19]
	v_mfma_f32_16x16x32_bf16 v[16:19], v[142:145], v[228:231], v[16:19]
	s_setprio 0
	s_setprio 1
	v_mfma_f32_16x16x32_bf16 v[56:59], v[178:181], v[194:197], v[56:59]
	v_mfma_f32_16x16x32_bf16 v[56:59], v[182:185], v[208:211], v[56:59]
	v_mfma_f32_16x16x32_bf16 v[52:55], v[190:193], v[208:211], v[52:55]
	v_mfma_f32_16x16x32_bf16 v[52:55], v[186:189], v[194:197], v[52:55]
	v_mfma_f32_16x16x32_bf16 v[36:39], v[186:189], v[212:215], v[36:39]
	v_mfma_f32_16x16x32_bf16 v[36:39], v[190:193], v[216:219], v[36:39]
	v_mfma_f32_16x16x32_bf16 v[40:43], v[182:185], v[216:219], v[40:43]
	v_mfma_f32_16x16x32_bf16 v[40:43], v[178:181], v[212:215], v[40:43]
	v_mfma_f32_16x16x32_bf16 v[24:27], v[178:181], v[220:223], v[24:27]
	v_mfma_f32_16x16x32_bf16 v[24:27], v[182:185], v[224:227], v[24:27]
	v_mfma_f32_16x16x32_bf16 v[20:23], v[190:193], v[224:227], v[20:23]
	v_mfma_f32_16x16x32_bf16 v[20:23], v[186:189], v[220:223], v[20:23]
	v_mfma_f32_16x16x32_bf16 v[4:7], v[186:189], v[228:231], v[4:7]
	v_mfma_f32_16x16x32_bf16 v[4:7], v[190:193], v[232:235], v[4:7]
	v_mfma_f32_16x16x32_bf16 v[8:11], v[182:185], v[232:235], v[8:11]
	v_mfma_f32_16x16x32_bf16 v[8:11], v[178:181], v[228:231], v[8:11]
	s_setprio 0
	s_barrier
	s_add_i32 s43, 0, 0x18000
	s_add_i32 s64, 0, 0x1c000
	v_add_u32_e32 v164, s43, v152
	v_add_u32_e32 v190, s64, v152
	ds_read_b128 v[142:145], v164
	ds_read_b128 v[146:149], v164 offset:1024
	ds_read_b128 v[160:163], v164 offset:2048
	ds_read_b128 v[164:167], v164 offset:3072
	ds_read_b128 v[178:181], v190
	ds_read_b128 v[182:185], v190 offset:1024
	ds_read_b128 v[186:189], v190 offset:2048
	ds_read_b128 v[190:193], v190 offset:3072
	s_add_u32 s36, s36, 0x80000
	s_addc_u32 s37, s37, 0
	s_mov_b32 m0, s58
	v_lshl_add_u64 v[242:243], s[36:37], 0, v[136:137]
	ds_read_b128 v[194:197], v159 offset:32768
	ds_read_b128 v[208:211], v159 offset:33792
	ds_read_b128 v[212:215], v159 offset:34816
	ds_read_b128 v[216:219], v159 offset:35840
	ds_read_b128 v[220:223], v159 offset:36864
	ds_read_b128 v[224:227], v159 offset:37888
	ds_read_b128 v[228:231], v159 offset:38912
	ds_read_b128 v[232:235], v159 offset:39936
	global_load_lds_dwordx4 v[242:243], off
	v_lshl_add_u64 v[242:243], s[36:37], 0, v[134:135]
	s_mov_b32 m0, s59
	s_nop 0
	global_load_lds_dwordx4 v[242:243], off
	s_waitcnt vmcnt(8)
	s_waitcnt lgkmcnt(0)
	s_barrier
	s_setprio 1
	s_waitcnt lgkmcnt(0)
	v_mfma_f32_16x16x32_bf16 v[128:131], v[142:145], v[194:197], v[128:131]
	v_mfma_f32_16x16x32_bf16 v[128:131], v[146:149], v[208:211], v[128:131]
	v_mfma_f32_16x16x32_bf16 v[124:127], v[164:167], v[208:211], v[124:127]
	v_mfma_f32_16x16x32_bf16 v[124:127], v[160:163], v[194:197], v[124:127]
	v_mfma_f32_16x16x32_bf16 v[108:111], v[160:163], v[212:215], v[108:111]
	v_mfma_f32_16x16x32_bf16 v[108:111], v[164:167], v[216:219], v[108:111]
	v_mfma_f32_16x16x32_bf16 v[112:115], v[146:149], v[216:219], v[112:115]
	v_mfma_f32_16x16x32_bf16 v[112:115], v[142:145], v[212:215], v[112:115]
	v_mfma_f32_16x16x32_bf16 v[96:99], v[142:145], v[220:223], v[96:99]
	v_mfma_f32_16x16x32_bf16 v[96:99], v[146:149], v[224:227], v[96:99]
	v_mfma_f32_16x16x32_bf16 v[92:95], v[164:167], v[224:227], v[92:95]
	v_mfma_f32_16x16x32_bf16 v[92:95], v[160:163], v[220:223], v[92:95]
	v_mfma_f32_16x16x32_bf16 v[76:79], v[160:163], v[228:231], v[76:79]
	v_mfma_f32_16x16x32_bf16 v[76:79], v[164:167], v[232:235], v[76:79]
	v_mfma_f32_16x16x32_bf16 v[80:83], v[146:149], v[232:235], v[80:83]
	v_mfma_f32_16x16x32_bf16 v[80:83], v[142:145], v[228:231], v[80:83]
	s_setprio 0
	s_setprio 1
	v_mfma_f32_16x16x32_bf16 v[120:123], v[178:181], v[194:197], v[120:123]
	v_mfma_f32_16x16x32_bf16 v[120:123], v[182:185], v[208:211], v[120:123]
	v_mfma_f32_16x16x32_bf16 v[116:119], v[190:193], v[208:211], v[116:119]
	v_mfma_f32_16x16x32_bf16 v[116:119], v[186:189], v[194:197], v[116:119]
	v_mfma_f32_16x16x32_bf16 v[100:103], v[186:189], v[212:215], v[100:103]
	v_mfma_f32_16x16x32_bf16 v[100:103], v[190:193], v[216:219], v[100:103]
	v_mfma_f32_16x16x32_bf16 v[104:107], v[182:185], v[216:219], v[104:107]
	v_mfma_f32_16x16x32_bf16 v[104:107], v[178:181], v[212:215], v[104:107]
	v_mfma_f32_16x16x32_bf16 v[88:91], v[178:181], v[220:223], v[88:91]
	v_mfma_f32_16x16x32_bf16 v[88:91], v[182:185], v[224:227], v[88:91]
	v_mfma_f32_16x16x32_bf16 v[84:87], v[190:193], v[224:227], v[84:87]
	v_mfma_f32_16x16x32_bf16 v[84:87], v[186:189], v[220:223], v[84:87]
	v_mfma_f32_16x16x32_bf16 v[68:71], v[186:189], v[228:231], v[68:71]
	v_mfma_f32_16x16x32_bf16 v[68:71], v[190:193], v[232:235], v[68:71]
	v_mfma_f32_16x16x32_bf16 v[72:75], v[182:185], v[232:235], v[72:75]
	v_mfma_f32_16x16x32_bf16 v[72:75], v[178:181], v[228:231], v[72:75]
	s_setprio 0
	s_barrier
	s_add_i32 s36, s43, s54
	v_lshl_add_u64 v[168:169], v[168:169], 0, s[18:19]
	s_mov_b32 m0, s36
	ds_read_b128 v[194:197], v159 offset:49152
	ds_read_b128 v[208:211], v159 offset:50176
	ds_read_b128 v[212:215], v159 offset:51200
	ds_read_b128 v[216:219], v159 offset:52224
	ds_read_b128 v[220:223], v159 offset:53248
	ds_read_b128 v[224:227], v159 offset:54272
	ds_read_b128 v[228:231], v159 offset:55296
	ds_read_b128 v[232:235], v159 offset:56320
	global_load_lds_dwordx4 v[168:169], off
	s_add_i32 m0, s36, 0x2000
	s_add_u32 s34, s34, 0x80080
	v_lshl_add_u64 v[168:169], v[236:237], 0, s[18:19]
	s_addc_u32 s35, s35, 0
	s_add_i32 s36, s64, s54
	global_load_lds_dwordx4 v[168:169], off
	v_lshl_add_u64 v[168:169], s[34:35], 0, v[2:3]
	s_mov_b32 m0, s36
	s_nop 0
	global_load_lds_dwordx4 v[168:169], off
	v_lshl_add_u64 v[168:169], s[34:35], 0, v[132:133]
	s_add_i32 m0, s36, 0x2000
	s_nop 0
	global_load_lds_dwordx4 v[168:169], off
	v_lshl_add_u64 v[168:169], v[238:239], 0, s[18:19]
	s_mov_b32 m0, s60
	s_nop 0
	global_load_lds_dwordx4 v[168:169], off
	v_lshl_add_u64 v[168:169], v[240:241], 0, s[18:19]
	s_mov_b32 m0, s61
	s_nop 0
	global_load_lds_dwordx4 v[168:169], off
	s_waitcnt vmcnt(8)
	s_waitcnt lgkmcnt(0)
	s_barrier
	s_setprio 1
	s_waitcnt lgkmcnt(0)
	v_mfma_f32_16x16x32_bf16 v[64:67], v[142:145], v[194:197], v[64:67]
	v_mfma_f32_16x16x32_bf16 v[64:67], v[146:149], v[208:211], v[64:67]
	v_mfma_f32_16x16x32_bf16 v[60:63], v[164:167], v[208:211], v[60:63]
	v_mfma_f32_16x16x32_bf16 v[60:63], v[160:163], v[194:197], v[60:63]
	v_mfma_f32_16x16x32_bf16 v[44:47], v[160:163], v[212:215], v[44:47]
	v_mfma_f32_16x16x32_bf16 v[44:47], v[164:167], v[216:219], v[44:47]
	v_mfma_f32_16x16x32_bf16 v[48:51], v[146:149], v[216:219], v[48:51]
	v_mfma_f32_16x16x32_bf16 v[48:51], v[142:145], v[212:215], v[48:51]
	v_mfma_f32_16x16x32_bf16 v[32:35], v[142:145], v[220:223], v[32:35]
	v_mfma_f32_16x16x32_bf16 v[32:35], v[146:149], v[224:227], v[32:35]
	v_mfma_f32_16x16x32_bf16 v[28:31], v[164:167], v[224:227], v[28:31]
	v_mfma_f32_16x16x32_bf16 v[28:31], v[160:163], v[220:223], v[28:31]
	v_mfma_f32_16x16x32_bf16 v[12:15], v[160:163], v[228:231], v[12:15]
	v_mfma_f32_16x16x32_bf16 v[12:15], v[164:167], v[232:235], v[12:15]
	v_mfma_f32_16x16x32_bf16 v[16:19], v[146:149], v[232:235], v[16:19]
	v_mfma_f32_16x16x32_bf16 v[16:19], v[142:145], v[228:231], v[16:19]
	s_setprio 0
	s_setprio 1
	v_mfma_f32_16x16x32_bf16 v[56:59], v[178:181], v[194:197], v[56:59]
	v_mfma_f32_16x16x32_bf16 v[56:59], v[182:185], v[208:211], v[56:59]
	v_mfma_f32_16x16x32_bf16 v[52:55], v[190:193], v[208:211], v[52:55]
	v_mfma_f32_16x16x32_bf16 v[52:55], v[186:189], v[194:197], v[52:55]
	v_mfma_f32_16x16x32_bf16 v[36:39], v[186:189], v[212:215], v[36:39]
	v_mfma_f32_16x16x32_bf16 v[36:39], v[190:193], v[216:219], v[36:39]
	v_mfma_f32_16x16x32_bf16 v[40:43], v[182:185], v[216:219], v[40:43]
	v_mfma_f32_16x16x32_bf16 v[40:43], v[178:181], v[212:215], v[40:43]
	v_mfma_f32_16x16x32_bf16 v[24:27], v[178:181], v[220:223], v[24:27]
	v_mfma_f32_16x16x32_bf16 v[24:27], v[182:185], v[224:227], v[24:27]
	v_mfma_f32_16x16x32_bf16 v[20:23], v[190:193], v[224:227], v[20:23]
	v_mfma_f32_16x16x32_bf16 v[20:23], v[186:189], v[220:223], v[20:23]
	v_mfma_f32_16x16x32_bf16 v[4:7], v[186:189], v[228:231], v[4:7]
	v_mfma_f32_16x16x32_bf16 v[4:7], v[190:193], v[232:235], v[4:7]
	v_mfma_f32_16x16x32_bf16 v[8:11], v[182:185], v[232:235], v[8:11]
	v_mfma_f32_16x16x32_bf16 v[8:11], v[178:181], v[228:231], v[8:11]
	s_setprio 0
	s_barrier
	s_add_i32 s33, s33, 2
	s_add_u32 s26, s26, 0x100
	s_addc_u32 s27, s27, 0
	s_add_u32 s22, s22, 0x100
	s_addc_u32 s29, s29, 0
	s_cmp_gt_u32 s33, 29
	s_cbranch_scc0 .LBB0_198
	s_and_b64 vcc, exec, s[12:13]
	s_cbranch_vccz .LBB0_201
	s_barrier

.LBB0_708:
	s_add_u32 s42, s40, 0xfff80080
	s_addc_u32 s43, s41, -1
	s_add_i32 s61, 0, 0x10000
	s_cmp_eq_u32 s55, 28
	s_cselect_b32 s45, s27, s43
	s_cselect_b32 s44, s51, s42
	v_add_u32_e32 v142, s61, v144
	s_cselect_b32 s43, s13, s54
	s_cselect_b32 s42, s52, s53
	s_add_i32 s65, 0, 0x14000
	ds_read_b128 v[148:151], v142
	ds_read_b128 v[152:155], v142 offset:1024
	ds_read_b128 v[156:159], v142 offset:2048
	ds_read_b128 v[160:163], v142 offset:3072
	v_add_u32_e32 v142, s65, v144
	ds_read_b128 v[164:167], v142
	ds_read_b128 v[178:181], v142 offset:1024
	ds_read_b128 v[182:185], v142 offset:2048
	ds_read_b128 v[186:189], v142 offset:3072
	v_lshl_add_u64 v[142:143], s[40:41], 0, v[138:139]
	s_add_i32 m0, s21, 0xc000
	ds_read_b128 v[190:193], v146
	ds_read_b128 v[194:197], v146 offset:1024
	ds_read_b128 v[208:211], v146 offset:2048
	ds_read_b128 v[212:215], v146 offset:3072
	ds_read_b128 v[216:219], v146 offset:4096
	ds_read_b128 v[220:223], v146 offset:5120
	ds_read_b128 v[224:227], v146 offset:6144
	ds_read_b128 v[228:231], v146 offset:7168
	global_load_lds_dwordx4 v[142:143], off
	v_lshl_add_u64 v[142:143], s[40:41], 0, v[140:141]
	s_add_i32 m0, s21, 0xe000
	s_nop 0
	global_load_lds_dwordx4 v[142:143], off
	s_waitcnt vmcnt(8)
	s_waitcnt lgkmcnt(0)
	s_barrier
	s_setprio 1
	s_waitcnt lgkmcnt(0)
	v_mfma_f32_16x16x32_bf16 v[128:131], v[148:151], v[190:193], v[128:131]
	v_mfma_f32_16x16x32_bf16 v[128:131], v[152:155], v[194:197], v[128:131]
	v_mfma_f32_16x16x32_bf16 v[124:127], v[160:163], v[194:197], v[124:127]
	v_mfma_f32_16x16x32_bf16 v[124:127], v[156:159], v[190:193], v[124:127]
	v_mfma_f32_16x16x32_bf16 v[112:115], v[156:159], v[208:211], v[112:115]
	v_mfma_f32_16x16x32_bf16 v[112:115], v[160:163], v[212:215], v[112:115]
	v_mfma_f32_16x16x32_bf16 v[120:123], v[152:155], v[212:215], v[120:123]
	v_mfma_f32_16x16x32_bf16 v[120:123], v[148:151], v[208:211], v[120:123]
	v_mfma_f32_16x16x32_bf16 v[104:107], v[148:151], v[216:219], v[104:107]
	v_mfma_f32_16x16x32_bf16 v[104:107], v[152:155], v[220:223], v[104:107]
	v_mfma_f32_16x16x32_bf16 v[96:99], v[160:163], v[220:223], v[96:99]
	v_mfma_f32_16x16x32_bf16 v[96:99], v[156:159], v[216:219], v[96:99]
	v_mfma_f32_16x16x32_bf16 v[80:83], v[156:159], v[224:227], v[80:83]
	v_mfma_f32_16x16x32_bf16 v[80:83], v[160:163], v[228:231], v[80:83]
	v_mfma_f32_16x16x32_bf16 v[88:91], v[152:155], v[228:231], v[88:91]
	v_mfma_f32_16x16x32_bf16 v[88:91], v[148:151], v[224:227], v[88:91]
	s_setprio 0
	s_setprio 1
	v_mfma_f32_16x16x32_bf16 v[116:119], v[164:167], v[190:193], v[116:119]
	v_mfma_f32_16x16x32_bf16 v[116:119], v[178:181], v[194:197], v[116:119]
	v_mfma_f32_16x16x32_bf16 v[108:111], v[186:189], v[194:197], v[108:111]
	v_mfma_f32_16x16x32_bf16 v[108:111], v[182:185], v[190:193], v[108:111]
	v_mfma_f32_16x16x32_bf16 v[92:95], v[182:185], v[208:211], v[92:95]
	v_mfma_f32_16x16x32_bf16 v[92:95], v[186:189], v[212:215], v[92:95]
	v_mfma_f32_16x16x32_bf16 v[100:103], v[178:181], v[212:215], v[100:103]
	v_mfma_f32_16x16x32_bf16 v[100:103], v[164:167], v[208:211], v[100:103]
	v_mfma_f32_16x16x32_bf16 v[84:87], v[164:167], v[216:219], v[84:87]
	v_mfma_f32_16x16x32_bf16 v[84:87], v[178:181], v[220:223], v[84:87]
	v_mfma_f32_16x16x32_bf16 v[76:79], v[186:189], v[220:223], v[76:79]
	v_mfma_f32_16x16x32_bf16 v[76:79], v[182:185], v[216:219], v[76:79]
	v_mfma_f32_16x16x32_bf16 v[68:71], v[182:185], v[224:227], v[68:71]
	v_mfma_f32_16x16x32_bf16 v[68:71], v[186:189], v[228:231], v[68:71]
	v_mfma_f32_16x16x32_bf16 v[72:75], v[178:181], v[228:231], v[72:75]
	v_mfma_f32_16x16x32_bf16 v[72:75], v[164:167], v[224:227], v[72:75]
	s_setprio 0
	s_barrier
	s_add_i32 s61, s61, s11
	v_lshl_add_u64 v[142:143], s[42:43], 0, v[2:3]
	s_mov_b32 m0, s61
	ds_read_b128 v[190:193], v146 offset:16384
	ds_read_b128 v[194:197], v146 offset:17408
	ds_read_b128 v[208:211], v146 offset:18432
	ds_read_b128 v[212:215], v146 offset:19456
	ds_read_b128 v[216:219], v146 offset:20480
	ds_read_b128 v[220:223], v146 offset:21504
	ds_read_b128 v[224:227], v146 offset:22528
	ds_read_b128 v[228:231], v146 offset:23552
	global_load_lds_dwordx4 v[142:143], off
	s_add_i32 m0, s61, 0x2000
	s_add_u32 s62, s42, 0x80000
	v_lshl_add_u64 v[168:169], s[42:43], 0, v[136:137]
	s_addc_u32 s63, s43, 0
	s_add_i32 s61, s65, s11
	global_load_lds_dwordx4 v[168:169], off
	v_lshl_add_u64 v[232:233], s[62:63], 0, v[2:3]
	s_mov_b32 m0, s61
	v_lshl_add_u64 v[234:235], s[44:45], 0, v[134:135]
	global_load_lds_dwordx4 v[232:233], off
	v_lshl_add_u64 v[232:233], s[62:63], 0, v[136:137]
	s_add_i32 m0, s61, 0x2000
	s_nop 0
	global_load_lds_dwordx4 v[232:233], off
	v_lshl_add_u64 v[232:233], s[44:45], 0, v[132:133]
	s_mov_b32 m0, s21
	s_nop 0
	global_load_lds_dwordx4 v[232:233], off
	s_mov_b32 m0, s22
	s_nop 0
	global_load_lds_dwordx4 v[234:235], off
	s_waitcnt vmcnt(8)
	s_waitcnt lgkmcnt(0)
	s_barrier
	s_setprio 1
	s_waitcnt lgkmcnt(0)
	v_mfma_f32_16x16x32_bf16 v[64:67], v[148:151], v[190:193], v[64:67]
	v_mfma_f32_16x16x32_bf16 v[64:67], v[152:155], v[194:197], v[64:67]
	v_mfma_f32_16x16x32_bf16 v[60:63], v[160:163], v[194:197], v[60:63]
	v_mfma_f32_16x16x32_bf16 v[60:63], v[156:159], v[190:193], v[60:63]
	v_mfma_f32_16x16x32_bf16 v[48:51], v[156:159], v[208:211], v[48:51]
	v_mfma_f32_16x16x32_bf16 v[48:51], v[160:163], v[212:215], v[48:51]
	v_mfma_f32_16x16x32_bf16 v[56:59], v[152:155], v[212:215], v[56:59]
	v_mfma_f32_16x16x32_bf16 v[56:59], v[148:151], v[208:211], v[56:59]
	v_mfma_f32_16x16x32_bf16 v[40:43], v[148:151], v[216:219], v[40:43]
	v_mfma_f32_16x16x32_bf16 v[40:43], v[152:155], v[220:223], v[40:43]
	v_mfma_f32_16x16x32_bf16 v[32:35], v[160:163], v[220:223], v[32:35]
	v_mfma_f32_16x16x32_bf16 v[32:35], v[156:159], v[216:219], v[32:35]
	v_mfma_f32_16x16x32_bf16 v[16:19], v[156:159], v[224:227], v[16:19]
	v_mfma_f32_16x16x32_bf16 v[16:19], v[160:163], v[228:231], v[16:19]
	v_mfma_f32_16x16x32_bf16 v[24:27], v[152:155], v[228:231], v[24:27]
	v_mfma_f32_16x16x32_bf16 v[24:27], v[148:151], v[224:227], v[24:27]
	s_setprio 0
	s_setprio 1
	v_mfma_f32_16x16x32_bf16 v[52:55], v[164:167], v[190:193], v[52:55]
	v_mfma_f32_16x16x32_bf16 v[52:55], v[178:181], v[194:197], v[52:55]
	v_mfma_f32_16x16x32_bf16 v[44:47], v[186:189], v[194:197], v[44:47]
	v_mfma_f32_16x16x32_bf16 v[44:47], v[182:185], v[190:193], v[44:47]
	v_mfma_f32_16x16x32_bf16 v[28:31], v[182:185], v[208:211], v[28:31]
	v_mfma_f32_16x16x32_bf16 v[28:31], v[186:189], v[212:215], v[28:31]
	v_mfma_f32_16x16x32_bf16 v[36:39], v[178:181], v[212:215], v[36:39]
	v_mfma_f32_16x16x32_bf16 v[36:39], v[164:167], v[208:211], v[36:39]
	v_mfma_f32_16x16x32_bf16 v[20:23], v[164:167], v[216:219], v[20:23]
	v_mfma_f32_16x16x32_bf16 v[20:23], v[178:181], v[220:223], v[20:23]
	v_mfma_f32_16x16x32_bf16 v[12:15], v[186:189], v[220:223], v[12:15]
	v_mfma_f32_16x16x32_bf16 v[12:15], v[182:185], v[216:219], v[12:15]
	v_mfma_f32_16x16x32_bf16 v[4:7], v[182:185], v[224:227], v[4:7]
	v_mfma_f32_16x16x32_bf16 v[4:7], v[186:189], v[228:231], v[4:7]
	v_mfma_f32_16x16x32_bf16 v[8:11], v[178:181], v[228:231], v[8:11]
	v_mfma_f32_16x16x32_bf16 v[8:11], v[164:167], v[224:227], v[8:11]
	s_setprio 0
	s_barrier
	s_add_i32 s61, 0, 0x18000
	v_add_u32_e32 v147, s61, v144
	s_add_i32 s62, 0, 0x1c000
	ds_read_b128 v[148:151], v147
	ds_read_b128 v[152:155], v147 offset:1024
	ds_read_b128 v[156:159], v147 offset:2048
	ds_read_b128 v[160:163], v147 offset:3072
	v_add_u32_e32 v147, s62, v144
	ds_read_b128 v[164:167], v147
	ds_read_b128 v[178:181], v147 offset:1024
	ds_read_b128 v[182:185], v147 offset:2048
	ds_read_b128 v[186:189], v147 offset:3072
	s_add_u32 s44, s44, 0x80000
	s_addc_u32 s45, s45, 0
	s_mov_b32 m0, s33
	v_lshl_add_u64 v[236:237], s[44:45], 0, v[132:133]
	ds_read_b128 v[190:193], v146 offset:32768
	ds_read_b128 v[194:197], v146 offset:33792
	ds_read_b128 v[208:211], v146 offset:34816
	ds_read_b128 v[212:215], v146 offset:35840
	ds_read_b128 v[216:219], v146 offset:36864
	ds_read_b128 v[220:223], v146 offset:37888
	ds_read_b128 v[224:227], v146 offset:38912
	ds_read_b128 v[228:231], v146 offset:39936
	global_load_lds_dwordx4 v[236:237], off
	v_lshl_add_u64 v[236:237], s[44:45], 0, v[134:135]
	s_mov_b32 m0, s46
	s_nop 0
	global_load_lds_dwordx4 v[236:237], off
	s_waitcnt vmcnt(8)
	s_waitcnt lgkmcnt(0)
	s_barrier
	s_setprio 1
	s_waitcnt lgkmcnt(0)
	v_mfma_f32_16x16x32_bf16 v[128:131], v[148:151], v[190:193], v[128:131]
	v_mfma_f32_16x16x32_bf16 v[128:131], v[152:155], v[194:197], v[128:131]
	v_mfma_f32_16x16x32_bf16 v[124:127], v[160:163], v[194:197], v[124:127]
	v_mfma_f32_16x16x32_bf16 v[124:127], v[156:159], v[190:193], v[124:127]
	v_mfma_f32_16x16x32_bf16 v[112:115], v[156:159], v[208:211], v[112:115]
	v_mfma_f32_16x16x32_bf16 v[112:115], v[160:163], v[212:215], v[112:115]
	v_mfma_f32_16x16x32_bf16 v[120:123], v[152:155], v[212:215], v[120:123]
	v_mfma_f32_16x16x32_bf16 v[120:123], v[148:151], v[208:211], v[120:123]
	v_mfma_f32_16x16x32_bf16 v[104:107], v[148:151], v[216:219], v[104:107]
	v_mfma_f32_16x16x32_bf16 v[104:107], v[152:155], v[220:223], v[104:107]
	v_mfma_f32_16x16x32_bf16 v[96:99], v[160:163], v[220:223], v[96:99]
	v_mfma_f32_16x16x32_bf16 v[96:99], v[156:159], v[216:219], v[96:99]
	v_mfma_f32_16x16x32_bf16 v[80:83], v[156:159], v[224:227], v[80:83]
	v_mfma_f32_16x16x32_bf16 v[80:83], v[160:163], v[228:231], v[80:83]
	v_mfma_f32_16x16x32_bf16 v[88:91], v[152:155], v[228:231], v[88:91]
	v_mfma_f32_16x16x32_bf16 v[88:91], v[148:151], v[224:227], v[88:91]
	s_setprio 0
	s_setprio 1
	v_mfma_f32_16x16x32_bf16 v[116:119], v[164:167], v[190:193], v[116:119]
	v_mfma_f32_16x16x32_bf16 v[116:119], v[178:181], v[194:197], v[116:119]
	v_mfma_f32_16x16x32_bf16 v[108:111], v[186:189], v[194:197], v[108:111]
	v_mfma_f32_16x16x32_bf16 v[108:111], v[182:185], v[190:193], v[108:111]
	v_mfma_f32_16x16x32_bf16 v[92:95], v[182:185], v[208:211], v[92:95]
	v_mfma_f32_16x16x32_bf16 v[92:95], v[186:189], v[212:215], v[92:95]
	v_mfma_f32_16x16x32_bf16 v[100:103], v[178:181], v[212:215], v[100:103]
	v_mfma_f32_16x16x32_bf16 v[100:103], v[164:167], v[208:211], v[100:103]
	v_mfma_f32_16x16x32_bf16 v[84:87], v[164:167], v[216:219], v[84:87]
	v_mfma_f32_16x16x32_bf16 v[84:87], v[178:181], v[220:223], v[84:87]
	v_mfma_f32_16x16x32_bf16 v[76:79], v[186:189], v[220:223], v[76:79]
	v_mfma_f32_16x16x32_bf16 v[76:79], v[182:185], v[216:219], v[76:79]
	v_mfma_f32_16x16x32_bf16 v[68:71], v[182:185], v[224:227], v[68:71]
	v_mfma_f32_16x16x32_bf16 v[68:71], v[186:189], v[228:231], v[68:71]
	v_mfma_f32_16x16x32_bf16 v[72:75], v[178:181], v[228:231], v[72:75]
	v_mfma_f32_16x16x32_bf16 v[72:75], v[164:167], v[224:227], v[72:75]
	s_setprio 0
	s_barrier
	s_add_i32 s44, s61, s11
	v_lshl_add_u64 v[142:143], v[142:143], 0, s[18:19]
	s_mov_b32 m0, s44
	ds_read_b128 v[190:193], v146 offset:49152
	ds_read_b128 v[194:197], v146 offset:50176
	ds_read_b128 v[208:211], v146 offset:51200
	ds_read_b128 v[212:215], v146 offset:52224
	ds_read_b128 v[216:219], v146 offset:53248
	ds_read_b128 v[220:223], v146 offset:54272
	ds_read_b128 v[224:227], v146 offset:55296
	ds_read_b128 v[228:231], v146 offset:56320
	global_load_lds_dwordx4 v[142:143], off
	s_add_i32 m0, s44, 0x2000
	s_add_u32 s42, s42, 0x80080
	v_lshl_add_u64 v[142:143], v[168:169], 0, s[18:19]
	s_addc_u32 s43, s43, 0
	s_add_i32 s44, s62, s11
	global_load_lds_dwordx4 v[142:143], off
	v_lshl_add_u64 v[142:143], s[42:43], 0, v[2:3]
	s_mov_b32 m0, s44
	s_nop 0
	global_load_lds_dwordx4 v[142:143], off
	v_lshl_add_u64 v[142:143], s[42:43], 0, v[136:137]
	s_add_i32 m0, s44, 0x2000
	s_nop 0
	global_load_lds_dwordx4 v[142:143], off
	v_lshl_add_u64 v[142:143], v[232:233], 0, s[18:19]
	s_mov_b32 m0, s47
	s_nop 0
	global_load_lds_dwordx4 v[142:143], off
	v_lshl_add_u64 v[142:143], v[234:235], 0, s[18:19]
	s_mov_b32 m0, s48
	s_nop 0
	global_load_lds_dwordx4 v[142:143], off
	s_waitcnt vmcnt(8)
	s_waitcnt lgkmcnt(0)
	s_barrier
	s_setprio 1
	s_waitcnt lgkmcnt(0)
	v_mfma_f32_16x16x32_bf16 v[64:67], v[148:151], v[190:193], v[64:67]
	v_mfma_f32_16x16x32_bf16 v[64:67], v[152:155], v[194:197], v[64:67]
	v_mfma_f32_16x16x32_bf16 v[60:63], v[160:163], v[194:197], v[60:63]
	v_mfma_f32_16x16x32_bf16 v[60:63], v[156:159], v[190:193], v[60:63]
	v_mfma_f32_16x16x32_bf16 v[48:51], v[156:159], v[208:211], v[48:51]
	v_mfma_f32_16x16x32_bf16 v[48:51], v[160:163], v[212:215], v[48:51]
	v_mfma_f32_16x16x32_bf16 v[56:59], v[152:155], v[212:215], v[56:59]
	v_mfma_f32_16x16x32_bf16 v[56:59], v[148:151], v[208:211], v[56:59]
	v_mfma_f32_16x16x32_bf16 v[40:43], v[148:151], v[216:219], v[40:43]
	v_mfma_f32_16x16x32_bf16 v[40:43], v[152:155], v[220:223], v[40:43]
	v_mfma_f32_16x16x32_bf16 v[32:35], v[160:163], v[220:223], v[32:35]
	v_mfma_f32_16x16x32_bf16 v[32:35], v[156:159], v[216:219], v[32:35]
	v_mfma_f32_16x16x32_bf16 v[16:19], v[156:159], v[224:227], v[16:19]
	v_mfma_f32_16x16x32_bf16 v[16:19], v[160:163], v[228:231], v[16:19]
	v_mfma_f32_16x16x32_bf16 v[24:27], v[152:155], v[228:231], v[24:27]
	v_mfma_f32_16x16x32_bf16 v[24:27], v[148:151], v[224:227], v[24:27]
	s_setprio 0
	s_setprio 1
	v_mfma_f32_16x16x32_bf16 v[52:55], v[164:167], v[190:193], v[52:55]
	v_mfma_f32_16x16x32_bf16 v[52:55], v[178:181], v[194:197], v[52:55]
	v_mfma_f32_16x16x32_bf16 v[44:47], v[186:189], v[194:197], v[44:47]
	v_mfma_f32_16x16x32_bf16 v[44:47], v[182:185], v[190:193], v[44:47]
	v_mfma_f32_16x16x32_bf16 v[28:31], v[182:185], v[208:211], v[28:31]
	v_mfma_f32_16x16x32_bf16 v[28:31], v[186:189], v[212:215], v[28:31]
	v_mfma_f32_16x16x32_bf16 v[36:39], v[178:181], v[212:215], v[36:39]
	v_mfma_f32_16x16x32_bf16 v[36:39], v[164:167], v[208:211], v[36:39]
	v_mfma_f32_16x16x32_bf16 v[20:23], v[164:167], v[216:219], v[20:23]
	v_mfma_f32_16x16x32_bf16 v[20:23], v[178:181], v[220:223], v[20:23]
	v_mfma_f32_16x16x32_bf16 v[12:15], v[186:189], v[220:223], v[12:15]
	v_mfma_f32_16x16x32_bf16 v[12:15], v[182:185], v[216:219], v[12:15]
	v_mfma_f32_16x16x32_bf16 v[4:7], v[182:185], v[224:227], v[4:7]
	v_mfma_f32_16x16x32_bf16 v[4:7], v[186:189], v[228:231], v[4:7]
	v_mfma_f32_16x16x32_bf16 v[8:11], v[178:181], v[228:231], v[8:11]
	v_mfma_f32_16x16x32_bf16 v[8:11], v[164:167], v[224:227], v[8:11]
	s_setprio 0
	s_barrier
	s_add_i32 s55, s55, 2
	s_add_u32 s40, s40, 0x100
	s_addc_u32 s41, s41, 0
	s_add_u32 s53, s53, 0x100
	s_addc_u32 s54, s54, 0
	s_cmp_gt_u32 s55, 29
	s_cbranch_scc0 .LBB0_708
	s_and_b64 vcc, exec, s[8:9]
	s_cbranch_vccz .LBB0_711
	s_barrier

.LBB0_722:
	s_add_u32 s47, s38, s46
	s_addc_u32 s52, s39, 0
	s_add_u32 s50, s47, 0x100
	s_addc_u32 s51, s52, 0
	s_and_b64 s[48:49], s[44:45], exec
	s_cselect_b32 s49, s5, s51
	s_cselect_b32 s48, s70, s50
	s_add_u32 s46, s40, s46
	s_addc_u32 s50, s41, 0
	s_add_u32 s46, s46, 0x100
	s_addc_u32 s50, s50, 0
	s_add_i32 s83, 0, 0x10000
	s_and_b64 s[44:45], s[44:45], exec
	s_cselect_b32 s51, s71, s50
	s_cselect_b32 s50, s72, s46
	s_add_i32 s45, 0, 0x14000
	s_add_u32 s54, s47, 0x80080
	s_addc_u32 s55, s52, 0
	s_add_i32 s82, s83, s21
	s_add_i32 m0, s33, 0xc000
	s_add_i32 s85, s33, 0xe000
	s_add_i32 s77, s82, 0x2000
	v_add_u32_e32 v2, s83, v136
	s_add_u32 s52, s50, 0x80000
	ds_read_b128 v[140:143], v2
	ds_read_b128 v[144:147], v2 offset:1024
	ds_read_b128 v[148:151], v2 offset:2048
	ds_read_b128 v[152:155], v2 offset:3072
	v_add_u32_e32 v2, s45, v136
	s_addc_u32 s53, s51, 0
	s_add_i32 s81, s45, s21
	ds_read_b128 v[156:159], v2
	ds_read_b128 v[160:163], v2 offset:1024
	ds_read_b128 v[164:167], v2 offset:2048
	ds_read_b128 v[178:181], v2 offset:3072
	s_add_i32 s80, s81, 0x2000
	s_add_i32 s76, 0, 0x18000
	s_add_i32 s75, 0, 0x1c000
	s_add_u32 s46, s48, 0x80000
	s_addc_u32 s47, s49, 0
	s_add_i32 s74, s76, s21
	s_add_i32 s73, s74, 0x2000
	s_add_u32 s44, s50, 0x80080
	s_addc_u32 s45, s51, 0
	s_add_i32 s84, s75, s21
	s_add_i32 s83, s84, 0x2000
	v_lshl_add_u64 v[168:169], s[54:55], 0, v[134:135]
	ds_read_b128 v[182:185], v138
	ds_read_b128 v[186:189], v138 offset:1024
	ds_read_b128 v[190:193], v138 offset:2048
	ds_read_b128 v[194:197], v138 offset:3072
	ds_read_b128 v[208:211], v138 offset:4096
	ds_read_b128 v[212:215], v138 offset:5120
	ds_read_b128 v[216:219], v138 offset:6144
	ds_read_b128 v[220:223], v138 offset:7168
	global_load_lds_dwordx4 v[168:169], off
	v_lshl_add_u64 v[168:169], s[54:55], 0, v[132:133]
	s_mov_b32 m0, s85
	s_nop 0
	global_load_lds_dwordx4 v[168:169], off
	s_waitcnt vmcnt(8)
	s_waitcnt lgkmcnt(0)
	s_barrier
	s_setprio 1
	s_waitcnt lgkmcnt(0)
	v_mfma_f32_16x16x32_bf16 v[128:131], v[140:143], v[182:185], v[128:131]
	v_mfma_f32_16x16x32_bf16 v[128:131], v[144:147], v[186:189], v[128:131]
	v_mfma_f32_16x16x32_bf16 v[124:127], v[152:155], v[186:189], v[124:127]
	v_mfma_f32_16x16x32_bf16 v[124:127], v[148:151], v[182:185], v[124:127]
	v_mfma_f32_16x16x32_bf16 v[116:119], v[148:151], v[190:193], v[116:119]
	v_mfma_f32_16x16x32_bf16 v[116:119], v[152:155], v[194:197], v[116:119]
	v_mfma_f32_16x16x32_bf16 v[120:123], v[144:147], v[194:197], v[120:123]
	v_mfma_f32_16x16x32_bf16 v[120:123], v[140:143], v[190:193], v[120:123]
	v_mfma_f32_16x16x32_bf16 v[108:111], v[140:143], v[208:211], v[108:111]
	v_mfma_f32_16x16x32_bf16 v[108:111], v[144:147], v[212:215], v[108:111]
	v_mfma_f32_16x16x32_bf16 v[100:103], v[152:155], v[212:215], v[100:103]
	v_mfma_f32_16x16x32_bf16 v[100:103], v[148:151], v[208:211], v[100:103]
	v_mfma_f32_16x16x32_bf16 v[84:87], v[148:151], v[216:219], v[84:87]
	v_mfma_f32_16x16x32_bf16 v[84:87], v[152:155], v[220:223], v[84:87]
	v_mfma_f32_16x16x32_bf16 v[92:95], v[144:147], v[220:223], v[92:95]
	v_mfma_f32_16x16x32_bf16 v[92:95], v[140:143], v[216:219], v[92:95]
	s_setprio 0
	s_setprio 1
	v_mfma_f32_16x16x32_bf16 v[112:115], v[156:159], v[182:185], v[112:115]
	v_mfma_f32_16x16x32_bf16 v[112:115], v[160:163], v[186:189], v[112:115]
	v_mfma_f32_16x16x32_bf16 v[104:107], v[178:181], v[186:189], v[104:107]
	v_mfma_f32_16x16x32_bf16 v[104:107], v[164:167], v[182:185], v[104:107]
	v_mfma_f32_16x16x32_bf16 v[88:91], v[164:167], v[190:193], v[88:91]
	v_mfma_f32_16x16x32_bf16 v[88:91], v[178:181], v[194:197], v[88:91]
	v_mfma_f32_16x16x32_bf16 v[96:99], v[160:163], v[194:197], v[96:99]
	v_mfma_f32_16x16x32_bf16 v[96:99], v[156:159], v[190:193], v[96:99]
	v_mfma_f32_16x16x32_bf16 v[80:83], v[156:159], v[208:211], v[80:83]
	v_mfma_f32_16x16x32_bf16 v[80:83], v[160:163], v[212:215], v[80:83]
	v_mfma_f32_16x16x32_bf16 v[76:79], v[178:181], v[212:215], v[76:79]
	v_mfma_f32_16x16x32_bf16 v[76:79], v[164:167], v[208:211], v[76:79]
	v_mfma_f32_16x16x32_bf16 v[68:71], v[164:167], v[216:219], v[68:71]
	v_mfma_f32_16x16x32_bf16 v[68:71], v[178:181], v[220:223], v[68:71]
	v_mfma_f32_16x16x32_bf16 v[72:75], v[160:163], v[220:223], v[72:75]
	v_mfma_f32_16x16x32_bf16 v[72:75], v[156:159], v[216:219], v[72:75]
	s_setprio 0
	s_barrier
	s_mov_b32 m0, s82
	v_lshl_add_u64 v[168:169], s[50:51], 0, v[134:135]
	ds_read_b128 v[182:185], v138 offset:16384
	ds_read_b128 v[186:189], v138 offset:17408
	ds_read_b128 v[190:193], v138 offset:18432
	ds_read_b128 v[194:197], v138 offset:19456
	ds_read_b128 v[208:211], v138 offset:20480
	ds_read_b128 v[212:215], v138 offset:21504
	ds_read_b128 v[216:219], v138 offset:22528
	ds_read_b128 v[220:223], v138 offset:23552
	global_load_lds_dwordx4 v[168:169], off
	v_lshl_add_u64 v[224:225], s[50:51], 0, v[132:133]
	s_mov_b32 m0, s77
	v_lshl_add_u64 v[226:227], s[52:53], 0, v[134:135]
	global_load_lds_dwordx4 v[224:225], off
	s_mov_b32 m0, s81
	v_lshl_add_u64 v[228:229], s[48:49], 0, v[132:133]
	global_load_lds_dwordx4 v[226:227], off
	v_lshl_add_u64 v[226:227], s[52:53], 0, v[132:133]
	s_mov_b32 m0, s80
	s_nop 0
	global_load_lds_dwordx4 v[226:227], off
	v_lshl_add_u64 v[226:227], s[48:49], 0, v[134:135]
	s_mov_b32 m0, s33
	s_nop 0
	global_load_lds_dwordx4 v[226:227], off
	s_mov_b32 m0, s61
	s_nop 0
	global_load_lds_dwordx4 v[228:229], off
	s_waitcnt vmcnt(8)
	s_waitcnt lgkmcnt(0)
	s_barrier
	s_setprio 1
	s_waitcnt lgkmcnt(0)
	v_mfma_f32_16x16x32_bf16 v[64:67], v[140:143], v[182:185], v[64:67]
	v_mfma_f32_16x16x32_bf16 v[64:67], v[144:147], v[186:189], v[64:67]
	v_mfma_f32_16x16x32_bf16 v[60:63], v[152:155], v[186:189], v[60:63]
	v_mfma_f32_16x16x32_bf16 v[60:63], v[148:151], v[182:185], v[60:63]
	v_mfma_f32_16x16x32_bf16 v[52:55], v[148:151], v[190:193], v[52:55]
	v_mfma_f32_16x16x32_bf16 v[52:55], v[152:155], v[194:197], v[52:55]
	v_mfma_f32_16x16x32_bf16 v[56:59], v[144:147], v[194:197], v[56:59]
	v_mfma_f32_16x16x32_bf16 v[56:59], v[140:143], v[190:193], v[56:59]
	v_mfma_f32_16x16x32_bf16 v[40:43], v[140:143], v[208:211], v[40:43]
	v_mfma_f32_16x16x32_bf16 v[40:43], v[144:147], v[212:215], v[40:43]
	v_mfma_f32_16x16x32_bf16 v[36:39], v[152:155], v[212:215], v[36:39]
	v_mfma_f32_16x16x32_bf16 v[36:39], v[148:151], v[208:211], v[36:39]
	v_mfma_f32_16x16x32_bf16 v[20:23], v[148:151], v[216:219], v[20:23]
	v_mfma_f32_16x16x32_bf16 v[20:23], v[152:155], v[220:223], v[20:23]
	v_mfma_f32_16x16x32_bf16 v[24:27], v[144:147], v[220:223], v[24:27]
	v_mfma_f32_16x16x32_bf16 v[24:27], v[140:143], v[216:219], v[24:27]
	s_setprio 0
	s_setprio 1
	v_mfma_f32_16x16x32_bf16 v[48:51], v[156:159], v[182:185], v[48:51]
	v_mfma_f32_16x16x32_bf16 v[48:51], v[160:163], v[186:189], v[48:51]
	v_mfma_f32_16x16x32_bf16 v[44:47], v[178:181], v[186:189], v[44:47]
	v_mfma_f32_16x16x32_bf16 v[44:47], v[164:167], v[182:185], v[44:47]
	v_mfma_f32_16x16x32_bf16 v[28:31], v[164:167], v[190:193], v[28:31]
	v_mfma_f32_16x16x32_bf16 v[28:31], v[178:181], v[194:197], v[28:31]
	v_mfma_f32_16x16x32_bf16 v[32:35], v[160:163], v[194:197], v[32:35]
	v_mfma_f32_16x16x32_bf16 v[32:35], v[156:159], v[190:193], v[32:35]
	v_mfma_f32_16x16x32_bf16 v[16:19], v[156:159], v[208:211], v[16:19]
	v_mfma_f32_16x16x32_bf16 v[16:19], v[160:163], v[212:215], v[16:19]
	v_mfma_f32_16x16x32_bf16 v[12:15], v[178:181], v[212:215], v[12:15]
	v_mfma_f32_16x16x32_bf16 v[12:15], v[164:167], v[208:211], v[12:15]
	v_mfma_f32_16x16x32_bf16 v[4:7], v[164:167], v[216:219], v[4:7]
	v_mfma_f32_16x16x32_bf16 v[4:7], v[178:181], v[220:223], v[4:7]
	v_mfma_f32_16x16x32_bf16 v[8:11], v[160:163], v[220:223], v[8:11]
	v_mfma_f32_16x16x32_bf16 v[8:11], v[156:159], v[216:219], v[8:11]
	s_setprio 0
	s_barrier
	v_add_u32_e32 v2, s76, v136
	ds_read_b128 v[140:143], v2
	ds_read_b128 v[144:147], v2 offset:1024
	ds_read_b128 v[148:151], v2 offset:2048
	ds_read_b128 v[152:155], v2 offset:3072
	v_add_u32_e32 v2, s75, v136
	ds_read_b128 v[156:159], v2
	ds_read_b128 v[160:163], v2 offset:1024
	ds_read_b128 v[164:167], v2 offset:2048
	ds_read_b128 v[178:181], v2 offset:3072
	s_mov_b32 m0, s62
	v_lshl_add_u64 v[230:231], s[46:47], 0, v[134:135]
	ds_read_b128 v[182:185], v138 offset:32768
	ds_read_b128 v[186:189], v138 offset:33792
	ds_read_b128 v[190:193], v138 offset:34816
	ds_read_b128 v[194:197], v138 offset:35840
	ds_read_b128 v[208:211], v138 offset:36864
	ds_read_b128 v[212:215], v138 offset:37888
	ds_read_b128 v[216:219], v138 offset:38912
	ds_read_b128 v[220:223], v138 offset:39936
	global_load_lds_dwordx4 v[230:231], off
	v_lshl_add_u64 v[230:231], s[46:47], 0, v[132:133]
	s_mov_b32 m0, s63
	s_nop 0
	global_load_lds_dwordx4 v[230:231], off
	s_waitcnt vmcnt(8)
	s_waitcnt lgkmcnt(0)
	s_barrier
	s_setprio 1
	s_waitcnt lgkmcnt(0)
	v_mfma_f32_16x16x32_bf16 v[128:131], v[140:143], v[182:185], v[128:131]
	v_mfma_f32_16x16x32_bf16 v[128:131], v[144:147], v[186:189], v[128:131]
	v_mfma_f32_16x16x32_bf16 v[124:127], v[152:155], v[186:189], v[124:127]
	v_mfma_f32_16x16x32_bf16 v[124:127], v[148:151], v[182:185], v[124:127]
	v_mfma_f32_16x16x32_bf16 v[116:119], v[148:151], v[190:193], v[116:119]
	v_mfma_f32_16x16x32_bf16 v[116:119], v[152:155], v[194:197], v[116:119]
	v_mfma_f32_16x16x32_bf16 v[120:123], v[144:147], v[194:197], v[120:123]
	v_mfma_f32_16x16x32_bf16 v[120:123], v[140:143], v[190:193], v[120:123]
	v_mfma_f32_16x16x32_bf16 v[108:111], v[140:143], v[208:211], v[108:111]
	v_mfma_f32_16x16x32_bf16 v[108:111], v[144:147], v[212:215], v[108:111]
	v_mfma_f32_16x16x32_bf16 v[100:103], v[152:155], v[212:215], v[100:103]
	v_mfma_f32_16x16x32_bf16 v[100:103], v[148:151], v[208:211], v[100:103]
	v_mfma_f32_16x16x32_bf16 v[84:87], v[148:151], v[216:219], v[84:87]
	v_mfma_f32_16x16x32_bf16 v[84:87], v[152:155], v[220:223], v[84:87]
	v_mfma_f32_16x16x32_bf16 v[92:95], v[144:147], v[220:223], v[92:95]
	v_mfma_f32_16x16x32_bf16 v[92:95], v[140:143], v[216:219], v[92:95]
	s_setprio 0
	s_setprio 1
	v_mfma_f32_16x16x32_bf16 v[112:115], v[156:159], v[182:185], v[112:115]
	v_mfma_f32_16x16x32_bf16 v[112:115], v[160:163], v[186:189], v[112:115]
	v_mfma_f32_16x16x32_bf16 v[104:107], v[178:181], v[186:189], v[104:107]
	v_mfma_f32_16x16x32_bf16 v[104:107], v[164:167], v[182:185], v[104:107]
	v_mfma_f32_16x16x32_bf16 v[88:91], v[164:167], v[190:193], v[88:91]
	v_mfma_f32_16x16x32_bf16 v[88:91], v[178:181], v[194:197], v[88:91]
	v_mfma_f32_16x16x32_bf16 v[96:99], v[160:163], v[194:197], v[96:99]
	v_mfma_f32_16x16x32_bf16 v[96:99], v[156:159], v[190:193], v[96:99]
	v_mfma_f32_16x16x32_bf16 v[80:83], v[156:159], v[208:211], v[80:83]
	v_mfma_f32_16x16x32_bf16 v[80:83], v[160:163], v[212:215], v[80:83]
	v_mfma_f32_16x16x32_bf16 v[76:79], v[178:181], v[212:215], v[76:79]
	v_mfma_f32_16x16x32_bf16 v[76:79], v[164:167], v[208:211], v[76:79]
	v_mfma_f32_16x16x32_bf16 v[68:71], v[164:167], v[216:219], v[68:71]
	v_mfma_f32_16x16x32_bf16 v[68:71], v[178:181], v[220:223], v[68:71]
	v_mfma_f32_16x16x32_bf16 v[72:75], v[160:163], v[220:223], v[72:75]
	v_mfma_f32_16x16x32_bf16 v[72:75], v[156:159], v[216:219], v[72:75]
	s_setprio 0
	s_barrier
	s_mov_b32 m0, s74
	v_lshl_add_u64 v[168:169], v[168:169], 0, s[18:19]
	ds_read_b128 v[182:185], v138 offset:49152
	ds_read_b128 v[186:189], v138 offset:50176
	ds_read_b128 v[190:193], v138 offset:51200
	ds_read_b128 v[194:197], v138 offset:52224
	ds_read_b128 v[208:211], v138 offset:53248
	ds_read_b128 v[212:215], v138 offset:54272
	ds_read_b128 v[216:219], v138 offset:55296
	ds_read_b128 v[220:223], v138 offset:56320
	global_load_lds_dwordx4 v[168:169], off
	v_lshl_add_u64 v[168:169], v[224:225], 0, s[18:19]
	s_mov_b32 m0, s73
	s_nop 0
	global_load_lds_dwordx4 v[168:169], off
	v_lshl_add_u64 v[168:169], s[44:45], 0, v[134:135]
	s_mov_b32 m0, s84
	s_nop 0
	global_load_lds_dwordx4 v[168:169], off
	v_lshl_add_u64 v[168:169], s[44:45], 0, v[132:133]
	s_mov_b32 m0, s83
	s_nop 0
	global_load_lds_dwordx4 v[168:169], off
	v_lshl_add_u64 v[168:169], v[226:227], 0, s[18:19]
	s_mov_b32 m0, s65
	s_nop 0
	global_load_lds_dwordx4 v[168:169], off
	v_lshl_add_u64 v[168:169], v[228:229], 0, s[18:19]
	s_mov_b32 m0, s66
	s_nop 0
	global_load_lds_dwordx4 v[168:169], off
	s_waitcnt vmcnt(8)
	s_waitcnt lgkmcnt(0)
	s_barrier
	s_setprio 1
	s_waitcnt lgkmcnt(0)
	v_mfma_f32_16x16x32_bf16 v[64:67], v[140:143], v[182:185], v[64:67]
	v_mfma_f32_16x16x32_bf16 v[64:67], v[144:147], v[186:189], v[64:67]
	v_mfma_f32_16x16x32_bf16 v[60:63], v[152:155], v[186:189], v[60:63]
	v_mfma_f32_16x16x32_bf16 v[60:63], v[148:151], v[182:185], v[60:63]
	v_mfma_f32_16x16x32_bf16 v[52:55], v[148:151], v[190:193], v[52:55]
	v_mfma_f32_16x16x32_bf16 v[52:55], v[152:155], v[194:197], v[52:55]
	v_mfma_f32_16x16x32_bf16 v[56:59], v[144:147], v[194:197], v[56:59]
	v_mfma_f32_16x16x32_bf16 v[56:59], v[140:143], v[190:193], v[56:59]
	v_mfma_f32_16x16x32_bf16 v[40:43], v[140:143], v[208:211], v[40:43]
	v_mfma_f32_16x16x32_bf16 v[40:43], v[144:147], v[212:215], v[40:43]
	v_mfma_f32_16x16x32_bf16 v[36:39], v[152:155], v[212:215], v[36:39]
	v_mfma_f32_16x16x32_bf16 v[36:39], v[148:151], v[208:211], v[36:39]
	v_mfma_f32_16x16x32_bf16 v[20:23], v[148:151], v[216:219], v[20:23]
	v_mfma_f32_16x16x32_bf16 v[20:23], v[152:155], v[220:223], v[20:23]
	v_mfma_f32_16x16x32_bf16 v[24:27], v[144:147], v[220:223], v[24:27]
	v_mfma_f32_16x16x32_bf16 v[24:27], v[140:143], v[216:219], v[24:27]
	s_setprio 0
	s_setprio 1
	v_mfma_f32_16x16x32_bf16 v[48:51], v[156:159], v[182:185], v[48:51]
	v_mfma_f32_16x16x32_bf16 v[48:51], v[160:163], v[186:189], v[48:51]
	v_mfma_f32_16x16x32_bf16 v[44:47], v[178:181], v[186:189], v[44:47]
	v_mfma_f32_16x16x32_bf16 v[44:47], v[164:167], v[182:185], v[44:47]
	v_mfma_f32_16x16x32_bf16 v[28:31], v[164:167], v[190:193], v[28:31]
	v_mfma_f32_16x16x32_bf16 v[28:31], v[178:181], v[194:197], v[28:31]
	v_mfma_f32_16x16x32_bf16 v[32:35], v[160:163], v[194:197], v[32:35]
	v_mfma_f32_16x16x32_bf16 v[32:35], v[156:159], v[190:193], v[32:35]
	v_mfma_f32_16x16x32_bf16 v[16:19], v[156:159], v[208:211], v[16:19]
	v_mfma_f32_16x16x32_bf16 v[16:19], v[160:163], v[212:215], v[16:19]
	v_mfma_f32_16x16x32_bf16 v[12:15], v[178:181], v[212:215], v[12:15]
	v_mfma_f32_16x16x32_bf16 v[12:15], v[164:167], v[208:211], v[12:15]
	v_mfma_f32_16x16x32_bf16 v[4:7], v[164:167], v[216:219], v[4:7]
	v_mfma_f32_16x16x32_bf16 v[4:7], v[178:181], v[220:223], v[4:7]
	v_mfma_f32_16x16x32_bf16 v[8:11], v[160:163], v[220:223], v[8:11]
	v_mfma_f32_16x16x32_bf16 v[8:11], v[156:159], v[216:219], v[8:11]
	s_setprio 0
	s_barrier
	s_movk_i32 s46, 0x100
	s_andn2_b64 vcc, exec, s[42:43]
	s_mov_b64 s[44:45], -1
	s_mov_b64 s[42:43], 0
	s_cbranch_vccz .LBB0_722
	s_and_b64 vcc, exec, s[34:35]
	s_cbranch_vccz .LBB0_725
	s_barrier

.LBB0_748:
	s_add_u32 s42, s40, 0xfff00080
	s_addc_u32 s43, s41, -1
	s_add_i32 s61, 0, 0x10000
	s_cmp_eq_u32 s55, 60
	s_cselect_b32 s45, s27, s43
	s_cselect_b32 s44, s51, s42
	v_add_u32_e32 v142, s61, v144
	s_cselect_b32 s43, s13, s54
	s_cselect_b32 s42, s52, s53
	s_add_i32 s65, 0, 0x14000
	ds_read_b128 v[148:151], v142
	ds_read_b128 v[152:155], v142 offset:1024
	ds_read_b128 v[156:159], v142 offset:2048
	ds_read_b128 v[160:163], v142 offset:3072
	v_add_u32_e32 v142, s65, v144
	ds_read_b128 v[164:167], v142
	ds_read_b128 v[178:181], v142 offset:1024
	ds_read_b128 v[182:185], v142 offset:2048
	ds_read_b128 v[186:189], v142 offset:3072
	v_lshl_add_u64 v[142:143], s[40:41], 0, v[138:139]
	s_add_i32 m0, s21, 0xc000
	ds_read_b128 v[190:193], v146
	ds_read_b128 v[194:197], v146 offset:1024
	ds_read_b128 v[208:211], v146 offset:2048
	ds_read_b128 v[212:215], v146 offset:3072
	ds_read_b128 v[216:219], v146 offset:4096
	ds_read_b128 v[220:223], v146 offset:5120
	ds_read_b128 v[224:227], v146 offset:6144
	ds_read_b128 v[228:231], v146 offset:7168
	global_load_lds_dwordx4 v[142:143], off
	v_lshl_add_u64 v[142:143], s[40:41], 0, v[140:141]
	s_add_i32 m0, s21, 0xe000
	s_nop 0
	global_load_lds_dwordx4 v[142:143], off
	s_waitcnt vmcnt(8)
	s_waitcnt lgkmcnt(0)
	s_barrier
	s_setprio 1
	s_waitcnt lgkmcnt(0)
	v_mfma_f32_16x16x32_bf16 v[128:131], v[148:151], v[190:193], v[128:131]
	v_mfma_f32_16x16x32_bf16 v[128:131], v[152:155], v[194:197], v[128:131]
	v_mfma_f32_16x16x32_bf16 v[124:127], v[160:163], v[194:197], v[124:127]
	v_mfma_f32_16x16x32_bf16 v[124:127], v[156:159], v[190:193], v[124:127]
	v_mfma_f32_16x16x32_bf16 v[112:115], v[156:159], v[208:211], v[112:115]
	v_mfma_f32_16x16x32_bf16 v[112:115], v[160:163], v[212:215], v[112:115]
	v_mfma_f32_16x16x32_bf16 v[120:123], v[152:155], v[212:215], v[120:123]
	v_mfma_f32_16x16x32_bf16 v[120:123], v[148:151], v[208:211], v[120:123]
	v_mfma_f32_16x16x32_bf16 v[104:107], v[148:151], v[216:219], v[104:107]
	v_mfma_f32_16x16x32_bf16 v[104:107], v[152:155], v[220:223], v[104:107]
	v_mfma_f32_16x16x32_bf16 v[96:99], v[160:163], v[220:223], v[96:99]
	v_mfma_f32_16x16x32_bf16 v[96:99], v[156:159], v[216:219], v[96:99]
	v_mfma_f32_16x16x32_bf16 v[80:83], v[156:159], v[224:227], v[80:83]
	v_mfma_f32_16x16x32_bf16 v[80:83], v[160:163], v[228:231], v[80:83]
	v_mfma_f32_16x16x32_bf16 v[88:91], v[152:155], v[228:231], v[88:91]
	v_mfma_f32_16x16x32_bf16 v[88:91], v[148:151], v[224:227], v[88:91]
	s_setprio 0
	s_setprio 1
	v_mfma_f32_16x16x32_bf16 v[116:119], v[164:167], v[190:193], v[116:119]
	v_mfma_f32_16x16x32_bf16 v[116:119], v[178:181], v[194:197], v[116:119]
	v_mfma_f32_16x16x32_bf16 v[108:111], v[186:189], v[194:197], v[108:111]
	v_mfma_f32_16x16x32_bf16 v[108:111], v[182:185], v[190:193], v[108:111]
	v_mfma_f32_16x16x32_bf16 v[92:95], v[182:185], v[208:211], v[92:95]
	v_mfma_f32_16x16x32_bf16 v[92:95], v[186:189], v[212:215], v[92:95]
	v_mfma_f32_16x16x32_bf16 v[100:103], v[178:181], v[212:215], v[100:103]
	v_mfma_f32_16x16x32_bf16 v[100:103], v[164:167], v[208:211], v[100:103]
	v_mfma_f32_16x16x32_bf16 v[84:87], v[164:167], v[216:219], v[84:87]
	v_mfma_f32_16x16x32_bf16 v[84:87], v[178:181], v[220:223], v[84:87]
	v_mfma_f32_16x16x32_bf16 v[76:79], v[186:189], v[220:223], v[76:79]
	v_mfma_f32_16x16x32_bf16 v[76:79], v[182:185], v[216:219], v[76:79]
	v_mfma_f32_16x16x32_bf16 v[68:71], v[182:185], v[224:227], v[68:71]
	v_mfma_f32_16x16x32_bf16 v[68:71], v[186:189], v[228:231], v[68:71]
	v_mfma_f32_16x16x32_bf16 v[72:75], v[178:181], v[228:231], v[72:75]
	v_mfma_f32_16x16x32_bf16 v[72:75], v[164:167], v[224:227], v[72:75]
	s_setprio 0
	s_barrier
	s_add_i32 s61, s61, s11
	v_lshl_add_u64 v[142:143], s[42:43], 0, v[2:3]
	s_mov_b32 m0, s61
	ds_read_b128 v[190:193], v146 offset:16384
	ds_read_b128 v[194:197], v146 offset:17408
	ds_read_b128 v[208:211], v146 offset:18432
	ds_read_b128 v[212:215], v146 offset:19456
	ds_read_b128 v[216:219], v146 offset:20480
	ds_read_b128 v[220:223], v146 offset:21504
	ds_read_b128 v[224:227], v146 offset:22528
	ds_read_b128 v[228:231], v146 offset:23552
	global_load_lds_dwordx4 v[142:143], off
	s_add_i32 m0, s61, 0x2000
	s_add_u32 s62, s42, 0x100000
	v_lshl_add_u64 v[168:169], s[42:43], 0, v[136:137]
	s_addc_u32 s63, s43, 0
	s_add_i32 s61, s65, s11
	global_load_lds_dwordx4 v[168:169], off
	v_lshl_add_u64 v[232:233], s[62:63], 0, v[2:3]
	s_mov_b32 m0, s61
	v_lshl_add_u64 v[234:235], s[44:45], 0, v[134:135]
	global_load_lds_dwordx4 v[232:233], off
	v_lshl_add_u64 v[232:233], s[62:63], 0, v[136:137]
	s_add_i32 m0, s61, 0x2000
	s_nop 0
	global_load_lds_dwordx4 v[232:233], off
	v_lshl_add_u64 v[232:233], s[44:45], 0, v[132:133]
	s_mov_b32 m0, s21
	s_nop 0
	global_load_lds_dwordx4 v[232:233], off
	s_mov_b32 m0, s22
	s_nop 0
	global_load_lds_dwordx4 v[234:235], off
	s_waitcnt vmcnt(8)
	s_waitcnt lgkmcnt(0)
	s_barrier
	s_setprio 1
	s_waitcnt lgkmcnt(0)
	v_mfma_f32_16x16x32_bf16 v[64:67], v[148:151], v[190:193], v[64:67]
	v_mfma_f32_16x16x32_bf16 v[64:67], v[152:155], v[194:197], v[64:67]
	v_mfma_f32_16x16x32_bf16 v[60:63], v[160:163], v[194:197], v[60:63]
	v_mfma_f32_16x16x32_bf16 v[60:63], v[156:159], v[190:193], v[60:63]
	v_mfma_f32_16x16x32_bf16 v[48:51], v[156:159], v[208:211], v[48:51]
	v_mfma_f32_16x16x32_bf16 v[48:51], v[160:163], v[212:215], v[48:51]
	v_mfma_f32_16x16x32_bf16 v[56:59], v[152:155], v[212:215], v[56:59]
	v_mfma_f32_16x16x32_bf16 v[56:59], v[148:151], v[208:211], v[56:59]
	v_mfma_f32_16x16x32_bf16 v[40:43], v[148:151], v[216:219], v[40:43]
	v_mfma_f32_16x16x32_bf16 v[40:43], v[152:155], v[220:223], v[40:43]
	v_mfma_f32_16x16x32_bf16 v[32:35], v[160:163], v[220:223], v[32:35]
	v_mfma_f32_16x16x32_bf16 v[32:35], v[156:159], v[216:219], v[32:35]
	v_mfma_f32_16x16x32_bf16 v[16:19], v[156:159], v[224:227], v[16:19]
	v_mfma_f32_16x16x32_bf16 v[16:19], v[160:163], v[228:231], v[16:19]
	v_mfma_f32_16x16x32_bf16 v[24:27], v[152:155], v[228:231], v[24:27]
	v_mfma_f32_16x16x32_bf16 v[24:27], v[148:151], v[224:227], v[24:27]
	s_setprio 0
	s_setprio 1
	v_mfma_f32_16x16x32_bf16 v[52:55], v[164:167], v[190:193], v[52:55]
	v_mfma_f32_16x16x32_bf16 v[52:55], v[178:181], v[194:197], v[52:55]
	v_mfma_f32_16x16x32_bf16 v[44:47], v[186:189], v[194:197], v[44:47]
	v_mfma_f32_16x16x32_bf16 v[44:47], v[182:185], v[190:193], v[44:47]
	v_mfma_f32_16x16x32_bf16 v[28:31], v[182:185], v[208:211], v[28:31]
	v_mfma_f32_16x16x32_bf16 v[28:31], v[186:189], v[212:215], v[28:31]
	v_mfma_f32_16x16x32_bf16 v[36:39], v[178:181], v[212:215], v[36:39]
	v_mfma_f32_16x16x32_bf16 v[36:39], v[164:167], v[208:211], v[36:39]
	v_mfma_f32_16x16x32_bf16 v[20:23], v[164:167], v[216:219], v[20:23]
	v_mfma_f32_16x16x32_bf16 v[20:23], v[178:181], v[220:223], v[20:23]
	v_mfma_f32_16x16x32_bf16 v[12:15], v[186:189], v[220:223], v[12:15]
	v_mfma_f32_16x16x32_bf16 v[12:15], v[182:185], v[216:219], v[12:15]
	v_mfma_f32_16x16x32_bf16 v[4:7], v[182:185], v[224:227], v[4:7]
	v_mfma_f32_16x16x32_bf16 v[4:7], v[186:189], v[228:231], v[4:7]
	v_mfma_f32_16x16x32_bf16 v[8:11], v[178:181], v[228:231], v[8:11]
	v_mfma_f32_16x16x32_bf16 v[8:11], v[164:167], v[224:227], v[8:11]
	s_setprio 0
	s_barrier
	s_add_i32 s61, 0, 0x18000
	v_add_u32_e32 v147, s61, v144
	s_add_i32 s62, 0, 0x1c000
	ds_read_b128 v[148:151], v147
	ds_read_b128 v[152:155], v147 offset:1024
	ds_read_b128 v[156:159], v147 offset:2048
	ds_read_b128 v[160:163], v147 offset:3072
	v_add_u32_e32 v147, s62, v144
	ds_read_b128 v[164:167], v147
	ds_read_b128 v[178:181], v147 offset:1024
	ds_read_b128 v[182:185], v147 offset:2048
	ds_read_b128 v[186:189], v147 offset:3072
	s_add_u32 s44, s44, 0x100000
	s_addc_u32 s45, s45, 0
	s_mov_b32 m0, s33
	v_lshl_add_u64 v[236:237], s[44:45], 0, v[132:133]
	ds_read_b128 v[190:193], v146 offset:32768
	ds_read_b128 v[194:197], v146 offset:33792
	ds_read_b128 v[208:211], v146 offset:34816
	ds_read_b128 v[212:215], v146 offset:35840
	ds_read_b128 v[216:219], v146 offset:36864
	ds_read_b128 v[220:223], v146 offset:37888
	ds_read_b128 v[224:227], v146 offset:38912
	ds_read_b128 v[228:231], v146 offset:39936
	global_load_lds_dwordx4 v[236:237], off
	v_lshl_add_u64 v[236:237], s[44:45], 0, v[134:135]
	s_mov_b32 m0, s46
	s_nop 0
	global_load_lds_dwordx4 v[236:237], off
	s_waitcnt vmcnt(8)
	s_waitcnt lgkmcnt(0)
	s_barrier
	s_setprio 1
	s_waitcnt lgkmcnt(0)
	v_mfma_f32_16x16x32_bf16 v[128:131], v[148:151], v[190:193], v[128:131]
	v_mfma_f32_16x16x32_bf16 v[128:131], v[152:155], v[194:197], v[128:131]
	v_mfma_f32_16x16x32_bf16 v[124:127], v[160:163], v[194:197], v[124:127]
	v_mfma_f32_16x16x32_bf16 v[124:127], v[156:159], v[190:193], v[124:127]
	v_mfma_f32_16x16x32_bf16 v[112:115], v[156:159], v[208:211], v[112:115]
	v_mfma_f32_16x16x32_bf16 v[112:115], v[160:163], v[212:215], v[112:115]
	v_mfma_f32_16x16x32_bf16 v[120:123], v[152:155], v[212:215], v[120:123]
	v_mfma_f32_16x16x32_bf16 v[120:123], v[148:151], v[208:211], v[120:123]
	v_mfma_f32_16x16x32_bf16 v[104:107], v[148:151], v[216:219], v[104:107]
	v_mfma_f32_16x16x32_bf16 v[104:107], v[152:155], v[220:223], v[104:107]
	v_mfma_f32_16x16x32_bf16 v[96:99], v[160:163], v[220:223], v[96:99]
	v_mfma_f32_16x16x32_bf16 v[96:99], v[156:159], v[216:219], v[96:99]
	v_mfma_f32_16x16x32_bf16 v[80:83], v[156:159], v[224:227], v[80:83]
	v_mfma_f32_16x16x32_bf16 v[80:83], v[160:163], v[228:231], v[80:83]
	v_mfma_f32_16x16x32_bf16 v[88:91], v[152:155], v[228:231], v[88:91]
	v_mfma_f32_16x16x32_bf16 v[88:91], v[148:151], v[224:227], v[88:91]
	s_setprio 0
	s_setprio 1
	v_mfma_f32_16x16x32_bf16 v[116:119], v[164:167], v[190:193], v[116:119]
	v_mfma_f32_16x16x32_bf16 v[116:119], v[178:181], v[194:197], v[116:119]
	v_mfma_f32_16x16x32_bf16 v[108:111], v[186:189], v[194:197], v[108:111]
	v_mfma_f32_16x16x32_bf16 v[108:111], v[182:185], v[190:193], v[108:111]
	v_mfma_f32_16x16x32_bf16 v[92:95], v[182:185], v[208:211], v[92:95]
	v_mfma_f32_16x16x32_bf16 v[92:95], v[186:189], v[212:215], v[92:95]
	v_mfma_f32_16x16x32_bf16 v[100:103], v[178:181], v[212:215], v[100:103]
	v_mfma_f32_16x16x32_bf16 v[100:103], v[164:167], v[208:211], v[100:103]
	v_mfma_f32_16x16x32_bf16 v[84:87], v[164:167], v[216:219], v[84:87]
	v_mfma_f32_16x16x32_bf16 v[84:87], v[178:181], v[220:223], v[84:87]
	v_mfma_f32_16x16x32_bf16 v[76:79], v[186:189], v[220:223], v[76:79]
	v_mfma_f32_16x16x32_bf16 v[76:79], v[182:185], v[216:219], v[76:79]
	v_mfma_f32_16x16x32_bf16 v[68:71], v[182:185], v[224:227], v[68:71]
	v_mfma_f32_16x16x32_bf16 v[68:71], v[186:189], v[228:231], v[68:71]
	v_mfma_f32_16x16x32_bf16 v[72:75], v[178:181], v[228:231], v[72:75]
	v_mfma_f32_16x16x32_bf16 v[72:75], v[164:167], v[224:227], v[72:75]
	s_setprio 0
	s_barrier
	s_add_i32 s44, s61, s11
	v_lshl_add_u64 v[142:143], v[142:143], 0, s[18:19]
	s_mov_b32 m0, s44
	ds_read_b128 v[190:193], v146 offset:49152
	ds_read_b128 v[194:197], v146 offset:50176
	ds_read_b128 v[208:211], v146 offset:51200
	ds_read_b128 v[212:215], v146 offset:52224
	ds_read_b128 v[216:219], v146 offset:53248
	ds_read_b128 v[220:223], v146 offset:54272
	ds_read_b128 v[224:227], v146 offset:55296
	ds_read_b128 v[228:231], v146 offset:56320
	global_load_lds_dwordx4 v[142:143], off
	s_add_i32 m0, s44, 0x2000
	s_add_u32 s42, s42, 0x100080
	v_lshl_add_u64 v[142:143], v[168:169], 0, s[18:19]
	s_addc_u32 s43, s43, 0
	s_add_i32 s44, s62, s11
	global_load_lds_dwordx4 v[142:143], off
	v_lshl_add_u64 v[142:143], s[42:43], 0, v[2:3]
	s_mov_b32 m0, s44
	s_nop 0
	global_load_lds_dwordx4 v[142:143], off
	v_lshl_add_u64 v[142:143], s[42:43], 0, v[136:137]
	s_add_i32 m0, s44, 0x2000
	s_nop 0
	global_load_lds_dwordx4 v[142:143], off
	v_lshl_add_u64 v[142:143], v[232:233], 0, s[18:19]
	s_mov_b32 m0, s47
	s_nop 0
	global_load_lds_dwordx4 v[142:143], off
	v_lshl_add_u64 v[142:143], v[234:235], 0, s[18:19]
	s_mov_b32 m0, s48
	s_nop 0
	global_load_lds_dwordx4 v[142:143], off
	s_waitcnt vmcnt(8)
	s_waitcnt lgkmcnt(0)
	s_barrier
	s_setprio 1
	s_waitcnt lgkmcnt(0)
	v_mfma_f32_16x16x32_bf16 v[64:67], v[148:151], v[190:193], v[64:67]
	v_mfma_f32_16x16x32_bf16 v[64:67], v[152:155], v[194:197], v[64:67]
	v_mfma_f32_16x16x32_bf16 v[60:63], v[160:163], v[194:197], v[60:63]
	v_mfma_f32_16x16x32_bf16 v[60:63], v[156:159], v[190:193], v[60:63]
	v_mfma_f32_16x16x32_bf16 v[48:51], v[156:159], v[208:211], v[48:51]
	v_mfma_f32_16x16x32_bf16 v[48:51], v[160:163], v[212:215], v[48:51]
	v_mfma_f32_16x16x32_bf16 v[56:59], v[152:155], v[212:215], v[56:59]
	v_mfma_f32_16x16x32_bf16 v[56:59], v[148:151], v[208:211], v[56:59]
	v_mfma_f32_16x16x32_bf16 v[40:43], v[148:151], v[216:219], v[40:43]
	v_mfma_f32_16x16x32_bf16 v[40:43], v[152:155], v[220:223], v[40:43]
	v_mfma_f32_16x16x32_bf16 v[32:35], v[160:163], v[220:223], v[32:35]
	v_mfma_f32_16x16x32_bf16 v[32:35], v[156:159], v[216:219], v[32:35]
	v_mfma_f32_16x16x32_bf16 v[16:19], v[156:159], v[224:227], v[16:19]
	v_mfma_f32_16x16x32_bf16 v[16:19], v[160:163], v[228:231], v[16:19]
	v_mfma_f32_16x16x32_bf16 v[24:27], v[152:155], v[228:231], v[24:27]
	v_mfma_f32_16x16x32_bf16 v[24:27], v[148:151], v[224:227], v[24:27]
	s_setprio 0
	s_setprio 1
	v_mfma_f32_16x16x32_bf16 v[52:55], v[164:167], v[190:193], v[52:55]
	v_mfma_f32_16x16x32_bf16 v[52:55], v[178:181], v[194:197], v[52:55]
	v_mfma_f32_16x16x32_bf16 v[44:47], v[186:189], v[194:197], v[44:47]
	v_mfma_f32_16x16x32_bf16 v[44:47], v[182:185], v[190:193], v[44:47]
	v_mfma_f32_16x16x32_bf16 v[28:31], v[182:185], v[208:211], v[28:31]
	v_mfma_f32_16x16x32_bf16 v[28:31], v[186:189], v[212:215], v[28:31]
	v_mfma_f32_16x16x32_bf16 v[36:39], v[178:181], v[212:215], v[36:39]
	v_mfma_f32_16x16x32_bf16 v[36:39], v[164:167], v[208:211], v[36:39]
	v_mfma_f32_16x16x32_bf16 v[20:23], v[164:167], v[216:219], v[20:23]
	v_mfma_f32_16x16x32_bf16 v[20:23], v[178:181], v[220:223], v[20:23]
	v_mfma_f32_16x16x32_bf16 v[12:15], v[186:189], v[220:223], v[12:15]
	v_mfma_f32_16x16x32_bf16 v[12:15], v[182:185], v[216:219], v[12:15]
	v_mfma_f32_16x16x32_bf16 v[4:7], v[182:185], v[224:227], v[4:7]
	v_mfma_f32_16x16x32_bf16 v[4:7], v[186:189], v[228:231], v[4:7]
	v_mfma_f32_16x16x32_bf16 v[8:11], v[178:181], v[228:231], v[8:11]
	v_mfma_f32_16x16x32_bf16 v[8:11], v[164:167], v[224:227], v[8:11]
	s_setprio 0
	s_barrier
	s_add_i32 s55, s55, 2
	s_add_u32 s40, s40, 0x100
	s_addc_u32 s41, s41, 0
	s_add_u32 s53, s53, 0x100
	s_addc_u32 s54, s54, 0
	s_cmp_gt_u32 s55, 61
	s_cbranch_scc0 .LBB0_748
	s_and_b64 vcc, exec, s[8:9]
	s_cbranch_vccz .LBB0_751
	s_barrier

.LBB0_762:
	s_add_u32 s38, s36, 0xfff00080
	s_addc_u32 s39, s37, -1
	s_add_i32 s55, 0, 0x10000
	s_cmp_eq_u32 s54, 4
	s_cselect_b32 s41, s3, s39
	s_cselect_b32 s40, s49, s38
	v_add_u32_e32 v2, s55, v140
	s_cselect_b32 s39, s50, s53
	s_cselect_b32 s38, s51, s52
	s_add_i32 s58, 0, 0x14000
	ds_read_b128 v[144:147], v2
	ds_read_b128 v[148:151], v2 offset:1024
	ds_read_b128 v[152:155], v2 offset:2048
	ds_read_b128 v[156:159], v2 offset:3072
	v_add_u32_e32 v2, s58, v140
	ds_read_b128 v[160:163], v2
	ds_read_b128 v[164:167], v2 offset:1024
	ds_read_b128 v[178:181], v2 offset:2048
	ds_read_b128 v[182:185], v2 offset:3072
	v_lshl_add_u64 v[168:169], s[36:37], 0, v[136:137]
	s_add_i32 m0, s33, 0xc000
	ds_read_b128 v[186:189], v142
	ds_read_b128 v[190:193], v142 offset:1024
	ds_read_b128 v[194:197], v142 offset:2048
	ds_read_b128 v[208:211], v142 offset:3072
	ds_read_b128 v[212:215], v142 offset:4096
	ds_read_b128 v[216:219], v142 offset:5120
	ds_read_b128 v[220:223], v142 offset:6144
	ds_read_b128 v[224:227], v142 offset:7168
	global_load_lds_dwordx4 v[168:169], off
	v_lshl_add_u64 v[168:169], s[36:37], 0, v[138:139]
	s_add_i32 m0, s33, 0xe000
	s_nop 0
	global_load_lds_dwordx4 v[168:169], off
	s_waitcnt vmcnt(8)
	s_waitcnt lgkmcnt(0)
	s_barrier
	s_setprio 1
	s_waitcnt lgkmcnt(0)
	v_mfma_f32_16x16x32_bf16 v[128:131], v[144:147], v[186:189], v[128:131]
	v_mfma_f32_16x16x32_bf16 v[128:131], v[148:151], v[190:193], v[128:131]
	v_mfma_f32_16x16x32_bf16 v[124:127], v[156:159], v[190:193], v[124:127]
	v_mfma_f32_16x16x32_bf16 v[124:127], v[152:155], v[186:189], v[124:127]
	v_mfma_f32_16x16x32_bf16 v[116:119], v[152:155], v[194:197], v[116:119]
	v_mfma_f32_16x16x32_bf16 v[116:119], v[156:159], v[208:211], v[116:119]
	v_mfma_f32_16x16x32_bf16 v[120:123], v[148:151], v[208:211], v[120:123]
	v_mfma_f32_16x16x32_bf16 v[120:123], v[144:147], v[194:197], v[120:123]
	v_mfma_f32_16x16x32_bf16 v[108:111], v[144:147], v[212:215], v[108:111]
	v_mfma_f32_16x16x32_bf16 v[108:111], v[148:151], v[216:219], v[108:111]
	v_mfma_f32_16x16x32_bf16 v[100:103], v[156:159], v[216:219], v[100:103]
	v_mfma_f32_16x16x32_bf16 v[100:103], v[152:155], v[212:215], v[100:103]
	v_mfma_f32_16x16x32_bf16 v[84:87], v[152:155], v[220:223], v[84:87]
	v_mfma_f32_16x16x32_bf16 v[84:87], v[156:159], v[224:227], v[84:87]
	v_mfma_f32_16x16x32_bf16 v[92:95], v[148:151], v[224:227], v[92:95]
	v_mfma_f32_16x16x32_bf16 v[92:95], v[144:147], v[220:223], v[92:95]
	s_setprio 0
	s_setprio 1
	v_mfma_f32_16x16x32_bf16 v[112:115], v[160:163], v[186:189], v[112:115]
	v_mfma_f32_16x16x32_bf16 v[112:115], v[164:167], v[190:193], v[112:115]
	v_mfma_f32_16x16x32_bf16 v[104:107], v[182:185], v[190:193], v[104:107]
	v_mfma_f32_16x16x32_bf16 v[104:107], v[178:181], v[186:189], v[104:107]
	v_mfma_f32_16x16x32_bf16 v[88:91], v[178:181], v[194:197], v[88:91]
	v_mfma_f32_16x16x32_bf16 v[88:91], v[182:185], v[208:211], v[88:91]
	v_mfma_f32_16x16x32_bf16 v[96:99], v[164:167], v[208:211], v[96:99]
	v_mfma_f32_16x16x32_bf16 v[96:99], v[160:163], v[194:197], v[96:99]
	v_mfma_f32_16x16x32_bf16 v[80:83], v[160:163], v[212:215], v[80:83]
	v_mfma_f32_16x16x32_bf16 v[80:83], v[164:167], v[216:219], v[80:83]
	v_mfma_f32_16x16x32_bf16 v[76:79], v[182:185], v[216:219], v[76:79]
	v_mfma_f32_16x16x32_bf16 v[76:79], v[178:181], v[212:215], v[76:79]
	v_mfma_f32_16x16x32_bf16 v[68:71], v[178:181], v[220:223], v[68:71]
	v_mfma_f32_16x16x32_bf16 v[68:71], v[182:185], v[224:227], v[68:71]
	v_mfma_f32_16x16x32_bf16 v[72:75], v[164:167], v[224:227], v[72:75]
	v_mfma_f32_16x16x32_bf16 v[72:75], v[160:163], v[220:223], v[72:75]
	s_setprio 0
	s_barrier
	s_add_i32 s55, s55, s21
	v_lshl_add_u64 v[168:169], s[38:39], 0, v[134:135]
	s_mov_b32 m0, s55
	ds_read_b128 v[186:189], v142 offset:16384
	ds_read_b128 v[190:193], v142 offset:17408
	ds_read_b128 v[194:197], v142 offset:18432
	ds_read_b128 v[208:211], v142 offset:19456
	ds_read_b128 v[212:215], v142 offset:20480
	ds_read_b128 v[216:219], v142 offset:21504
	ds_read_b128 v[220:223], v142 offset:22528
	ds_read_b128 v[224:227], v142 offset:23552
	global_load_lds_dwordx4 v[168:169], off
	s_add_i32 m0, s55, 0x2000
	s_add_u32 s56, s38, 0x100000
	v_lshl_add_u64 v[228:229], s[38:39], 0, v[132:133]
	s_addc_u32 s57, s39, 0
	s_add_i32 s55, s58, s21
	global_load_lds_dwordx4 v[228:229], off
	v_lshl_add_u64 v[230:231], s[56:57], 0, v[134:135]
	s_mov_b32 m0, s55
	v_lshl_add_u64 v[232:233], s[40:41], 0, v[132:133]
	global_load_lds_dwordx4 v[230:231], off
	v_lshl_add_u64 v[230:231], s[56:57], 0, v[132:133]
	s_add_i32 m0, s55, 0x2000
	s_nop 0
	global_load_lds_dwordx4 v[230:231], off
	v_lshl_add_u64 v[230:231], s[40:41], 0, v[134:135]
	s_mov_b32 m0, s33
	s_nop 0
	global_load_lds_dwordx4 v[230:231], off
	s_mov_b32 m0, s42
	s_nop 0
	global_load_lds_dwordx4 v[232:233], off
	s_waitcnt vmcnt(8)
	s_waitcnt lgkmcnt(0)
	s_barrier
	s_setprio 1
	s_waitcnt lgkmcnt(0)
	v_mfma_f32_16x16x32_bf16 v[64:67], v[144:147], v[186:189], v[64:67]
	v_mfma_f32_16x16x32_bf16 v[64:67], v[148:151], v[190:193], v[64:67]
	v_mfma_f32_16x16x32_bf16 v[60:63], v[156:159], v[190:193], v[60:63]
	v_mfma_f32_16x16x32_bf16 v[60:63], v[152:155], v[186:189], v[60:63]
	v_mfma_f32_16x16x32_bf16 v[52:55], v[152:155], v[194:197], v[52:55]
	v_mfma_f32_16x16x32_bf16 v[52:55], v[156:159], v[208:211], v[52:55]
	v_mfma_f32_16x16x32_bf16 v[56:59], v[148:151], v[208:211], v[56:59]
	v_mfma_f32_16x16x32_bf16 v[56:59], v[144:147], v[194:197], v[56:59]
	v_mfma_f32_16x16x32_bf16 v[40:43], v[144:147], v[212:215], v[40:43]
	v_mfma_f32_16x16x32_bf16 v[40:43], v[148:151], v[216:219], v[40:43]
	v_mfma_f32_16x16x32_bf16 v[36:39], v[156:159], v[216:219], v[36:39]
	v_mfma_f32_16x16x32_bf16 v[36:39], v[152:155], v[212:215], v[36:39]
	v_mfma_f32_16x16x32_bf16 v[20:23], v[152:155], v[220:223], v[20:23]
	v_mfma_f32_16x16x32_bf16 v[20:23], v[156:159], v[224:227], v[20:23]
	v_mfma_f32_16x16x32_bf16 v[24:27], v[148:151], v[224:227], v[24:27]
	v_mfma_f32_16x16x32_bf16 v[24:27], v[144:147], v[220:223], v[24:27]
	s_setprio 0
	s_setprio 1
	v_mfma_f32_16x16x32_bf16 v[48:51], v[160:163], v[186:189], v[48:51]
	v_mfma_f32_16x16x32_bf16 v[48:51], v[164:167], v[190:193], v[48:51]
	v_mfma_f32_16x16x32_bf16 v[44:47], v[182:185], v[190:193], v[44:47]
	v_mfma_f32_16x16x32_bf16 v[44:47], v[178:181], v[186:189], v[44:47]
	v_mfma_f32_16x16x32_bf16 v[28:31], v[178:181], v[194:197], v[28:31]
	v_mfma_f32_16x16x32_bf16 v[28:31], v[182:185], v[208:211], v[28:31]
	v_mfma_f32_16x16x32_bf16 v[32:35], v[164:167], v[208:211], v[32:35]
	v_mfma_f32_16x16x32_bf16 v[32:35], v[160:163], v[194:197], v[32:35]
	v_mfma_f32_16x16x32_bf16 v[16:19], v[160:163], v[212:215], v[16:19]
	v_mfma_f32_16x16x32_bf16 v[16:19], v[164:167], v[216:219], v[16:19]
	v_mfma_f32_16x16x32_bf16 v[12:15], v[182:185], v[216:219], v[12:15]
	v_mfma_f32_16x16x32_bf16 v[12:15], v[178:181], v[212:215], v[12:15]
	v_mfma_f32_16x16x32_bf16 v[4:7], v[178:181], v[220:223], v[4:7]
	v_mfma_f32_16x16x32_bf16 v[4:7], v[182:185], v[224:227], v[4:7]
	v_mfma_f32_16x16x32_bf16 v[8:11], v[164:167], v[224:227], v[8:11]
	v_mfma_f32_16x16x32_bf16 v[8:11], v[160:163], v[220:223], v[8:11]
	s_setprio 0
	s_barrier
	s_add_i32 s55, 0, 0x18000
	v_add_u32_e32 v2, s55, v140
	s_add_i32 s56, 0, 0x1c000
	ds_read_b128 v[144:147], v2
	ds_read_b128 v[148:151], v2 offset:1024
	ds_read_b128 v[152:155], v2 offset:2048
	ds_read_b128 v[156:159], v2 offset:3072
	v_add_u32_e32 v2, s56, v140
	ds_read_b128 v[160:163], v2
	ds_read_b128 v[164:167], v2 offset:1024
	ds_read_b128 v[178:181], v2 offset:2048
	ds_read_b128 v[182:185], v2 offset:3072
	s_add_u32 s40, s40, 0x100000
	s_addc_u32 s41, s41, 0
	s_mov_b32 m0, s43
	v_lshl_add_u64 v[234:235], s[40:41], 0, v[134:135]
	ds_read_b128 v[186:189], v142 offset:32768
	ds_read_b128 v[190:193], v142 offset:33792
	ds_read_b128 v[194:197], v142 offset:34816
	ds_read_b128 v[208:211], v142 offset:35840
	ds_read_b128 v[212:215], v142 offset:36864
	ds_read_b128 v[216:219], v142 offset:37888
	ds_read_b128 v[220:223], v142 offset:38912
	ds_read_b128 v[224:227], v142 offset:39936
	global_load_lds_dwordx4 v[234:235], off
	v_lshl_add_u64 v[234:235], s[40:41], 0, v[132:133]
	s_mov_b32 m0, s44
	s_nop 0
	global_load_lds_dwordx4 v[234:235], off
	s_waitcnt vmcnt(8)
	s_waitcnt lgkmcnt(0)
	s_barrier
	s_setprio 1
	s_waitcnt lgkmcnt(0)
	v_mfma_f32_16x16x32_bf16 v[128:131], v[144:147], v[186:189], v[128:131]
	v_mfma_f32_16x16x32_bf16 v[128:131], v[148:151], v[190:193], v[128:131]
	v_mfma_f32_16x16x32_bf16 v[124:127], v[156:159], v[190:193], v[124:127]
	v_mfma_f32_16x16x32_bf16 v[124:127], v[152:155], v[186:189], v[124:127]
	v_mfma_f32_16x16x32_bf16 v[116:119], v[152:155], v[194:197], v[116:119]
	v_mfma_f32_16x16x32_bf16 v[116:119], v[156:159], v[208:211], v[116:119]
	v_mfma_f32_16x16x32_bf16 v[120:123], v[148:151], v[208:211], v[120:123]
	v_mfma_f32_16x16x32_bf16 v[120:123], v[144:147], v[194:197], v[120:123]
	v_mfma_f32_16x16x32_bf16 v[108:111], v[144:147], v[212:215], v[108:111]
	v_mfma_f32_16x16x32_bf16 v[108:111], v[148:151], v[216:219], v[108:111]
	v_mfma_f32_16x16x32_bf16 v[100:103], v[156:159], v[216:219], v[100:103]
	v_mfma_f32_16x16x32_bf16 v[100:103], v[152:155], v[212:215], v[100:103]
	v_mfma_f32_16x16x32_bf16 v[84:87], v[152:155], v[220:223], v[84:87]
	v_mfma_f32_16x16x32_bf16 v[84:87], v[156:159], v[224:227], v[84:87]
	v_mfma_f32_16x16x32_bf16 v[92:95], v[148:151], v[224:227], v[92:95]
	v_mfma_f32_16x16x32_bf16 v[92:95], v[144:147], v[220:223], v[92:95]
	s_setprio 0
	s_setprio 1
	v_mfma_f32_16x16x32_bf16 v[112:115], v[160:163], v[186:189], v[112:115]
	v_mfma_f32_16x16x32_bf16 v[112:115], v[164:167], v[190:193], v[112:115]
	v_mfma_f32_16x16x32_bf16 v[104:107], v[182:185], v[190:193], v[104:107]
	v_mfma_f32_16x16x32_bf16 v[104:107], v[178:181], v[186:189], v[104:107]
	v_mfma_f32_16x16x32_bf16 v[88:91], v[178:181], v[194:197], v[88:91]
	v_mfma_f32_16x16x32_bf16 v[88:91], v[182:185], v[208:211], v[88:91]
	v_mfma_f32_16x16x32_bf16 v[96:99], v[164:167], v[208:211], v[96:99]
	v_mfma_f32_16x16x32_bf16 v[96:99], v[160:163], v[194:197], v[96:99]
	v_mfma_f32_16x16x32_bf16 v[80:83], v[160:163], v[212:215], v[80:83]
	v_mfma_f32_16x16x32_bf16 v[80:83], v[164:167], v[216:219], v[80:83]
	v_mfma_f32_16x16x32_bf16 v[76:79], v[182:185], v[216:219], v[76:79]
	v_mfma_f32_16x16x32_bf16 v[76:79], v[178:181], v[212:215], v[76:79]
	v_mfma_f32_16x16x32_bf16 v[68:71], v[178:181], v[220:223], v[68:71]
	v_mfma_f32_16x16x32_bf16 v[68:71], v[182:185], v[224:227], v[68:71]
	v_mfma_f32_16x16x32_bf16 v[72:75], v[164:167], v[224:227], v[72:75]
	v_mfma_f32_16x16x32_bf16 v[72:75], v[160:163], v[220:223], v[72:75]
	s_setprio 0
	s_barrier
	s_add_i32 s40, s55, s21
	v_lshl_add_u64 v[168:169], v[168:169], 0, s[18:19]
	s_mov_b32 m0, s40
	ds_read_b128 v[186:189], v142 offset:49152
	ds_read_b128 v[190:193], v142 offset:50176
	ds_read_b128 v[194:197], v142 offset:51200
	ds_read_b128 v[208:211], v142 offset:52224
	ds_read_b128 v[212:215], v142 offset:53248
	ds_read_b128 v[216:219], v142 offset:54272
	ds_read_b128 v[220:223], v142 offset:55296
	ds_read_b128 v[224:227], v142 offset:56320
	global_load_lds_dwordx4 v[168:169], off
	s_add_i32 m0, s40, 0x2000
	s_add_u32 s38, s38, 0x100080
	v_lshl_add_u64 v[168:169], v[228:229], 0, s[18:19]
	s_addc_u32 s39, s39, 0
	s_add_i32 s40, s56, s21
	global_load_lds_dwordx4 v[168:169], off
	v_lshl_add_u64 v[168:169], s[38:39], 0, v[134:135]
	s_mov_b32 m0, s40
	s_nop 0
	global_load_lds_dwordx4 v[168:169], off
	v_lshl_add_u64 v[168:169], s[38:39], 0, v[132:133]
	s_add_i32 m0, s40, 0x2000
	s_nop 0
	global_load_lds_dwordx4 v[168:169], off
	v_lshl_add_u64 v[168:169], v[230:231], 0, s[18:19]
	s_mov_b32 m0, s25
	s_nop 0
	global_load_lds_dwordx4 v[168:169], off
	v_lshl_add_u64 v[168:169], v[232:233], 0, s[18:19]
	s_mov_b32 m0, s45
	s_nop 0
	global_load_lds_dwordx4 v[168:169], off
	s_waitcnt vmcnt(8)
	s_waitcnt lgkmcnt(0)
	s_barrier
	s_setprio 1
	s_waitcnt lgkmcnt(0)
	v_mfma_f32_16x16x32_bf16 v[64:67], v[144:147], v[186:189], v[64:67]
	v_mfma_f32_16x16x32_bf16 v[64:67], v[148:151], v[190:193], v[64:67]
	v_mfma_f32_16x16x32_bf16 v[60:63], v[156:159], v[190:193], v[60:63]
	v_mfma_f32_16x16x32_bf16 v[60:63], v[152:155], v[186:189], v[60:63]
	v_mfma_f32_16x16x32_bf16 v[52:55], v[152:155], v[194:197], v[52:55]
	v_mfma_f32_16x16x32_bf16 v[52:55], v[156:159], v[208:211], v[52:55]
	v_mfma_f32_16x16x32_bf16 v[56:59], v[148:151], v[208:211], v[56:59]
	v_mfma_f32_16x16x32_bf16 v[56:59], v[144:147], v[194:197], v[56:59]
	v_mfma_f32_16x16x32_bf16 v[40:43], v[144:147], v[212:215], v[40:43]
	v_mfma_f32_16x16x32_bf16 v[40:43], v[148:151], v[216:219], v[40:43]
	v_mfma_f32_16x16x32_bf16 v[36:39], v[156:159], v[216:219], v[36:39]
	v_mfma_f32_16x16x32_bf16 v[36:39], v[152:155], v[212:215], v[36:39]
	v_mfma_f32_16x16x32_bf16 v[20:23], v[152:155], v[220:223], v[20:23]
	v_mfma_f32_16x16x32_bf16 v[20:23], v[156:159], v[224:227], v[20:23]
	v_mfma_f32_16x16x32_bf16 v[24:27], v[148:151], v[224:227], v[24:27]
	v_mfma_f32_16x16x32_bf16 v[24:27], v[144:147], v[220:223], v[24:27]
	s_setprio 0
	s_setprio 1
	v_mfma_f32_16x16x32_bf16 v[48:51], v[160:163], v[186:189], v[48:51]
	v_mfma_f32_16x16x32_bf16 v[48:51], v[164:167], v[190:193], v[48:51]
	v_mfma_f32_16x16x32_bf16 v[44:47], v[182:185], v[190:193], v[44:47]
	v_mfma_f32_16x16x32_bf16 v[44:47], v[178:181], v[186:189], v[44:47]
	v_mfma_f32_16x16x32_bf16 v[28:31], v[178:181], v[194:197], v[28:31]
	v_mfma_f32_16x16x32_bf16 v[28:31], v[182:185], v[208:211], v[28:31]
	v_mfma_f32_16x16x32_bf16 v[32:35], v[164:167], v[208:211], v[32:35]
	v_mfma_f32_16x16x32_bf16 v[32:35], v[160:163], v[194:197], v[32:35]
	v_mfma_f32_16x16x32_bf16 v[16:19], v[160:163], v[212:215], v[16:19]
	v_mfma_f32_16x16x32_bf16 v[16:19], v[164:167], v[216:219], v[16:19]
	v_mfma_f32_16x16x32_bf16 v[12:15], v[182:185], v[216:219], v[12:15]
	v_mfma_f32_16x16x32_bf16 v[12:15], v[178:181], v[212:215], v[12:15]
	v_mfma_f32_16x16x32_bf16 v[4:7], v[178:181], v[220:223], v[4:7]
	v_mfma_f32_16x16x32_bf16 v[4:7], v[182:185], v[224:227], v[4:7]
	v_mfma_f32_16x16x32_bf16 v[8:11], v[164:167], v[224:227], v[8:11]
	v_mfma_f32_16x16x32_bf16 v[8:11], v[160:163], v[220:223], v[8:11]
	s_setprio 0
	s_barrier
	s_add_i32 s54, s54, 2
	s_add_u32 s36, s36, 0x100
	s_addc_u32 s37, s37, 0
	s_add_u32 s52, s52, 0x100
	s_addc_u32 s53, s53, 0
	s_cmp_gt_u32 s54, 5
	s_cbranch_scc0 .LBB0_762
	s_and_b64 vcc, exec, s[28:29]
	s_cbranch_vccz .LBB0_765
	s_barrier

.LBB0_901:
	s_add_u32 s12, s8, 0xfff80080
	s_addc_u32 s13, s9, -1
	s_add_i32 s47, 0, 0x10000
	s_cmp_eq_u32 s33, 28
	s_cselect_b32 s27, s5, s13
	s_cselect_b32 s26, s7, s12
	s_cselect_b32 s13, s10, s22
	s_cselect_b32 s12, s11, s21
	s_add_i32 s49, 0, 0x14000
	v_add_u32_e32 v158, s47, v151
	v_add_u32_e32 v182, s49, v151
	ds_read_b128 v[142:145], v158
	ds_read_b128 v[146:149], v158 offset:1024
	ds_read_b128 v[154:157], v158 offset:2048
	ds_read_b128 v[158:161], v158 offset:3072
	ds_read_b128 v[162:165], v182
	ds_read_b128 v[166:169], v182 offset:1024
	ds_read_b128 v[178:181], v182 offset:2048
	ds_read_b128 v[182:185], v182 offset:3072
	v_lshl_add_u64 v[228:229], s[8:9], 0, v[138:139]
	s_add_i32 m0, s57, 0xc000
	ds_read_b128 v[186:189], v153
	ds_read_b128 v[190:193], v153 offset:1024
	ds_read_b128 v[194:197], v153 offset:2048
	ds_read_b128 v[208:211], v153 offset:3072
	ds_read_b128 v[212:215], v153 offset:4096
	ds_read_b128 v[216:219], v153 offset:5120
	ds_read_b128 v[220:223], v153 offset:6144
	ds_read_b128 v[224:227], v153 offset:7168
	global_load_lds_dwordx4 v[228:229], off
	v_lshl_add_u64 v[228:229], s[8:9], 0, v[140:141]
	s_add_i32 m0, s57, 0xe000
	s_nop 0
	global_load_lds_dwordx4 v[228:229], off
	s_waitcnt vmcnt(8)
	s_waitcnt lgkmcnt(0)
	s_barrier
	s_setprio 1
	s_waitcnt lgkmcnt(0)
	v_mfma_f32_16x16x32_bf16 v[128:131], v[142:145], v[186:189], v[128:131]
	v_mfma_f32_16x16x32_bf16 v[128:131], v[146:149], v[190:193], v[128:131]
	v_mfma_f32_16x16x32_bf16 v[124:127], v[158:161], v[190:193], v[124:127]
	v_mfma_f32_16x16x32_bf16 v[124:127], v[154:157], v[186:189], v[124:127]
	v_mfma_f32_16x16x32_bf16 v[108:111], v[154:157], v[194:197], v[108:111]
	v_mfma_f32_16x16x32_bf16 v[108:111], v[158:161], v[208:211], v[108:111]
	v_mfma_f32_16x16x32_bf16 v[112:115], v[146:149], v[208:211], v[112:115]
	v_mfma_f32_16x16x32_bf16 v[112:115], v[142:145], v[194:197], v[112:115]
	v_mfma_f32_16x16x32_bf16 v[96:99], v[142:145], v[212:215], v[96:99]
	v_mfma_f32_16x16x32_bf16 v[96:99], v[146:149], v[216:219], v[96:99]
	v_mfma_f32_16x16x32_bf16 v[92:95], v[158:161], v[216:219], v[92:95]
	v_mfma_f32_16x16x32_bf16 v[92:95], v[154:157], v[212:215], v[92:95]
	v_mfma_f32_16x16x32_bf16 v[76:79], v[154:157], v[220:223], v[76:79]
	v_mfma_f32_16x16x32_bf16 v[76:79], v[158:161], v[224:227], v[76:79]
	v_mfma_f32_16x16x32_bf16 v[80:83], v[146:149], v[224:227], v[80:83]
	v_mfma_f32_16x16x32_bf16 v[80:83], v[142:145], v[220:223], v[80:83]
	s_setprio 0
	s_setprio 1
	v_mfma_f32_16x16x32_bf16 v[120:123], v[162:165], v[186:189], v[120:123]
	v_mfma_f32_16x16x32_bf16 v[120:123], v[166:169], v[190:193], v[120:123]
	v_mfma_f32_16x16x32_bf16 v[116:119], v[182:185], v[190:193], v[116:119]
	v_mfma_f32_16x16x32_bf16 v[116:119], v[178:181], v[186:189], v[116:119]
	v_mfma_f32_16x16x32_bf16 v[100:103], v[178:181], v[194:197], v[100:103]
	v_mfma_f32_16x16x32_bf16 v[100:103], v[182:185], v[208:211], v[100:103]
	v_mfma_f32_16x16x32_bf16 v[104:107], v[166:169], v[208:211], v[104:107]
	v_mfma_f32_16x16x32_bf16 v[104:107], v[162:165], v[194:197], v[104:107]
	v_mfma_f32_16x16x32_bf16 v[88:91], v[162:165], v[212:215], v[88:91]
	v_mfma_f32_16x16x32_bf16 v[88:91], v[166:169], v[216:219], v[88:91]
	v_mfma_f32_16x16x32_bf16 v[84:87], v[182:185], v[216:219], v[84:87]
	v_mfma_f32_16x16x32_bf16 v[84:87], v[178:181], v[212:215], v[84:87]
	v_mfma_f32_16x16x32_bf16 v[68:71], v[178:181], v[220:223], v[68:71]
	v_mfma_f32_16x16x32_bf16 v[68:71], v[182:185], v[224:227], v[68:71]
	v_mfma_f32_16x16x32_bf16 v[72:75], v[166:169], v[224:227], v[72:75]
	v_mfma_f32_16x16x32_bf16 v[72:75], v[162:165], v[220:223], v[72:75]
	s_setprio 0
	s_barrier
	s_add_i32 s47, s47, s55
	v_lshl_add_u64 v[228:229], s[12:13], 0, v[2:3]
	s_mov_b32 m0, s47
	ds_read_b128 v[186:189], v153 offset:16384
	ds_read_b128 v[190:193], v153 offset:17408
	ds_read_b128 v[194:197], v153 offset:18432
	ds_read_b128 v[208:211], v153 offset:19456
	ds_read_b128 v[212:215], v153 offset:20480
	ds_read_b128 v[216:219], v153 offset:21504
	ds_read_b128 v[220:223], v153 offset:22528
	ds_read_b128 v[224:227], v153 offset:23552
	global_load_lds_dwordx4 v[228:229], off
	s_add_i32 m0, s47, 0x2000
	s_add_u32 s66, s12, 0x80000
	v_lshl_add_u64 v[230:231], s[12:13], 0, v[132:133]
	s_addc_u32 s67, s13, 0
	s_add_i32 s47, s49, s55
	global_load_lds_dwordx4 v[230:231], off
	v_lshl_add_u64 v[232:233], s[66:67], 0, v[2:3]
	s_mov_b32 m0, s47
	v_lshl_add_u64 v[234:235], s[26:27], 0, v[134:135]
	global_load_lds_dwordx4 v[232:233], off
	v_lshl_add_u64 v[232:233], s[66:67], 0, v[132:133]
	s_add_i32 m0, s47, 0x2000
	s_nop 0
	global_load_lds_dwordx4 v[232:233], off
	v_lshl_add_u64 v[232:233], s[26:27], 0, v[136:137]
	s_mov_b32 m0, s57
	s_nop 0
	global_load_lds_dwordx4 v[232:233], off
	s_mov_b32 m0, s58
	s_nop 0
	global_load_lds_dwordx4 v[234:235], off
	s_waitcnt vmcnt(8)
	s_waitcnt lgkmcnt(0)
	s_barrier
	s_setprio 1
	s_waitcnt lgkmcnt(0)
	v_mfma_f32_16x16x32_bf16 v[64:67], v[142:145], v[186:189], v[64:67]
	v_mfma_f32_16x16x32_bf16 v[64:67], v[146:149], v[190:193], v[64:67]
	v_mfma_f32_16x16x32_bf16 v[60:63], v[158:161], v[190:193], v[60:63]
	v_mfma_f32_16x16x32_bf16 v[60:63], v[154:157], v[186:189], v[60:63]
	v_mfma_f32_16x16x32_bf16 v[44:47], v[154:157], v[194:197], v[44:47]
	v_mfma_f32_16x16x32_bf16 v[44:47], v[158:161], v[208:211], v[44:47]
	v_mfma_f32_16x16x32_bf16 v[48:51], v[146:149], v[208:211], v[48:51]
	v_mfma_f32_16x16x32_bf16 v[48:51], v[142:145], v[194:197], v[48:51]
	v_mfma_f32_16x16x32_bf16 v[32:35], v[142:145], v[212:215], v[32:35]
	v_mfma_f32_16x16x32_bf16 v[32:35], v[146:149], v[216:219], v[32:35]
	v_mfma_f32_16x16x32_bf16 v[28:31], v[158:161], v[216:219], v[28:31]
	v_mfma_f32_16x16x32_bf16 v[28:31], v[154:157], v[212:215], v[28:31]
	v_mfma_f32_16x16x32_bf16 v[12:15], v[154:157], v[220:223], v[12:15]
	v_mfma_f32_16x16x32_bf16 v[12:15], v[158:161], v[224:227], v[12:15]
	v_mfma_f32_16x16x32_bf16 v[16:19], v[146:149], v[224:227], v[16:19]
	v_mfma_f32_16x16x32_bf16 v[16:19], v[142:145], v[220:223], v[16:19]
	s_setprio 0
	s_setprio 1
	v_mfma_f32_16x16x32_bf16 v[56:59], v[162:165], v[186:189], v[56:59]
	v_mfma_f32_16x16x32_bf16 v[56:59], v[166:169], v[190:193], v[56:59]
	v_mfma_f32_16x16x32_bf16 v[52:55], v[182:185], v[190:193], v[52:55]
	v_mfma_f32_16x16x32_bf16 v[52:55], v[178:181], v[186:189], v[52:55]
	v_mfma_f32_16x16x32_bf16 v[36:39], v[178:181], v[194:197], v[36:39]
	v_mfma_f32_16x16x32_bf16 v[36:39], v[182:185], v[208:211], v[36:39]
	v_mfma_f32_16x16x32_bf16 v[40:43], v[166:169], v[208:211], v[40:43]
	v_mfma_f32_16x16x32_bf16 v[40:43], v[162:165], v[194:197], v[40:43]
	v_mfma_f32_16x16x32_bf16 v[24:27], v[162:165], v[212:215], v[24:27]
	v_mfma_f32_16x16x32_bf16 v[24:27], v[166:169], v[216:219], v[24:27]
	v_mfma_f32_16x16x32_bf16 v[20:23], v[182:185], v[216:219], v[20:23]
	v_mfma_f32_16x16x32_bf16 v[20:23], v[178:181], v[212:215], v[20:23]
	v_mfma_f32_16x16x32_bf16 v[4:7], v[178:181], v[220:223], v[4:7]
	v_mfma_f32_16x16x32_bf16 v[4:7], v[182:185], v[224:227], v[4:7]
	v_mfma_f32_16x16x32_bf16 v[8:11], v[166:169], v[224:227], v[8:11]
	v_mfma_f32_16x16x32_bf16 v[8:11], v[162:165], v[220:223], v[8:11]
	s_setprio 0
	s_barrier
	s_add_i32 s47, 0, 0x18000
	s_add_i32 s49, 0, 0x1c000
	v_add_u32_e32 v158, s47, v151
	v_add_u32_e32 v182, s49, v151
	ds_read_b128 v[142:145], v158
	ds_read_b128 v[146:149], v158 offset:1024
	ds_read_b128 v[154:157], v158 offset:2048
	ds_read_b128 v[158:161], v158 offset:3072
	ds_read_b128 v[162:165], v182
	ds_read_b128 v[166:169], v182 offset:1024
	ds_read_b128 v[178:181], v182 offset:2048
	ds_read_b128 v[182:185], v182 offset:3072
	s_add_u32 s26, s26, 0x80000
	s_addc_u32 s27, s27, 0
	s_mov_b32 m0, s59
	v_lshl_add_u64 v[236:237], s[26:27], 0, v[136:137]
	ds_read_b128 v[186:189], v153 offset:32768
	ds_read_b128 v[190:193], v153 offset:33792
	ds_read_b128 v[194:197], v153 offset:34816
	ds_read_b128 v[208:211], v153 offset:35840
	ds_read_b128 v[212:215], v153 offset:36864
	ds_read_b128 v[216:219], v153 offset:37888
	ds_read_b128 v[220:223], v153 offset:38912
	ds_read_b128 v[224:227], v153 offset:39936
	global_load_lds_dwordx4 v[236:237], off
	v_lshl_add_u64 v[236:237], s[26:27], 0, v[134:135]
	s_mov_b32 m0, s60
	s_nop 0
	global_load_lds_dwordx4 v[236:237], off
	s_waitcnt vmcnt(8)
	s_waitcnt lgkmcnt(0)
	s_barrier
	s_setprio 1
	s_waitcnt lgkmcnt(0)
	v_mfma_f32_16x16x32_bf16 v[128:131], v[142:145], v[186:189], v[128:131]
	v_mfma_f32_16x16x32_bf16 v[128:131], v[146:149], v[190:193], v[128:131]
	v_mfma_f32_16x16x32_bf16 v[124:127], v[158:161], v[190:193], v[124:127]
	v_mfma_f32_16x16x32_bf16 v[124:127], v[154:157], v[186:189], v[124:127]
	v_mfma_f32_16x16x32_bf16 v[108:111], v[154:157], v[194:197], v[108:111]
	v_mfma_f32_16x16x32_bf16 v[108:111], v[158:161], v[208:211], v[108:111]
	v_mfma_f32_16x16x32_bf16 v[112:115], v[146:149], v[208:211], v[112:115]
	v_mfma_f32_16x16x32_bf16 v[112:115], v[142:145], v[194:197], v[112:115]
	v_mfma_f32_16x16x32_bf16 v[96:99], v[142:145], v[212:215], v[96:99]
	v_mfma_f32_16x16x32_bf16 v[96:99], v[146:149], v[216:219], v[96:99]
	v_mfma_f32_16x16x32_bf16 v[92:95], v[158:161], v[216:219], v[92:95]
	v_mfma_f32_16x16x32_bf16 v[92:95], v[154:157], v[212:215], v[92:95]
	v_mfma_f32_16x16x32_bf16 v[76:79], v[154:157], v[220:223], v[76:79]
	v_mfma_f32_16x16x32_bf16 v[76:79], v[158:161], v[224:227], v[76:79]
	v_mfma_f32_16x16x32_bf16 v[80:83], v[146:149], v[224:227], v[80:83]
	v_mfma_f32_16x16x32_bf16 v[80:83], v[142:145], v[220:223], v[80:83]
	s_setprio 0
	s_setprio 1
	v_mfma_f32_16x16x32_bf16 v[120:123], v[162:165], v[186:189], v[120:123]
	v_mfma_f32_16x16x32_bf16 v[120:123], v[166:169], v[190:193], v[120:123]
	v_mfma_f32_16x16x32_bf16 v[116:119], v[182:185], v[190:193], v[116:119]
	v_mfma_f32_16x16x32_bf16 v[116:119], v[178:181], v[186:189], v[116:119]
	v_mfma_f32_16x16x32_bf16 v[100:103], v[178:181], v[194:197], v[100:103]
	v_mfma_f32_16x16x32_bf16 v[100:103], v[182:185], v[208:211], v[100:103]
	v_mfma_f32_16x16x32_bf16 v[104:107], v[166:169], v[208:211], v[104:107]
	v_mfma_f32_16x16x32_bf16 v[104:107], v[162:165], v[194:197], v[104:107]
	v_mfma_f32_16x16x32_bf16 v[88:91], v[162:165], v[212:215], v[88:91]
	v_mfma_f32_16x16x32_bf16 v[88:91], v[166:169], v[216:219], v[88:91]
	v_mfma_f32_16x16x32_bf16 v[84:87], v[182:185], v[216:219], v[84:87]
	v_mfma_f32_16x16x32_bf16 v[84:87], v[178:181], v[212:215], v[84:87]
	v_mfma_f32_16x16x32_bf16 v[68:71], v[178:181], v[220:223], v[68:71]
	v_mfma_f32_16x16x32_bf16 v[68:71], v[182:185], v[224:227], v[68:71]
	v_mfma_f32_16x16x32_bf16 v[72:75], v[166:169], v[224:227], v[72:75]
	v_mfma_f32_16x16x32_bf16 v[72:75], v[162:165], v[220:223], v[72:75]
	s_setprio 0
	s_barrier
	s_add_i32 s26, s47, s55
	v_lshl_add_u64 v[228:229], v[228:229], 0, s[18:19]
	s_mov_b32 m0, s26
	ds_read_b128 v[186:189], v153 offset:49152
	ds_read_b128 v[190:193], v153 offset:50176
	ds_read_b128 v[194:197], v153 offset:51200
	ds_read_b128 v[208:211], v153 offset:52224
	ds_read_b128 v[212:215], v153 offset:53248
	ds_read_b128 v[216:219], v153 offset:54272
	ds_read_b128 v[220:223], v153 offset:55296
	ds_read_b128 v[224:227], v153 offset:56320
	global_load_lds_dwordx4 v[228:229], off
	s_add_i32 m0, s26, 0x2000
	s_add_u32 s12, s12, 0x80080
	v_lshl_add_u64 v[228:229], v[230:231], 0, s[18:19]
	s_addc_u32 s13, s13, 0
	s_add_i32 s26, s49, s55
	global_load_lds_dwordx4 v[228:229], off
	v_lshl_add_u64 v[228:229], s[12:13], 0, v[2:3]
	s_mov_b32 m0, s26
	s_nop 0
	global_load_lds_dwordx4 v[228:229], off
	v_lshl_add_u64 v[228:229], s[12:13], 0, v[132:133]
	s_add_i32 m0, s26, 0x2000
	s_nop 0
	global_load_lds_dwordx4 v[228:229], off
	v_lshl_add_u64 v[228:229], v[232:233], 0, s[18:19]
	s_mov_b32 m0, s14
	s_nop 0
	global_load_lds_dwordx4 v[228:229], off
	v_lshl_add_u64 v[228:229], v[234:235], 0, s[18:19]
	s_mov_b32 m0, s61
	s_nop 0
	global_load_lds_dwordx4 v[228:229], off
	s_waitcnt vmcnt(8)
	s_waitcnt lgkmcnt(0)
	s_barrier
	s_setprio 1
	s_waitcnt lgkmcnt(0)
	v_mfma_f32_16x16x32_bf16 v[64:67], v[142:145], v[186:189], v[64:67]
	v_mfma_f32_16x16x32_bf16 v[64:67], v[146:149], v[190:193], v[64:67]
	v_mfma_f32_16x16x32_bf16 v[60:63], v[158:161], v[190:193], v[60:63]
	v_mfma_f32_16x16x32_bf16 v[60:63], v[154:157], v[186:189], v[60:63]
	v_mfma_f32_16x16x32_bf16 v[44:47], v[154:157], v[194:197], v[44:47]
	v_mfma_f32_16x16x32_bf16 v[44:47], v[158:161], v[208:211], v[44:47]
	v_mfma_f32_16x16x32_bf16 v[48:51], v[146:149], v[208:211], v[48:51]
	v_mfma_f32_16x16x32_bf16 v[48:51], v[142:145], v[194:197], v[48:51]
	v_mfma_f32_16x16x32_bf16 v[32:35], v[142:145], v[212:215], v[32:35]
	v_mfma_f32_16x16x32_bf16 v[32:35], v[146:149], v[216:219], v[32:35]
	v_mfma_f32_16x16x32_bf16 v[28:31], v[158:161], v[216:219], v[28:31]
	v_mfma_f32_16x16x32_bf16 v[28:31], v[154:157], v[212:215], v[28:31]
	v_mfma_f32_16x16x32_bf16 v[12:15], v[154:157], v[220:223], v[12:15]
	v_mfma_f32_16x16x32_bf16 v[12:15], v[158:161], v[224:227], v[12:15]
	v_mfma_f32_16x16x32_bf16 v[16:19], v[146:149], v[224:227], v[16:19]
	v_mfma_f32_16x16x32_bf16 v[16:19], v[142:145], v[220:223], v[16:19]
	s_setprio 0
	s_setprio 1
	v_mfma_f32_16x16x32_bf16 v[56:59], v[162:165], v[186:189], v[56:59]
	v_mfma_f32_16x16x32_bf16 v[56:59], v[166:169], v[190:193], v[56:59]
	v_mfma_f32_16x16x32_bf16 v[52:55], v[182:185], v[190:193], v[52:55]
	v_mfma_f32_16x16x32_bf16 v[52:55], v[178:181], v[186:189], v[52:55]
	v_mfma_f32_16x16x32_bf16 v[36:39], v[178:181], v[194:197], v[36:39]
	v_mfma_f32_16x16x32_bf16 v[36:39], v[182:185], v[208:211], v[36:39]
	v_mfma_f32_16x16x32_bf16 v[40:43], v[166:169], v[208:211], v[40:43]
	v_mfma_f32_16x16x32_bf16 v[40:43], v[162:165], v[194:197], v[40:43]
	v_mfma_f32_16x16x32_bf16 v[24:27], v[162:165], v[212:215], v[24:27]
	v_mfma_f32_16x16x32_bf16 v[24:27], v[166:169], v[216:219], v[24:27]
	v_mfma_f32_16x16x32_bf16 v[20:23], v[182:185], v[216:219], v[20:23]
	v_mfma_f32_16x16x32_bf16 v[20:23], v[178:181], v[212:215], v[20:23]
	v_mfma_f32_16x16x32_bf16 v[4:7], v[178:181], v[220:223], v[4:7]
	v_mfma_f32_16x16x32_bf16 v[4:7], v[182:185], v[224:227], v[4:7]
	v_mfma_f32_16x16x32_bf16 v[8:11], v[166:169], v[224:227], v[8:11]
	v_mfma_f32_16x16x32_bf16 v[8:11], v[162:165], v[220:223], v[8:11]
	s_setprio 0
	s_barrier
	s_add_i32 s33, s33, 2
	s_add_u32 s8, s8, 0x100
	s_addc_u32 s9, s9, 0
	s_add_u32 s21, s21, 0x100
	s_addc_u32 s22, s22, 0
	s_cmp_gt_u32 s33, 29
	s_cbranch_scc0 .LBB0_901
	s_and_b64 vcc, exec, s[44:45]
	s_cbranch_vccz .LBB0_904
	s_barrier

.LBB0_1074:
	s_add_u32 s42, s40, 0xffe00080
	s_addc_u32 s43, s41, -1
	s_add_i32 s59, 0, 0x10000
	s_cmpk_eq_i32 s58, 0x7c
	s_cselect_b32 s45, s27, s43
	s_cselect_b32 s44, s54, s42
	v_add_u32_e32 v142, s59, v144
	s_cselect_b32 s43, s13, s57
	s_cselect_b32 s42, s55, s56
	s_add_i32 s62, 0, 0x14000
	ds_read_b128 v[148:151], v142
	ds_read_b128 v[152:155], v142 offset:1024
	ds_read_b128 v[156:159], v142 offset:2048
	ds_read_b128 v[160:163], v142 offset:3072
	v_add_u32_e32 v142, s62, v144
	ds_read_b128 v[164:167], v142
	ds_read_b128 v[178:181], v142 offset:1024
	ds_read_b128 v[182:185], v142 offset:2048
	ds_read_b128 v[186:189], v142 offset:3072
	v_lshl_add_u64 v[142:143], s[40:41], 0, v[138:139]
	s_add_i32 m0, s46, 0xc000
	ds_read_b128 v[190:193], v146
	ds_read_b128 v[194:197], v146 offset:1024
	ds_read_b128 v[208:211], v146 offset:2048
	ds_read_b128 v[212:215], v146 offset:3072
	ds_read_b128 v[216:219], v146 offset:4096
	ds_read_b128 v[220:223], v146 offset:5120
	ds_read_b128 v[224:227], v146 offset:6144
	ds_read_b128 v[228:231], v146 offset:7168
	global_load_lds_dwordx4 v[142:143], off
	v_lshl_add_u64 v[142:143], s[40:41], 0, v[140:141]
	s_add_i32 m0, s46, 0xe000
	s_nop 0
	global_load_lds_dwordx4 v[142:143], off
	s_waitcnt vmcnt(8)
	s_waitcnt lgkmcnt(0)
	s_barrier
	s_setprio 1
	s_waitcnt lgkmcnt(0)
	v_mfma_f32_16x16x32_bf16 v[128:131], v[148:151], v[190:193], v[128:131]
	v_mfma_f32_16x16x32_bf16 v[128:131], v[152:155], v[194:197], v[128:131]
	v_mfma_f32_16x16x32_bf16 v[124:127], v[160:163], v[194:197], v[124:127]
	v_mfma_f32_16x16x32_bf16 v[124:127], v[156:159], v[190:193], v[124:127]
	v_mfma_f32_16x16x32_bf16 v[112:115], v[156:159], v[208:211], v[112:115]
	v_mfma_f32_16x16x32_bf16 v[112:115], v[160:163], v[212:215], v[112:115]
	v_mfma_f32_16x16x32_bf16 v[120:123], v[152:155], v[212:215], v[120:123]
	v_mfma_f32_16x16x32_bf16 v[120:123], v[148:151], v[208:211], v[120:123]
	v_mfma_f32_16x16x32_bf16 v[104:107], v[148:151], v[216:219], v[104:107]
	v_mfma_f32_16x16x32_bf16 v[104:107], v[152:155], v[220:223], v[104:107]
	v_mfma_f32_16x16x32_bf16 v[96:99], v[160:163], v[220:223], v[96:99]
	v_mfma_f32_16x16x32_bf16 v[96:99], v[156:159], v[216:219], v[96:99]
	v_mfma_f32_16x16x32_bf16 v[80:83], v[156:159], v[224:227], v[80:83]
	v_mfma_f32_16x16x32_bf16 v[80:83], v[160:163], v[228:231], v[80:83]
	v_mfma_f32_16x16x32_bf16 v[88:91], v[152:155], v[228:231], v[88:91]
	v_mfma_f32_16x16x32_bf16 v[88:91], v[148:151], v[224:227], v[88:91]
	s_setprio 0
	s_setprio 1
	v_mfma_f32_16x16x32_bf16 v[116:119], v[164:167], v[190:193], v[116:119]
	v_mfma_f32_16x16x32_bf16 v[116:119], v[178:181], v[194:197], v[116:119]
	v_mfma_f32_16x16x32_bf16 v[108:111], v[186:189], v[194:197], v[108:111]
	v_mfma_f32_16x16x32_bf16 v[108:111], v[182:185], v[190:193], v[108:111]
	v_mfma_f32_16x16x32_bf16 v[92:95], v[182:185], v[208:211], v[92:95]
	v_mfma_f32_16x16x32_bf16 v[92:95], v[186:189], v[212:215], v[92:95]
	v_mfma_f32_16x16x32_bf16 v[100:103], v[178:181], v[212:215], v[100:103]
	v_mfma_f32_16x16x32_bf16 v[100:103], v[164:167], v[208:211], v[100:103]
	v_mfma_f32_16x16x32_bf16 v[84:87], v[164:167], v[216:219], v[84:87]
	v_mfma_f32_16x16x32_bf16 v[84:87], v[178:181], v[220:223], v[84:87]
	v_mfma_f32_16x16x32_bf16 v[76:79], v[186:189], v[220:223], v[76:79]
	v_mfma_f32_16x16x32_bf16 v[76:79], v[182:185], v[216:219], v[76:79]
	v_mfma_f32_16x16x32_bf16 v[68:71], v[182:185], v[224:227], v[68:71]
	v_mfma_f32_16x16x32_bf16 v[68:71], v[186:189], v[228:231], v[68:71]
	v_mfma_f32_16x16x32_bf16 v[72:75], v[178:181], v[228:231], v[72:75]
	v_mfma_f32_16x16x32_bf16 v[72:75], v[164:167], v[224:227], v[72:75]
	s_setprio 0
	s_barrier
	s_add_i32 s59, s59, s33
	v_lshl_add_u64 v[142:143], s[42:43], 0, v[2:3]
	s_mov_b32 m0, s59
	ds_read_b128 v[190:193], v146 offset:16384
	ds_read_b128 v[194:197], v146 offset:17408
	ds_read_b128 v[208:211], v146 offset:18432
	ds_read_b128 v[212:215], v146 offset:19456
	ds_read_b128 v[216:219], v146 offset:20480
	ds_read_b128 v[220:223], v146 offset:21504
	ds_read_b128 v[224:227], v146 offset:22528
	ds_read_b128 v[228:231], v146 offset:23552
	global_load_lds_dwordx4 v[142:143], off
	s_add_i32 m0, s59, 0x2000
	s_add_u32 s60, s42, 0x200000
	v_lshl_add_u64 v[168:169], s[42:43], 0, v[136:137]
	s_addc_u32 s61, s43, 0
	s_add_i32 s59, s62, s33
	global_load_lds_dwordx4 v[168:169], off
	v_lshl_add_u64 v[232:233], s[60:61], 0, v[2:3]
	s_mov_b32 m0, s59
	v_lshl_add_u64 v[234:235], s[44:45], 0, v[134:135]
	global_load_lds_dwordx4 v[232:233], off
	v_lshl_add_u64 v[232:233], s[60:61], 0, v[136:137]
	s_add_i32 m0, s59, 0x2000
	s_nop 0
	global_load_lds_dwordx4 v[232:233], off
	v_lshl_add_u64 v[232:233], s[44:45], 0, v[132:133]
	s_mov_b32 m0, s46
	s_nop 0
	global_load_lds_dwordx4 v[232:233], off
	s_mov_b32 m0, s47
	s_nop 0
	global_load_lds_dwordx4 v[234:235], off
	s_waitcnt vmcnt(8)
	s_waitcnt lgkmcnt(0)
	s_barrier
	s_setprio 1
	s_waitcnt lgkmcnt(0)
	v_mfma_f32_16x16x32_bf16 v[64:67], v[148:151], v[190:193], v[64:67]
	v_mfma_f32_16x16x32_bf16 v[64:67], v[152:155], v[194:197], v[64:67]
	v_mfma_f32_16x16x32_bf16 v[60:63], v[160:163], v[194:197], v[60:63]
	v_mfma_f32_16x16x32_bf16 v[60:63], v[156:159], v[190:193], v[60:63]
	v_mfma_f32_16x16x32_bf16 v[48:51], v[156:159], v[208:211], v[48:51]
	v_mfma_f32_16x16x32_bf16 v[48:51], v[160:163], v[212:215], v[48:51]
	v_mfma_f32_16x16x32_bf16 v[56:59], v[152:155], v[212:215], v[56:59]
	v_mfma_f32_16x16x32_bf16 v[56:59], v[148:151], v[208:211], v[56:59]
	v_mfma_f32_16x16x32_bf16 v[40:43], v[148:151], v[216:219], v[40:43]
	v_mfma_f32_16x16x32_bf16 v[40:43], v[152:155], v[220:223], v[40:43]
	v_mfma_f32_16x16x32_bf16 v[32:35], v[160:163], v[220:223], v[32:35]
	v_mfma_f32_16x16x32_bf16 v[32:35], v[156:159], v[216:219], v[32:35]
	v_mfma_f32_16x16x32_bf16 v[16:19], v[156:159], v[224:227], v[16:19]
	v_mfma_f32_16x16x32_bf16 v[16:19], v[160:163], v[228:231], v[16:19]
	v_mfma_f32_16x16x32_bf16 v[24:27], v[152:155], v[228:231], v[24:27]
	v_mfma_f32_16x16x32_bf16 v[24:27], v[148:151], v[224:227], v[24:27]
	s_setprio 0
	s_setprio 1
	v_mfma_f32_16x16x32_bf16 v[52:55], v[164:167], v[190:193], v[52:55]
	v_mfma_f32_16x16x32_bf16 v[52:55], v[178:181], v[194:197], v[52:55]
	v_mfma_f32_16x16x32_bf16 v[44:47], v[186:189], v[194:197], v[44:47]
	v_mfma_f32_16x16x32_bf16 v[44:47], v[182:185], v[190:193], v[44:47]
	v_mfma_f32_16x16x32_bf16 v[28:31], v[182:185], v[208:211], v[28:31]
	v_mfma_f32_16x16x32_bf16 v[28:31], v[186:189], v[212:215], v[28:31]
	v_mfma_f32_16x16x32_bf16 v[36:39], v[178:181], v[212:215], v[36:39]
	v_mfma_f32_16x16x32_bf16 v[36:39], v[164:167], v[208:211], v[36:39]
	v_mfma_f32_16x16x32_bf16 v[20:23], v[164:167], v[216:219], v[20:23]
	v_mfma_f32_16x16x32_bf16 v[20:23], v[178:181], v[220:223], v[20:23]
	v_mfma_f32_16x16x32_bf16 v[12:15], v[186:189], v[220:223], v[12:15]
	v_mfma_f32_16x16x32_bf16 v[12:15], v[182:185], v[216:219], v[12:15]
	v_mfma_f32_16x16x32_bf16 v[4:7], v[182:185], v[224:227], v[4:7]
	v_mfma_f32_16x16x32_bf16 v[4:7], v[186:189], v[228:231], v[4:7]
	v_mfma_f32_16x16x32_bf16 v[8:11], v[178:181], v[228:231], v[8:11]
	v_mfma_f32_16x16x32_bf16 v[8:11], v[164:167], v[224:227], v[8:11]
	s_setprio 0
	s_barrier
	s_add_i32 s59, 0, 0x18000
	v_add_u32_e32 v147, s59, v144
	s_add_i32 s60, 0, 0x1c000
	ds_read_b128 v[148:151], v147
	ds_read_b128 v[152:155], v147 offset:1024
	ds_read_b128 v[156:159], v147 offset:2048
	ds_read_b128 v[160:163], v147 offset:3072
	v_add_u32_e32 v147, s60, v144
	ds_read_b128 v[164:167], v147
	ds_read_b128 v[178:181], v147 offset:1024
	ds_read_b128 v[182:185], v147 offset:2048
	ds_read_b128 v[186:189], v147 offset:3072
	s_add_u32 s44, s44, 0x200000
	s_addc_u32 s45, s45, 0
	s_mov_b32 m0, s48
	v_lshl_add_u64 v[236:237], s[44:45], 0, v[132:133]
	ds_read_b128 v[190:193], v146 offset:32768
	ds_read_b128 v[194:197], v146 offset:33792
	ds_read_b128 v[208:211], v146 offset:34816
	ds_read_b128 v[212:215], v146 offset:35840
	ds_read_b128 v[216:219], v146 offset:36864
	ds_read_b128 v[220:223], v146 offset:37888
	ds_read_b128 v[224:227], v146 offset:38912
	ds_read_b128 v[228:231], v146 offset:39936
	global_load_lds_dwordx4 v[236:237], off
	v_lshl_add_u64 v[236:237], s[44:45], 0, v[134:135]
	s_mov_b32 m0, s49
	s_nop 0
	global_load_lds_dwordx4 v[236:237], off
	s_waitcnt vmcnt(8)
	s_waitcnt lgkmcnt(0)
	s_barrier
	s_setprio 1
	s_waitcnt lgkmcnt(0)
	v_mfma_f32_16x16x32_bf16 v[128:131], v[148:151], v[190:193], v[128:131]
	v_mfma_f32_16x16x32_bf16 v[128:131], v[152:155], v[194:197], v[128:131]
	v_mfma_f32_16x16x32_bf16 v[124:127], v[160:163], v[194:197], v[124:127]
	v_mfma_f32_16x16x32_bf16 v[124:127], v[156:159], v[190:193], v[124:127]
	v_mfma_f32_16x16x32_bf16 v[112:115], v[156:159], v[208:211], v[112:115]
	v_mfma_f32_16x16x32_bf16 v[112:115], v[160:163], v[212:215], v[112:115]
	v_mfma_f32_16x16x32_bf16 v[120:123], v[152:155], v[212:215], v[120:123]
	v_mfma_f32_16x16x32_bf16 v[120:123], v[148:151], v[208:211], v[120:123]
	v_mfma_f32_16x16x32_bf16 v[104:107], v[148:151], v[216:219], v[104:107]
	v_mfma_f32_16x16x32_bf16 v[104:107], v[152:155], v[220:223], v[104:107]
	v_mfma_f32_16x16x32_bf16 v[96:99], v[160:163], v[220:223], v[96:99]
	v_mfma_f32_16x16x32_bf16 v[96:99], v[156:159], v[216:219], v[96:99]
	v_mfma_f32_16x16x32_bf16 v[80:83], v[156:159], v[224:227], v[80:83]
	v_mfma_f32_16x16x32_bf16 v[80:83], v[160:163], v[228:231], v[80:83]
	v_mfma_f32_16x16x32_bf16 v[88:91], v[152:155], v[228:231], v[88:91]
	v_mfma_f32_16x16x32_bf16 v[88:91], v[148:151], v[224:227], v[88:91]
	s_setprio 0
	s_setprio 1
	v_mfma_f32_16x16x32_bf16 v[116:119], v[164:167], v[190:193], v[116:119]
	v_mfma_f32_16x16x32_bf16 v[116:119], v[178:181], v[194:197], v[116:119]
	v_mfma_f32_16x16x32_bf16 v[108:111], v[186:189], v[194:197], v[108:111]
	v_mfma_f32_16x16x32_bf16 v[108:111], v[182:185], v[190:193], v[108:111]
	v_mfma_f32_16x16x32_bf16 v[92:95], v[182:185], v[208:211], v[92:95]
	v_mfma_f32_16x16x32_bf16 v[92:95], v[186:189], v[212:215], v[92:95]
	v_mfma_f32_16x16x32_bf16 v[100:103], v[178:181], v[212:215], v[100:103]
	v_mfma_f32_16x16x32_bf16 v[100:103], v[164:167], v[208:211], v[100:103]
	v_mfma_f32_16x16x32_bf16 v[84:87], v[164:167], v[216:219], v[84:87]
	v_mfma_f32_16x16x32_bf16 v[84:87], v[178:181], v[220:223], v[84:87]
	v_mfma_f32_16x16x32_bf16 v[76:79], v[186:189], v[220:223], v[76:79]
	v_mfma_f32_16x16x32_bf16 v[76:79], v[182:185], v[216:219], v[76:79]
	v_mfma_f32_16x16x32_bf16 v[68:71], v[182:185], v[224:227], v[68:71]
	v_mfma_f32_16x16x32_bf16 v[68:71], v[186:189], v[228:231], v[68:71]
	v_mfma_f32_16x16x32_bf16 v[72:75], v[178:181], v[228:231], v[72:75]
	v_mfma_f32_16x16x32_bf16 v[72:75], v[164:167], v[224:227], v[72:75]
	s_setprio 0
	s_barrier
	s_add_i32 s44, s59, s33
	v_lshl_add_u64 v[142:143], v[142:143], 0, s[18:19]
	s_mov_b32 m0, s44
	ds_read_b128 v[190:193], v146 offset:49152
	ds_read_b128 v[194:197], v146 offset:50176
	ds_read_b128 v[208:211], v146 offset:51200
	ds_read_b128 v[212:215], v146 offset:52224
	ds_read_b128 v[216:219], v146 offset:53248
	ds_read_b128 v[220:223], v146 offset:54272
	ds_read_b128 v[224:227], v146 offset:55296
	ds_read_b128 v[228:231], v146 offset:56320
	global_load_lds_dwordx4 v[142:143], off
	s_add_i32 m0, s44, 0x2000
	s_add_u32 s42, s42, 0x200080
	v_lshl_add_u64 v[142:143], v[168:169], 0, s[18:19]
	s_addc_u32 s43, s43, 0
	s_add_i32 s44, s60, s33
	global_load_lds_dwordx4 v[142:143], off
	v_lshl_add_u64 v[142:143], s[42:43], 0, v[2:3]
	s_mov_b32 m0, s44
	s_nop 0
	global_load_lds_dwordx4 v[142:143], off
	v_lshl_add_u64 v[142:143], s[42:43], 0, v[136:137]
	s_add_i32 m0, s44, 0x2000
	s_nop 0
	global_load_lds_dwordx4 v[142:143], off
	v_lshl_add_u64 v[142:143], v[232:233], 0, s[18:19]
	s_mov_b32 m0, s50
	s_nop 0
	global_load_lds_dwordx4 v[142:143], off
	v_lshl_add_u64 v[142:143], v[234:235], 0, s[18:19]
	s_mov_b32 m0, s51
	s_nop 0
	global_load_lds_dwordx4 v[142:143], off
	s_waitcnt vmcnt(8)
	s_waitcnt lgkmcnt(0)
	s_barrier
	s_setprio 1
	s_waitcnt lgkmcnt(0)
	v_mfma_f32_16x16x32_bf16 v[64:67], v[148:151], v[190:193], v[64:67]
	v_mfma_f32_16x16x32_bf16 v[64:67], v[152:155], v[194:197], v[64:67]
	v_mfma_f32_16x16x32_bf16 v[60:63], v[160:163], v[194:197], v[60:63]
	v_mfma_f32_16x16x32_bf16 v[60:63], v[156:159], v[190:193], v[60:63]
	v_mfma_f32_16x16x32_bf16 v[48:51], v[156:159], v[208:211], v[48:51]
	v_mfma_f32_16x16x32_bf16 v[48:51], v[160:163], v[212:215], v[48:51]
	v_mfma_f32_16x16x32_bf16 v[56:59], v[152:155], v[212:215], v[56:59]
	v_mfma_f32_16x16x32_bf16 v[56:59], v[148:151], v[208:211], v[56:59]
	v_mfma_f32_16x16x32_bf16 v[40:43], v[148:151], v[216:219], v[40:43]
	v_mfma_f32_16x16x32_bf16 v[40:43], v[152:155], v[220:223], v[40:43]
	v_mfma_f32_16x16x32_bf16 v[32:35], v[160:163], v[220:223], v[32:35]
	v_mfma_f32_16x16x32_bf16 v[32:35], v[156:159], v[216:219], v[32:35]
	v_mfma_f32_16x16x32_bf16 v[16:19], v[156:159], v[224:227], v[16:19]
	v_mfma_f32_16x16x32_bf16 v[16:19], v[160:163], v[228:231], v[16:19]
	v_mfma_f32_16x16x32_bf16 v[24:27], v[152:155], v[228:231], v[24:27]
	v_mfma_f32_16x16x32_bf16 v[24:27], v[148:151], v[224:227], v[24:27]
	s_setprio 0
	s_setprio 1
	v_mfma_f32_16x16x32_bf16 v[52:55], v[164:167], v[190:193], v[52:55]
	v_mfma_f32_16x16x32_bf16 v[52:55], v[178:181], v[194:197], v[52:55]
	v_mfma_f32_16x16x32_bf16 v[44:47], v[186:189], v[194:197], v[44:47]
	v_mfma_f32_16x16x32_bf16 v[44:47], v[182:185], v[190:193], v[44:47]
	v_mfma_f32_16x16x32_bf16 v[28:31], v[182:185], v[208:211], v[28:31]
	v_mfma_f32_16x16x32_bf16 v[28:31], v[186:189], v[212:215], v[28:31]
	v_mfma_f32_16x16x32_bf16 v[36:39], v[178:181], v[212:215], v[36:39]
	v_mfma_f32_16x16x32_bf16 v[36:39], v[164:167], v[208:211], v[36:39]
	v_mfma_f32_16x16x32_bf16 v[20:23], v[164:167], v[216:219], v[20:23]
	v_mfma_f32_16x16x32_bf16 v[20:23], v[178:181], v[220:223], v[20:23]
	v_mfma_f32_16x16x32_bf16 v[12:15], v[186:189], v[220:223], v[12:15]
	v_mfma_f32_16x16x32_bf16 v[12:15], v[182:185], v[216:219], v[12:15]
	v_mfma_f32_16x16x32_bf16 v[4:7], v[182:185], v[224:227], v[4:7]
	v_mfma_f32_16x16x32_bf16 v[4:7], v[186:189], v[228:231], v[4:7]
	v_mfma_f32_16x16x32_bf16 v[8:11], v[178:181], v[228:231], v[8:11]
	v_mfma_f32_16x16x32_bf16 v[8:11], v[164:167], v[224:227], v[8:11]
	s_setprio 0
	s_barrier
	s_add_i32 s58, s58, 2
	s_add_u32 s40, s40, 0x100
	s_addc_u32 s41, s41, 0
	s_add_u32 s56, s56, 0x100
	s_addc_u32 s57, s57, 0
	s_cmpk_gt_u32 s58, 0x7d
	s_cbranch_scc0 .LBB0_1074
	s_and_b64 vcc, exec, s[8:9]
	s_cbranch_vccz .LBB0_1077
	s_barrier

.LBB0_1088:
	s_add_u32 s38, s36, 0xffe00080
	s_addc_u32 s39, s37, -1
	s_add_i32 s55, 0, 0x10000
	s_cmp_eq_u32 s54, 12
	s_cselect_b32 s41, s3, s39
	s_cselect_b32 s40, s49, s38
	v_add_u32_e32 v2, s55, v140
	s_cselect_b32 s39, s50, s53
	s_cselect_b32 s38, s51, s52
	s_add_i32 s58, 0, 0x14000
	ds_read_b128 v[144:147], v2
	ds_read_b128 v[148:151], v2 offset:1024
	ds_read_b128 v[152:155], v2 offset:2048
	ds_read_b128 v[156:159], v2 offset:3072
	v_add_u32_e32 v2, s58, v140
	ds_read_b128 v[160:163], v2
	ds_read_b128 v[164:167], v2 offset:1024
	ds_read_b128 v[178:181], v2 offset:2048
	ds_read_b128 v[182:185], v2 offset:3072
	v_lshl_add_u64 v[168:169], s[36:37], 0, v[136:137]
	s_add_i32 m0, s42, 0xc000
	ds_read_b128 v[186:189], v142
	ds_read_b128 v[190:193], v142 offset:1024
	ds_read_b128 v[194:197], v142 offset:2048
	ds_read_b128 v[208:211], v142 offset:3072
	ds_read_b128 v[212:215], v142 offset:4096
	ds_read_b128 v[216:219], v142 offset:5120
	ds_read_b128 v[220:223], v142 offset:6144
	ds_read_b128 v[224:227], v142 offset:7168
	global_load_lds_dwordx4 v[168:169], off
	v_lshl_add_u64 v[168:169], s[36:37], 0, v[138:139]
	s_add_i32 m0, s42, 0xe000
	s_nop 0
	global_load_lds_dwordx4 v[168:169], off
	s_waitcnt vmcnt(8)
	s_waitcnt lgkmcnt(0)
	s_barrier
	s_setprio 1
	s_waitcnt lgkmcnt(0)
	v_mfma_f32_16x16x32_bf16 v[128:131], v[144:147], v[186:189], v[128:131]
	v_mfma_f32_16x16x32_bf16 v[128:131], v[148:151], v[190:193], v[128:131]
	v_mfma_f32_16x16x32_bf16 v[124:127], v[156:159], v[190:193], v[124:127]
	v_mfma_f32_16x16x32_bf16 v[124:127], v[152:155], v[186:189], v[124:127]
	v_mfma_f32_16x16x32_bf16 v[116:119], v[152:155], v[194:197], v[116:119]
	v_mfma_f32_16x16x32_bf16 v[116:119], v[156:159], v[208:211], v[116:119]
	v_mfma_f32_16x16x32_bf16 v[120:123], v[148:151], v[208:211], v[120:123]
	v_mfma_f32_16x16x32_bf16 v[120:123], v[144:147], v[194:197], v[120:123]
	v_mfma_f32_16x16x32_bf16 v[108:111], v[144:147], v[212:215], v[108:111]
	v_mfma_f32_16x16x32_bf16 v[108:111], v[148:151], v[216:219], v[108:111]
	v_mfma_f32_16x16x32_bf16 v[100:103], v[156:159], v[216:219], v[100:103]
	v_mfma_f32_16x16x32_bf16 v[100:103], v[152:155], v[212:215], v[100:103]
	v_mfma_f32_16x16x32_bf16 v[84:87], v[152:155], v[220:223], v[84:87]
	v_mfma_f32_16x16x32_bf16 v[84:87], v[156:159], v[224:227], v[84:87]
	v_mfma_f32_16x16x32_bf16 v[92:95], v[148:151], v[224:227], v[92:95]
	v_mfma_f32_16x16x32_bf16 v[92:95], v[144:147], v[220:223], v[92:95]
	s_setprio 0
	s_setprio 1
	v_mfma_f32_16x16x32_bf16 v[112:115], v[160:163], v[186:189], v[112:115]
	v_mfma_f32_16x16x32_bf16 v[112:115], v[164:167], v[190:193], v[112:115]
	v_mfma_f32_16x16x32_bf16 v[104:107], v[182:185], v[190:193], v[104:107]
	v_mfma_f32_16x16x32_bf16 v[104:107], v[178:181], v[186:189], v[104:107]
	v_mfma_f32_16x16x32_bf16 v[88:91], v[178:181], v[194:197], v[88:91]
	v_mfma_f32_16x16x32_bf16 v[88:91], v[182:185], v[208:211], v[88:91]
	v_mfma_f32_16x16x32_bf16 v[96:99], v[164:167], v[208:211], v[96:99]
	v_mfma_f32_16x16x32_bf16 v[96:99], v[160:163], v[194:197], v[96:99]
	v_mfma_f32_16x16x32_bf16 v[80:83], v[160:163], v[212:215], v[80:83]
	v_mfma_f32_16x16x32_bf16 v[80:83], v[164:167], v[216:219], v[80:83]
	v_mfma_f32_16x16x32_bf16 v[76:79], v[182:185], v[216:219], v[76:79]
	v_mfma_f32_16x16x32_bf16 v[76:79], v[178:181], v[212:215], v[76:79]
	v_mfma_f32_16x16x32_bf16 v[68:71], v[178:181], v[220:223], v[68:71]
	v_mfma_f32_16x16x32_bf16 v[68:71], v[182:185], v[224:227], v[68:71]
	v_mfma_f32_16x16x32_bf16 v[72:75], v[164:167], v[224:227], v[72:75]
	v_mfma_f32_16x16x32_bf16 v[72:75], v[160:163], v[220:223], v[72:75]
	s_setprio 0
	s_barrier
	s_add_i32 s55, s55, s25
	v_lshl_add_u64 v[168:169], s[38:39], 0, v[134:135]
	s_mov_b32 m0, s55
	ds_read_b128 v[186:189], v142 offset:16384
	ds_read_b128 v[190:193], v142 offset:17408
	ds_read_b128 v[194:197], v142 offset:18432
	ds_read_b128 v[208:211], v142 offset:19456
	ds_read_b128 v[212:215], v142 offset:20480
	ds_read_b128 v[216:219], v142 offset:21504
	ds_read_b128 v[220:223], v142 offset:22528
	ds_read_b128 v[224:227], v142 offset:23552
	global_load_lds_dwordx4 v[168:169], off
	s_add_i32 m0, s55, 0x2000
	s_add_u32 s56, s38, 0x200000
	v_lshl_add_u64 v[228:229], s[38:39], 0, v[132:133]
	s_addc_u32 s57, s39, 0
	s_add_i32 s55, s58, s25
	global_load_lds_dwordx4 v[228:229], off
	v_lshl_add_u64 v[230:231], s[56:57], 0, v[134:135]
	s_mov_b32 m0, s55
	v_lshl_add_u64 v[232:233], s[40:41], 0, v[132:133]
	global_load_lds_dwordx4 v[230:231], off
	v_lshl_add_u64 v[230:231], s[56:57], 0, v[132:133]
	s_add_i32 m0, s55, 0x2000
	s_nop 0
	global_load_lds_dwordx4 v[230:231], off
	v_lshl_add_u64 v[230:231], s[40:41], 0, v[134:135]
	s_mov_b32 m0, s42
	s_nop 0
	global_load_lds_dwordx4 v[230:231], off
	s_mov_b32 m0, s43
	s_nop 0
	global_load_lds_dwordx4 v[232:233], off
	s_waitcnt vmcnt(8)
	s_waitcnt lgkmcnt(0)
	s_barrier
	s_setprio 1
	s_waitcnt lgkmcnt(0)
	v_mfma_f32_16x16x32_bf16 v[64:67], v[144:147], v[186:189], v[64:67]
	v_mfma_f32_16x16x32_bf16 v[64:67], v[148:151], v[190:193], v[64:67]
	v_mfma_f32_16x16x32_bf16 v[60:63], v[156:159], v[190:193], v[60:63]
	v_mfma_f32_16x16x32_bf16 v[60:63], v[152:155], v[186:189], v[60:63]
	v_mfma_f32_16x16x32_bf16 v[52:55], v[152:155], v[194:197], v[52:55]
	v_mfma_f32_16x16x32_bf16 v[52:55], v[156:159], v[208:211], v[52:55]
	v_mfma_f32_16x16x32_bf16 v[56:59], v[148:151], v[208:211], v[56:59]
	v_mfma_f32_16x16x32_bf16 v[56:59], v[144:147], v[194:197], v[56:59]
	v_mfma_f32_16x16x32_bf16 v[40:43], v[144:147], v[212:215], v[40:43]
	v_mfma_f32_16x16x32_bf16 v[40:43], v[148:151], v[216:219], v[40:43]
	v_mfma_f32_16x16x32_bf16 v[36:39], v[156:159], v[216:219], v[36:39]
	v_mfma_f32_16x16x32_bf16 v[36:39], v[152:155], v[212:215], v[36:39]
	v_mfma_f32_16x16x32_bf16 v[20:23], v[152:155], v[220:223], v[20:23]
	v_mfma_f32_16x16x32_bf16 v[20:23], v[156:159], v[224:227], v[20:23]
	v_mfma_f32_16x16x32_bf16 v[24:27], v[148:151], v[224:227], v[24:27]
	v_mfma_f32_16x16x32_bf16 v[24:27], v[144:147], v[220:223], v[24:27]
	s_setprio 0
	s_setprio 1
	v_mfma_f32_16x16x32_bf16 v[48:51], v[160:163], v[186:189], v[48:51]
	v_mfma_f32_16x16x32_bf16 v[48:51], v[164:167], v[190:193], v[48:51]
	v_mfma_f32_16x16x32_bf16 v[44:47], v[182:185], v[190:193], v[44:47]
	v_mfma_f32_16x16x32_bf16 v[44:47], v[178:181], v[186:189], v[44:47]
	v_mfma_f32_16x16x32_bf16 v[28:31], v[178:181], v[194:197], v[28:31]
	v_mfma_f32_16x16x32_bf16 v[28:31], v[182:185], v[208:211], v[28:31]
	v_mfma_f32_16x16x32_bf16 v[32:35], v[164:167], v[208:211], v[32:35]
	v_mfma_f32_16x16x32_bf16 v[32:35], v[160:163], v[194:197], v[32:35]
	v_mfma_f32_16x16x32_bf16 v[16:19], v[160:163], v[212:215], v[16:19]
	v_mfma_f32_16x16x32_bf16 v[16:19], v[164:167], v[216:219], v[16:19]
	v_mfma_f32_16x16x32_bf16 v[12:15], v[182:185], v[216:219], v[12:15]
	v_mfma_f32_16x16x32_bf16 v[12:15], v[178:181], v[212:215], v[12:15]
	v_mfma_f32_16x16x32_bf16 v[4:7], v[178:181], v[220:223], v[4:7]
	v_mfma_f32_16x16x32_bf16 v[4:7], v[182:185], v[224:227], v[4:7]
	v_mfma_f32_16x16x32_bf16 v[8:11], v[164:167], v[224:227], v[8:11]
	v_mfma_f32_16x16x32_bf16 v[8:11], v[160:163], v[220:223], v[8:11]
	s_setprio 0
	s_barrier
	s_add_i32 s55, 0, 0x18000
	v_add_u32_e32 v2, s55, v140
	s_add_i32 s56, 0, 0x1c000
	ds_read_b128 v[144:147], v2
	ds_read_b128 v[148:151], v2 offset:1024
	ds_read_b128 v[152:155], v2 offset:2048
	ds_read_b128 v[156:159], v2 offset:3072
	v_add_u32_e32 v2, s56, v140
	ds_read_b128 v[160:163], v2
	ds_read_b128 v[164:167], v2 offset:1024
	ds_read_b128 v[178:181], v2 offset:2048
	ds_read_b128 v[182:185], v2 offset:3072
	s_add_u32 s40, s40, 0x200000
	s_addc_u32 s41, s41, 0
	s_mov_b32 m0, s44
	v_lshl_add_u64 v[234:235], s[40:41], 0, v[134:135]
	ds_read_b128 v[186:189], v142 offset:32768
	ds_read_b128 v[190:193], v142 offset:33792
	ds_read_b128 v[194:197], v142 offset:34816
	ds_read_b128 v[208:211], v142 offset:35840
	ds_read_b128 v[212:215], v142 offset:36864
	ds_read_b128 v[216:219], v142 offset:37888
	ds_read_b128 v[220:223], v142 offset:38912
	ds_read_b128 v[224:227], v142 offset:39936
	global_load_lds_dwordx4 v[234:235], off
	v_lshl_add_u64 v[234:235], s[40:41], 0, v[132:133]
	s_mov_b32 m0, s45
	s_nop 0
	global_load_lds_dwordx4 v[234:235], off
	s_waitcnt vmcnt(8)
	s_waitcnt lgkmcnt(0)
	s_barrier
	s_setprio 1
	s_waitcnt lgkmcnt(0)
	v_mfma_f32_16x16x32_bf16 v[128:131], v[144:147], v[186:189], v[128:131]
	v_mfma_f32_16x16x32_bf16 v[128:131], v[148:151], v[190:193], v[128:131]
	v_mfma_f32_16x16x32_bf16 v[124:127], v[156:159], v[190:193], v[124:127]
	v_mfma_f32_16x16x32_bf16 v[124:127], v[152:155], v[186:189], v[124:127]
	v_mfma_f32_16x16x32_bf16 v[116:119], v[152:155], v[194:197], v[116:119]
	v_mfma_f32_16x16x32_bf16 v[116:119], v[156:159], v[208:211], v[116:119]
	v_mfma_f32_16x16x32_bf16 v[120:123], v[148:151], v[208:211], v[120:123]
	v_mfma_f32_16x16x32_bf16 v[120:123], v[144:147], v[194:197], v[120:123]
	v_mfma_f32_16x16x32_bf16 v[108:111], v[144:147], v[212:215], v[108:111]
	v_mfma_f32_16x16x32_bf16 v[108:111], v[148:151], v[216:219], v[108:111]
	v_mfma_f32_16x16x32_bf16 v[100:103], v[156:159], v[216:219], v[100:103]
	v_mfma_f32_16x16x32_bf16 v[100:103], v[152:155], v[212:215], v[100:103]
	v_mfma_f32_16x16x32_bf16 v[84:87], v[152:155], v[220:223], v[84:87]
	v_mfma_f32_16x16x32_bf16 v[84:87], v[156:159], v[224:227], v[84:87]
	v_mfma_f32_16x16x32_bf16 v[92:95], v[148:151], v[224:227], v[92:95]
	v_mfma_f32_16x16x32_bf16 v[92:95], v[144:147], v[220:223], v[92:95]
	s_setprio 0
	s_setprio 1
	v_mfma_f32_16x16x32_bf16 v[112:115], v[160:163], v[186:189], v[112:115]
	v_mfma_f32_16x16x32_bf16 v[112:115], v[164:167], v[190:193], v[112:115]
	v_mfma_f32_16x16x32_bf16 v[104:107], v[182:185], v[190:193], v[104:107]
	v_mfma_f32_16x16x32_bf16 v[104:107], v[178:181], v[186:189], v[104:107]
	v_mfma_f32_16x16x32_bf16 v[88:91], v[178:181], v[194:197], v[88:91]
	v_mfma_f32_16x16x32_bf16 v[88:91], v[182:185], v[208:211], v[88:91]
	v_mfma_f32_16x16x32_bf16 v[96:99], v[164:167], v[208:211], v[96:99]
	v_mfma_f32_16x16x32_bf16 v[96:99], v[160:163], v[194:197], v[96:99]
	v_mfma_f32_16x16x32_bf16 v[80:83], v[160:163], v[212:215], v[80:83]
	v_mfma_f32_16x16x32_bf16 v[80:83], v[164:167], v[216:219], v[80:83]
	v_mfma_f32_16x16x32_bf16 v[76:79], v[182:185], v[216:219], v[76:79]
	v_mfma_f32_16x16x32_bf16 v[76:79], v[178:181], v[212:215], v[76:79]
	v_mfma_f32_16x16x32_bf16 v[68:71], v[178:181], v[220:223], v[68:71]
	v_mfma_f32_16x16x32_bf16 v[68:71], v[182:185], v[224:227], v[68:71]
	v_mfma_f32_16x16x32_bf16 v[72:75], v[164:167], v[224:227], v[72:75]
	v_mfma_f32_16x16x32_bf16 v[72:75], v[160:163], v[220:223], v[72:75]
	s_setprio 0
	s_barrier
	s_add_i32 s40, s55, s25
	v_lshl_add_u64 v[168:169], v[168:169], 0, s[18:19]
	s_mov_b32 m0, s40
	ds_read_b128 v[186:189], v142 offset:49152
	ds_read_b128 v[190:193], v142 offset:50176
	ds_read_b128 v[194:197], v142 offset:51200
	ds_read_b128 v[208:211], v142 offset:52224
	ds_read_b128 v[212:215], v142 offset:53248
	ds_read_b128 v[216:219], v142 offset:54272
	ds_read_b128 v[220:223], v142 offset:55296
	ds_read_b128 v[224:227], v142 offset:56320
	global_load_lds_dwordx4 v[168:169], off
	s_add_i32 m0, s40, 0x2000
	s_add_u32 s38, s38, 0x200080
	v_lshl_add_u64 v[168:169], v[228:229], 0, s[18:19]
	s_addc_u32 s39, s39, 0
	s_add_i32 s40, s56, s25
	global_load_lds_dwordx4 v[168:169], off
	v_lshl_add_u64 v[168:169], s[38:39], 0, v[134:135]
	s_mov_b32 m0, s40
	s_nop 0
	global_load_lds_dwordx4 v[168:169], off
	v_lshl_add_u64 v[168:169], s[38:39], 0, v[132:133]
	s_add_i32 m0, s40, 0x2000
	s_nop 0
	global_load_lds_dwordx4 v[168:169], off
	v_lshl_add_u64 v[168:169], v[230:231], 0, s[18:19]
	s_mov_b32 m0, s1
	s_nop 0
	global_load_lds_dwordx4 v[168:169], off
	v_lshl_add_u64 v[168:169], v[232:233], 0, s[18:19]
	s_mov_b32 m0, s7
	s_nop 0
	global_load_lds_dwordx4 v[168:169], off
	s_waitcnt vmcnt(8)
	s_waitcnt lgkmcnt(0)
	s_barrier
	s_setprio 1
	s_waitcnt lgkmcnt(0)
	v_mfma_f32_16x16x32_bf16 v[64:67], v[144:147], v[186:189], v[64:67]
	v_mfma_f32_16x16x32_bf16 v[64:67], v[148:151], v[190:193], v[64:67]
	v_mfma_f32_16x16x32_bf16 v[60:63], v[156:159], v[190:193], v[60:63]
	v_mfma_f32_16x16x32_bf16 v[60:63], v[152:155], v[186:189], v[60:63]
	v_mfma_f32_16x16x32_bf16 v[52:55], v[152:155], v[194:197], v[52:55]
	v_mfma_f32_16x16x32_bf16 v[52:55], v[156:159], v[208:211], v[52:55]
	v_mfma_f32_16x16x32_bf16 v[56:59], v[148:151], v[208:211], v[56:59]
	v_mfma_f32_16x16x32_bf16 v[56:59], v[144:147], v[194:197], v[56:59]
	v_mfma_f32_16x16x32_bf16 v[40:43], v[144:147], v[212:215], v[40:43]
	v_mfma_f32_16x16x32_bf16 v[40:43], v[148:151], v[216:219], v[40:43]
	v_mfma_f32_16x16x32_bf16 v[36:39], v[156:159], v[216:219], v[36:39]
	v_mfma_f32_16x16x32_bf16 v[36:39], v[152:155], v[212:215], v[36:39]
	v_mfma_f32_16x16x32_bf16 v[20:23], v[152:155], v[220:223], v[20:23]
	v_mfma_f32_16x16x32_bf16 v[20:23], v[156:159], v[224:227], v[20:23]
	v_mfma_f32_16x16x32_bf16 v[24:27], v[148:151], v[224:227], v[24:27]
	v_mfma_f32_16x16x32_bf16 v[24:27], v[144:147], v[220:223], v[24:27]
	s_setprio 0
	s_setprio 1
	v_mfma_f32_16x16x32_bf16 v[48:51], v[160:163], v[186:189], v[48:51]
	v_mfma_f32_16x16x32_bf16 v[48:51], v[164:167], v[190:193], v[48:51]
	v_mfma_f32_16x16x32_bf16 v[44:47], v[182:185], v[190:193], v[44:47]
	v_mfma_f32_16x16x32_bf16 v[44:47], v[178:181], v[186:189], v[44:47]
	v_mfma_f32_16x16x32_bf16 v[28:31], v[178:181], v[194:197], v[28:31]
	v_mfma_f32_16x16x32_bf16 v[28:31], v[182:185], v[208:211], v[28:31]
	v_mfma_f32_16x16x32_bf16 v[32:35], v[164:167], v[208:211], v[32:35]
	v_mfma_f32_16x16x32_bf16 v[32:35], v[160:163], v[194:197], v[32:35]
	v_mfma_f32_16x16x32_bf16 v[16:19], v[160:163], v[212:215], v[16:19]
	v_mfma_f32_16x16x32_bf16 v[16:19], v[164:167], v[216:219], v[16:19]
	v_mfma_f32_16x16x32_bf16 v[12:15], v[182:185], v[216:219], v[12:15]
	v_mfma_f32_16x16x32_bf16 v[12:15], v[178:181], v[212:215], v[12:15]
	v_mfma_f32_16x16x32_bf16 v[4:7], v[178:181], v[220:223], v[4:7]
	v_mfma_f32_16x16x32_bf16 v[4:7], v[182:185], v[224:227], v[4:7]
	v_mfma_f32_16x16x32_bf16 v[8:11], v[164:167], v[224:227], v[8:11]
	v_mfma_f32_16x16x32_bf16 v[8:11], v[160:163], v[220:223], v[8:11]
	s_setprio 0
	s_barrier
	s_add_i32 s54, s54, 2
	s_add_u32 s36, s36, 0x100
	s_addc_u32 s37, s37, 0
	s_add_u32 s52, s52, 0x100
	s_addc_u32 s53, s53, 0
	s_cmp_gt_u32 s54, 13
	s_cbranch_scc0 .LBB0_1088
	s_and_b64 vcc, exec, s[28:29]
	s_cbranch_vccz .LBB0_1091
	s_barrier

.LBB0_1184:
	s_add_u32 s8, s4, 0xfff80080
	s_addc_u32 s9, s5, -1
	s_add_i32 s26, 0, 0x10000
	s_cmp_eq_u32 s22, 28
	s_cselect_b32 s13, s1, s9
	s_cselect_b32 s12, s3, s8
	v_add_u32_e32 v1, s26, v162
	s_cselect_b32 s9, s7, s21
	s_cselect_b32 s8, s10, s11
	s_add_i32 s33, 0, 0x14000
	ds_read_b128 v[148:151], v1
	ds_read_b128 v[152:155], v1 offset:1024
	ds_read_b128 v[156:159], v1 offset:2048
	ds_read_b128 v[166:169], v1 offset:3072
	v_add_u32_e32 v1, s33, v162
	ds_read_b128 v[178:181], v1
	ds_read_b128 v[182:185], v1 offset:1024
	ds_read_b128 v[186:189], v1 offset:2048
	ds_read_b128 v[190:193], v1 offset:3072
	v_lshl_add_u64 v[236:237], s[4:5], 0, v[144:145]
	s_add_i32 m0, s47, 0xc000
	ds_read_b128 v[194:197], v165
	ds_read_b128 v[208:211], v165 offset:1024
	ds_read_b128 v[212:215], v165 offset:2048
	ds_read_b128 v[216:219], v165 offset:3072
	ds_read_b128 v[220:223], v165 offset:4096
	ds_read_b128 v[224:227], v165 offset:5120
	ds_read_b128 v[228:231], v165 offset:6144
	ds_read_b128 v[232:235], v165 offset:7168
	global_load_lds_dwordx4 v[236:237], off
	v_lshl_add_u64 v[236:237], s[4:5], 0, v[146:147]
	s_add_i32 m0, s47, 0xe000
	s_nop 0
	global_load_lds_dwordx4 v[236:237], off
	s_waitcnt vmcnt(8)
	s_waitcnt lgkmcnt(0)
	s_barrier
	s_setprio 1
	s_waitcnt lgkmcnt(0)
	v_mfma_f32_16x16x32_bf16 v[128:131], v[148:151], v[194:197], v[128:131]
	v_mfma_f32_16x16x32_bf16 v[128:131], v[152:155], v[208:211], v[128:131]
	v_mfma_f32_16x16x32_bf16 v[124:127], v[166:169], v[208:211], v[124:127]
	v_mfma_f32_16x16x32_bf16 v[124:127], v[156:159], v[194:197], v[124:127]
	v_mfma_f32_16x16x32_bf16 v[108:111], v[156:159], v[212:215], v[108:111]
	v_mfma_f32_16x16x32_bf16 v[108:111], v[166:169], v[216:219], v[108:111]
	v_mfma_f32_16x16x32_bf16 v[112:115], v[152:155], v[216:219], v[112:115]
	v_mfma_f32_16x16x32_bf16 v[112:115], v[148:151], v[212:215], v[112:115]
	v_mfma_f32_16x16x32_bf16 v[96:99], v[148:151], v[220:223], v[96:99]
	v_mfma_f32_16x16x32_bf16 v[96:99], v[152:155], v[224:227], v[96:99]
	v_mfma_f32_16x16x32_bf16 v[92:95], v[166:169], v[224:227], v[92:95]
	v_mfma_f32_16x16x32_bf16 v[92:95], v[156:159], v[220:223], v[92:95]
	v_mfma_f32_16x16x32_bf16 v[76:79], v[156:159], v[228:231], v[76:79]
	v_mfma_f32_16x16x32_bf16 v[76:79], v[166:169], v[232:235], v[76:79]
	v_mfma_f32_16x16x32_bf16 v[80:83], v[152:155], v[232:235], v[80:83]
	v_mfma_f32_16x16x32_bf16 v[80:83], v[148:151], v[228:231], v[80:83]
	s_setprio 0
	s_setprio 1
	v_mfma_f32_16x16x32_bf16 v[120:123], v[178:181], v[194:197], v[120:123]
	v_mfma_f32_16x16x32_bf16 v[120:123], v[182:185], v[208:211], v[120:123]
	v_mfma_f32_16x16x32_bf16 v[116:119], v[190:193], v[208:211], v[116:119]
	v_mfma_f32_16x16x32_bf16 v[116:119], v[186:189], v[194:197], v[116:119]
	v_mfma_f32_16x16x32_bf16 v[100:103], v[186:189], v[212:215], v[100:103]
	v_mfma_f32_16x16x32_bf16 v[100:103], v[190:193], v[216:219], v[100:103]
	v_mfma_f32_16x16x32_bf16 v[104:107], v[182:185], v[216:219], v[104:107]
	v_mfma_f32_16x16x32_bf16 v[104:107], v[178:181], v[212:215], v[104:107]
	v_mfma_f32_16x16x32_bf16 v[88:91], v[178:181], v[220:223], v[88:91]
	v_mfma_f32_16x16x32_bf16 v[88:91], v[182:185], v[224:227], v[88:91]
	v_mfma_f32_16x16x32_bf16 v[84:87], v[190:193], v[224:227], v[84:87]
	v_mfma_f32_16x16x32_bf16 v[84:87], v[186:189], v[220:223], v[84:87]
	v_mfma_f32_16x16x32_bf16 v[68:71], v[186:189], v[228:231], v[68:71]
	v_mfma_f32_16x16x32_bf16 v[68:71], v[190:193], v[232:235], v[68:71]
	v_mfma_f32_16x16x32_bf16 v[72:75], v[182:185], v[232:235], v[72:75]
	v_mfma_f32_16x16x32_bf16 v[72:75], v[178:181], v[228:231], v[72:75]
	s_setprio 0
	s_barrier
	s_add_i32 s26, s26, s65
	v_lshl_add_u64 v[236:237], s[8:9], 0, v[134:135]
	s_mov_b32 m0, s26
	ds_read_b128 v[194:197], v165 offset:16384
	ds_read_b128 v[208:211], v165 offset:17408
	ds_read_b128 v[212:215], v165 offset:18432
	ds_read_b128 v[216:219], v165 offset:19456
	ds_read_b128 v[220:223], v165 offset:20480
	ds_read_b128 v[224:227], v165 offset:21504
	ds_read_b128 v[228:231], v165 offset:22528
	ds_read_b128 v[232:235], v165 offset:23552
	global_load_lds_dwordx4 v[236:237], off
	s_add_i32 m0, s26, 0x2000
	s_add_u32 s26, s8, 0x80000
	v_lshl_add_u64 v[238:239], s[8:9], 0, v[138:139]
	s_addc_u32 s27, s9, 0
	s_add_i32 s33, s33, s65
	global_load_lds_dwordx4 v[238:239], off
	v_lshl_add_u64 v[240:241], s[26:27], 0, v[134:135]
	s_mov_b32 m0, s33
	v_lshl_add_u64 v[242:243], s[12:13], 0, v[136:137]
	global_load_lds_dwordx4 v[240:241], off
	v_lshl_add_u64 v[240:241], s[26:27], 0, v[138:139]
	s_add_i32 m0, s33, 0x2000
	s_nop 0
	global_load_lds_dwordx4 v[240:241], off
	v_lshl_add_u64 v[240:241], s[12:13], 0, v[132:133]
	s_mov_b32 m0, s47
	s_nop 0
	global_load_lds_dwordx4 v[240:241], off
	s_mov_b32 m0, s66
	s_nop 0
	global_load_lds_dwordx4 v[242:243], off
	s_waitcnt vmcnt(8)
	s_waitcnt lgkmcnt(0)
	s_barrier
	s_setprio 1
	s_waitcnt lgkmcnt(0)
	v_mfma_f32_16x16x32_bf16 v[64:67], v[148:151], v[194:197], v[64:67]
	v_mfma_f32_16x16x32_bf16 v[64:67], v[152:155], v[208:211], v[64:67]
	v_mfma_f32_16x16x32_bf16 v[60:63], v[166:169], v[208:211], v[60:63]
	v_mfma_f32_16x16x32_bf16 v[60:63], v[156:159], v[194:197], v[60:63]
	v_mfma_f32_16x16x32_bf16 v[44:47], v[156:159], v[212:215], v[44:47]
	v_mfma_f32_16x16x32_bf16 v[44:47], v[166:169], v[216:219], v[44:47]
	v_mfma_f32_16x16x32_bf16 v[48:51], v[152:155], v[216:219], v[48:51]
	v_mfma_f32_16x16x32_bf16 v[48:51], v[148:151], v[212:215], v[48:51]
	v_mfma_f32_16x16x32_bf16 v[32:35], v[148:151], v[220:223], v[32:35]
	v_mfma_f32_16x16x32_bf16 v[32:35], v[152:155], v[224:227], v[32:35]
	v_mfma_f32_16x16x32_bf16 v[28:31], v[166:169], v[224:227], v[28:31]
	v_mfma_f32_16x16x32_bf16 v[28:31], v[156:159], v[220:223], v[28:31]
	v_mfma_f32_16x16x32_bf16 v[12:15], v[156:159], v[228:231], v[12:15]
	v_mfma_f32_16x16x32_bf16 v[12:15], v[166:169], v[232:235], v[12:15]
	v_mfma_f32_16x16x32_bf16 v[16:19], v[152:155], v[232:235], v[16:19]
	v_mfma_f32_16x16x32_bf16 v[16:19], v[148:151], v[228:231], v[16:19]
	s_setprio 0
	s_setprio 1
	v_mfma_f32_16x16x32_bf16 v[56:59], v[178:181], v[194:197], v[56:59]
	v_mfma_f32_16x16x32_bf16 v[56:59], v[182:185], v[208:211], v[56:59]
	v_mfma_f32_16x16x32_bf16 v[52:55], v[190:193], v[208:211], v[52:55]
	v_mfma_f32_16x16x32_bf16 v[52:55], v[186:189], v[194:197], v[52:55]
	v_mfma_f32_16x16x32_bf16 v[36:39], v[186:189], v[212:215], v[36:39]
	v_mfma_f32_16x16x32_bf16 v[36:39], v[190:193], v[216:219], v[36:39]
	v_mfma_f32_16x16x32_bf16 v[40:43], v[182:185], v[216:219], v[40:43]
	v_mfma_f32_16x16x32_bf16 v[40:43], v[178:181], v[212:215], v[40:43]
	v_mfma_f32_16x16x32_bf16 v[24:27], v[178:181], v[220:223], v[24:27]
	v_mfma_f32_16x16x32_bf16 v[24:27], v[182:185], v[224:227], v[24:27]
	v_mfma_f32_16x16x32_bf16 v[20:23], v[190:193], v[224:227], v[20:23]
	v_mfma_f32_16x16x32_bf16 v[20:23], v[186:189], v[220:223], v[20:23]
	v_mfma_f32_16x16x32_bf16 v[4:7], v[186:189], v[228:231], v[4:7]
	v_mfma_f32_16x16x32_bf16 v[4:7], v[190:193], v[232:235], v[4:7]
	v_mfma_f32_16x16x32_bf16 v[8:11], v[182:185], v[232:235], v[8:11]
	v_mfma_f32_16x16x32_bf16 v[8:11], v[178:181], v[228:231], v[8:11]
	s_setprio 0
	s_barrier
	s_add_i32 s26, 0, 0x18000
	v_add_u32_e32 v1, s26, v162
	s_add_i32 s27, 0, 0x1c000
	ds_read_b128 v[148:151], v1
	ds_read_b128 v[152:155], v1 offset:1024
	ds_read_b128 v[156:159], v1 offset:2048
	ds_read_b128 v[166:169], v1 offset:3072
	v_add_u32_e32 v1, s27, v162
	ds_read_b128 v[178:181], v1
	ds_read_b128 v[182:185], v1 offset:1024
	ds_read_b128 v[186:189], v1 offset:2048
	ds_read_b128 v[190:193], v1 offset:3072
	s_add_u32 s12, s12, 0x80000
	s_addc_u32 s13, s13, 0
	s_mov_b32 m0, s67
	v_lshl_add_u64 v[244:245], s[12:13], 0, v[132:133]
	ds_read_b128 v[194:197], v165 offset:32768
	ds_read_b128 v[208:211], v165 offset:33792
	ds_read_b128 v[212:215], v165 offset:34816
	ds_read_b128 v[216:219], v165 offset:35840
	ds_read_b128 v[220:223], v165 offset:36864
	ds_read_b128 v[224:227], v165 offset:37888
	ds_read_b128 v[228:231], v165 offset:38912
	ds_read_b128 v[232:235], v165 offset:39936
	global_load_lds_dwordx4 v[244:245], off
	v_lshl_add_u64 v[244:245], s[12:13], 0, v[136:137]
	s_mov_b32 m0, s68
	s_nop 0
	global_load_lds_dwordx4 v[244:245], off
	s_waitcnt vmcnt(8)
	s_waitcnt lgkmcnt(0)
	s_barrier
	s_setprio 1
	s_waitcnt lgkmcnt(0)
	v_mfma_f32_16x16x32_bf16 v[128:131], v[148:151], v[194:197], v[128:131]
	v_mfma_f32_16x16x32_bf16 v[128:131], v[152:155], v[208:211], v[128:131]
	v_mfma_f32_16x16x32_bf16 v[124:127], v[166:169], v[208:211], v[124:127]
	v_mfma_f32_16x16x32_bf16 v[124:127], v[156:159], v[194:197], v[124:127]
	v_mfma_f32_16x16x32_bf16 v[108:111], v[156:159], v[212:215], v[108:111]
	v_mfma_f32_16x16x32_bf16 v[108:111], v[166:169], v[216:219], v[108:111]
	v_mfma_f32_16x16x32_bf16 v[112:115], v[152:155], v[216:219], v[112:115]
	v_mfma_f32_16x16x32_bf16 v[112:115], v[148:151], v[212:215], v[112:115]
	v_mfma_f32_16x16x32_bf16 v[96:99], v[148:151], v[220:223], v[96:99]
	v_mfma_f32_16x16x32_bf16 v[96:99], v[152:155], v[224:227], v[96:99]
	v_mfma_f32_16x16x32_bf16 v[92:95], v[166:169], v[224:227], v[92:95]
	v_mfma_f32_16x16x32_bf16 v[92:95], v[156:159], v[220:223], v[92:95]
	v_mfma_f32_16x16x32_bf16 v[76:79], v[156:159], v[228:231], v[76:79]
	v_mfma_f32_16x16x32_bf16 v[76:79], v[166:169], v[232:235], v[76:79]
	v_mfma_f32_16x16x32_bf16 v[80:83], v[152:155], v[232:235], v[80:83]
	v_mfma_f32_16x16x32_bf16 v[80:83], v[148:151], v[228:231], v[80:83]
	s_setprio 0
	s_setprio 1
	v_mfma_f32_16x16x32_bf16 v[120:123], v[178:181], v[194:197], v[120:123]
	v_mfma_f32_16x16x32_bf16 v[120:123], v[182:185], v[208:211], v[120:123]
	v_mfma_f32_16x16x32_bf16 v[116:119], v[190:193], v[208:211], v[116:119]
	v_mfma_f32_16x16x32_bf16 v[116:119], v[186:189], v[194:197], v[116:119]
	v_mfma_f32_16x16x32_bf16 v[100:103], v[186:189], v[212:215], v[100:103]
	v_mfma_f32_16x16x32_bf16 v[100:103], v[190:193], v[216:219], v[100:103]
	v_mfma_f32_16x16x32_bf16 v[104:107], v[182:185], v[216:219], v[104:107]
	v_mfma_f32_16x16x32_bf16 v[104:107], v[178:181], v[212:215], v[104:107]
	v_mfma_f32_16x16x32_bf16 v[88:91], v[178:181], v[220:223], v[88:91]
	v_mfma_f32_16x16x32_bf16 v[88:91], v[182:185], v[224:227], v[88:91]
	v_mfma_f32_16x16x32_bf16 v[84:87], v[190:193], v[224:227], v[84:87]
	v_mfma_f32_16x16x32_bf16 v[84:87], v[186:189], v[220:223], v[84:87]
	v_mfma_f32_16x16x32_bf16 v[68:71], v[186:189], v[228:231], v[68:71]
	v_mfma_f32_16x16x32_bf16 v[68:71], v[190:193], v[232:235], v[68:71]
	v_mfma_f32_16x16x32_bf16 v[72:75], v[182:185], v[232:235], v[72:75]
	v_mfma_f32_16x16x32_bf16 v[72:75], v[178:181], v[228:231], v[72:75]
	s_setprio 0
	s_barrier
	s_add_i32 s12, s26, s65
	v_lshl_add_u64 v[236:237], v[236:237], 0, s[18:19]
	s_mov_b32 m0, s12
	ds_read_b128 v[194:197], v165 offset:49152
	ds_read_b128 v[208:211], v165 offset:50176
	ds_read_b128 v[212:215], v165 offset:51200
	ds_read_b128 v[216:219], v165 offset:52224
	ds_read_b128 v[220:223], v165 offset:53248
	ds_read_b128 v[224:227], v165 offset:54272
	ds_read_b128 v[228:231], v165 offset:55296
	ds_read_b128 v[232:235], v165 offset:56320
	global_load_lds_dwordx4 v[236:237], off
	s_add_i32 m0, s12, 0x2000
	s_add_u32 s8, s8, 0x80080
	v_lshl_add_u64 v[236:237], v[238:239], 0, s[18:19]
	s_addc_u32 s9, s9, 0
	s_add_i32 s12, s27, s65
	global_load_lds_dwordx4 v[236:237], off
	v_lshl_add_u64 v[236:237], s[8:9], 0, v[134:135]
	s_mov_b32 m0, s12
	s_nop 0
	global_load_lds_dwordx4 v[236:237], off
	v_lshl_add_u64 v[236:237], s[8:9], 0, v[138:139]
	s_add_i32 m0, s12, 0x2000
	s_nop 0
	global_load_lds_dwordx4 v[236:237], off
	v_lshl_add_u64 v[236:237], v[240:241], 0, s[18:19]
	s_mov_b32 m0, s82
	s_nop 0
	global_load_lds_dwordx4 v[236:237], off
	v_lshl_add_u64 v[236:237], v[242:243], 0, s[18:19]
	s_mov_b32 m0, s83
	s_nop 0
	global_load_lds_dwordx4 v[236:237], off
	s_waitcnt vmcnt(8)
	s_waitcnt lgkmcnt(0)
	s_barrier
	s_setprio 1
	s_waitcnt lgkmcnt(0)
	v_mfma_f32_16x16x32_bf16 v[64:67], v[148:151], v[194:197], v[64:67]
	v_mfma_f32_16x16x32_bf16 v[64:67], v[152:155], v[208:211], v[64:67]
	v_mfma_f32_16x16x32_bf16 v[60:63], v[166:169], v[208:211], v[60:63]
	v_mfma_f32_16x16x32_bf16 v[60:63], v[156:159], v[194:197], v[60:63]
	v_mfma_f32_16x16x32_bf16 v[44:47], v[156:159], v[212:215], v[44:47]
	v_mfma_f32_16x16x32_bf16 v[44:47], v[166:169], v[216:219], v[44:47]
	v_mfma_f32_16x16x32_bf16 v[48:51], v[152:155], v[216:219], v[48:51]
	v_mfma_f32_16x16x32_bf16 v[48:51], v[148:151], v[212:215], v[48:51]
	v_mfma_f32_16x16x32_bf16 v[32:35], v[148:151], v[220:223], v[32:35]
	v_mfma_f32_16x16x32_bf16 v[32:35], v[152:155], v[224:227], v[32:35]
	v_mfma_f32_16x16x32_bf16 v[28:31], v[166:169], v[224:227], v[28:31]
	v_mfma_f32_16x16x32_bf16 v[28:31], v[156:159], v[220:223], v[28:31]
	v_mfma_f32_16x16x32_bf16 v[12:15], v[156:159], v[228:231], v[12:15]
	v_mfma_f32_16x16x32_bf16 v[12:15], v[166:169], v[232:235], v[12:15]
	v_mfma_f32_16x16x32_bf16 v[16:19], v[152:155], v[232:235], v[16:19]
	v_mfma_f32_16x16x32_bf16 v[16:19], v[148:151], v[228:231], v[16:19]
	s_setprio 0
	s_setprio 1
	v_mfma_f32_16x16x32_bf16 v[56:59], v[178:181], v[194:197], v[56:59]
	v_mfma_f32_16x16x32_bf16 v[56:59], v[182:185], v[208:211], v[56:59]
	v_mfma_f32_16x16x32_bf16 v[52:55], v[190:193], v[208:211], v[52:55]
	v_mfma_f32_16x16x32_bf16 v[52:55], v[186:189], v[194:197], v[52:55]
	v_mfma_f32_16x16x32_bf16 v[36:39], v[186:189], v[212:215], v[36:39]
	v_mfma_f32_16x16x32_bf16 v[36:39], v[190:193], v[216:219], v[36:39]
	v_mfma_f32_16x16x32_bf16 v[40:43], v[182:185], v[216:219], v[40:43]
	v_mfma_f32_16x16x32_bf16 v[40:43], v[178:181], v[212:215], v[40:43]
	v_mfma_f32_16x16x32_bf16 v[24:27], v[178:181], v[220:223], v[24:27]
	v_mfma_f32_16x16x32_bf16 v[24:27], v[182:185], v[224:227], v[24:27]
	v_mfma_f32_16x16x32_bf16 v[20:23], v[190:193], v[224:227], v[20:23]
	v_mfma_f32_16x16x32_bf16 v[20:23], v[186:189], v[220:223], v[20:23]
	v_mfma_f32_16x16x32_bf16 v[4:7], v[186:189], v[228:231], v[4:7]
	v_mfma_f32_16x16x32_bf16 v[4:7], v[190:193], v[232:235], v[4:7]
	v_mfma_f32_16x16x32_bf16 v[8:11], v[182:185], v[232:235], v[8:11]
	v_mfma_f32_16x16x32_bf16 v[8:11], v[178:181], v[228:231], v[8:11]
	s_setprio 0
	s_barrier
	s_add_i32 s22, s22, 2
	s_add_u32 s4, s4, 0x100
	s_addc_u32 s5, s5, 0
	s_add_u32 s11, s11, 0x100
	s_addc_u32 s21, s21, 0
	s_cmp_gt_u32 s22, 29
	s_cbranch_scc0 .LBB0_1184
	s_and_b64 vcc, exec, s[54:55]
	s_cbranch_vccz .LBB0_1187
	s_barrier
